# k-loops: LDS-DMA loads use scalar base + 32-bit lane offset (drops 8 64-bit VALU adds per k-tile)
# speedup vs baseline: 1.0204x; 1.0082x over previous
.LBB0_114:
	v_mov_b32_e32 v6, v181
	s_ashr_i32 s93, s92, 6
	v_lshrrev_b32_e32 v7, 4, v6
	v_lshlrev_b32_e32 v1, 6, v6
	v_xor_b32_e32 v0, v7, v6
	v_and_b32_e32 v8, 0x3c0, v1
	v_lshlrev_b32_e32 v1, 7, v6
	s_bfe_u32 s94, s92, 0x20006
	s_and_b32 s86, s91, 63
	s_and_b32 s95, s92, 63
	s_and_b32 s21, s93, -4
	v_lshlrev_b32_e32 v0, 3, v0
	v_and_b32_e32 v1, 0xfffffc00, v1
	s_lshl_b32 s20, s86, 19
	s_or_b32 s58, s21, s94
	s_lshl_b32 s21, s95, 19
	v_and_or_b32 v0, v0, 56, v1
	s_waitcnt lgkmcnt(0)
	s_add_u32 s60, s3, s21
	v_ashrrev_i32_e32 v1, 31, v0
	v_lshl_add_u32 v129, v6, 4, 0
	s_addc_u32 s61, s90, 0
	v_lshlrev_b64 v[0:1], 1, v[0:1]
	v_readfirstlane_b32 s21, v129
	v_add_u32_e32 v9, 0x2000, v129
	v_lshl_add_u64 v[2:3], s[60:61], 0, v[0:1]
	s_mov_b32 m0, s21
	v_readfirstlane_b32 s21, v9
	v_add_u32_e32 v9, 0x4000, v129
	s_barrier
	global_load_lds_dwordx4 v[2:3], off
	v_lshl_add_u64 v[4:5], v[2:3], 0, s[10:11]
	s_mov_b32 m0, s21
	v_readfirstlane_b32 s21, v9
	global_load_lds_dwordx4 v[4:5], off
	v_lshl_add_u64 v[4:5], v[2:3], 0, s[12:13]
	s_mov_b32 m0, s21
	s_ashr_i32 s59, s58, 31
	global_load_lds_dwordx4 v[4:5], off
	v_add_u32_e32 v4, 0x6000, v129
	s_lshl_b64 s[88:89], s[58:59], 19
	v_readfirstlane_b32 s21, v4
	v_lshl_add_u64 v[2:3], v[2:3], 0, s[14:15]
	s_mov_b32 m0, s21
	s_add_u32 s88, s34, s88
	global_load_lds_dwordx4 v[2:3], off
	v_add_u32_e32 v2, 0x8000, v129
	s_addc_u32 s89, s35, s89
	v_readfirstlane_b32 s21, v2
	v_add_u32_e32 v4, 0xa000, v129
	v_lshl_add_u64 v[134:135], s[88:89], 0, v[0:1]
	s_mov_b32 m0, s21
	v_readfirstlane_b32 s21, v4
	v_add_u32_e32 v4, 0xc000, v129
	global_load_lds_dwordx4 v[134:135], off
	v_lshl_add_u64 v[2:3], v[134:135], 0, s[10:11]
	s_mov_b32 m0, s21
	v_readfirstlane_b32 s21, v4
	v_add_u32_e32 v4, 0xe000, v129
	global_load_lds_dwordx4 v[2:3], off
	v_lshl_add_u64 v[2:3], v[134:135], 0, s[12:13]
	s_mov_b32 m0, s21
	v_readfirstlane_b32 s21, v4
	global_load_lds_dwordx4 v[2:3], off
	v_lshl_add_u64 v[2:3], v[134:135], 0, s[14:15]
	s_mov_b32 m0, s21
	v_ashrrev_i32_e32 v4, 6, v6
	global_load_lds_dwordx4 v[2:3], off
	v_lshrrev_b32_e32 v5, 30, v4
	v_add_u32_e32 v5, v4, v5
	v_bfe_u32 v2, v6, 4, 2
	v_bfe_u32 v3, v6, 1, 3
	v_and_b32_e32 v6, 0x7fffc, v5
	v_sub_u32_e32 v4, v4, v6
	v_lshlrev_b32_e32 v139, 13, v4
	v_bitop3_b32 v4, v7, v3, 3 bitop3:0x6c
	v_bitop3_b32 v2, v2, v3, 4 bitop3:0x36
	s_add_u32 s60, s34, s20
	v_lshlrev_b32_e32 v5, 12, v5
	v_lshlrev_b32_e32 v4, 3, v4
	v_lshlrev_b32_e32 v2, 3, v2
	s_addc_u32 s61, s35, 0
	v_and_b32_e32 v138, 0xffffc000, v5
	v_lshl_add_u64 v[136:137], s[60:61], 0, v[0:1]
	s_mov_b64 s[60:61], 0
	v_lshlrev_b32_e32 v140, 1, v8
	v_lshlrev_b32_e32 v141, 1, v4
	v_lshlrev_b32_e32 v142, 1, v2
	s_mov_b32 s87, 0
	s_mov_b32 s59, 0
	v_mov_b32_e32 v8, v128
	v_mov_b32_e32 v9, v128
	v_mov_b32_e32 v10, v128
	v_mov_b32_e32 v11, v128
	v_mov_b32_e32 v20, v128
	v_mov_b32_e32 v21, v128
	v_mov_b32_e32 v22, v128
	v_mov_b32_e32 v23, v128
	v_mov_b32_e32 v0, v128
	v_mov_b32_e32 v1, v128
	v_mov_b32_e32 v2, v128
	v_mov_b32_e32 v3, v128
	v_mov_b32_e32 v4, v128
	v_mov_b32_e32 v5, v128
	v_mov_b32_e32 v6, v128
	v_mov_b32_e32 v7, v128
	v_mov_b32_e32 v12, v128
	v_mov_b32_e32 v13, v128
	v_mov_b32_e32 v14, v128
	v_mov_b32_e32 v15, v128
	v_mov_b32_e32 v24, v128
	v_mov_b32_e32 v25, v128
	v_mov_b32_e32 v26, v128
	v_mov_b32_e32 v27, v128
	v_mov_b32_e32 v16, v128
	v_mov_b32_e32 v17, v128
	v_mov_b32_e32 v18, v128
	v_mov_b32_e32 v19, v128
	v_mov_b32_e32 v28, v128
	v_mov_b32_e32 v29, v128
	v_mov_b32_e32 v30, v128
	v_mov_b32_e32 v31, v128
	v_mov_b32_e32 v32, v128
	v_mov_b32_e32 v33, v128
	v_mov_b32_e32 v34, v128
	v_mov_b32_e32 v35, v128
	v_mov_b32_e32 v40, v128
	v_mov_b32_e32 v41, v128
	v_mov_b32_e32 v42, v128
	v_mov_b32_e32 v43, v128
	v_mov_b32_e32 v36, v128
	v_mov_b32_e32 v37, v128
	v_mov_b32_e32 v38, v128
	v_mov_b32_e32 v39, v128
	v_mov_b32_e32 v44, v128
	v_mov_b32_e32 v45, v128
	v_mov_b32_e32 v46, v128
	v_mov_b32_e32 v47, v128
	v_mov_b32_e32 v48, v128
	v_mov_b32_e32 v49, v128
	v_mov_b32_e32 v50, v128
	v_mov_b32_e32 v51, v128
	v_mov_b32_e32 v56, v128
	v_mov_b32_e32 v57, v128
	v_mov_b32_e32 v58, v128
	v_mov_b32_e32 v59, v128
	v_mov_b32_e32 v52, v128
	v_mov_b32_e32 v53, v128
	v_mov_b32_e32 v54, v128
	v_mov_b32_e32 v55, v128
	v_mov_b32_e32 v60, v128
	v_mov_b32_e32 v61, v128
	v_mov_b32_e32 v62, v128
	v_mov_b32_e32 v63, v128
	v_mov_b32_e32 v64, v128
	v_mov_b32_e32 v65, v128
	v_mov_b32_e32 v66, v128
	v_mov_b32_e32 v67, v128
	v_mov_b32_e32 v72, v128
	v_mov_b32_e32 v73, v128
	v_mov_b32_e32 v74, v128
	v_mov_b32_e32 v75, v128
	v_mov_b32_e32 v68, v128
	v_mov_b32_e32 v69, v128
	v_mov_b32_e32 v70, v128
	v_mov_b32_e32 v71, v128
	v_mov_b32_e32 v76, v128
	v_mov_b32_e32 v77, v128
	v_mov_b32_e32 v78, v128
	v_mov_b32_e32 v79, v128
	v_mov_b32_e32 v80, v128
	v_mov_b32_e32 v81, v128
	v_mov_b32_e32 v82, v128
	v_mov_b32_e32 v83, v128
	v_mov_b32_e32 v88, v128
	v_mov_b32_e32 v89, v128
	v_mov_b32_e32 v90, v128
	v_mov_b32_e32 v91, v128
	v_mov_b32_e32 v84, v128
	v_mov_b32_e32 v85, v128
	v_mov_b32_e32 v86, v128
	v_mov_b32_e32 v87, v128
	v_mov_b32_e32 v92, v128
	v_mov_b32_e32 v93, v128
	v_mov_b32_e32 v94, v128
	v_mov_b32_e32 v95, v128
	v_mov_b32_e32 v96, v128
	v_mov_b32_e32 v97, v128
	v_mov_b32_e32 v98, v128
	v_mov_b32_e32 v99, v128
	v_mov_b32_e32 v104, v128
	v_mov_b32_e32 v105, v128
	v_mov_b32_e32 v106, v128
	v_mov_b32_e32 v107, v128
	v_mov_b32_e32 v100, v128
	v_mov_b32_e32 v101, v128
	v_mov_b32_e32 v102, v128
	v_mov_b32_e32 v103, v128
	v_mov_b32_e32 v108, v128
	v_mov_b32_e32 v109, v128
	v_mov_b32_e32 v110, v128
	v_mov_b32_e32 v111, v128
	v_mov_b32_e32 v112, v128
	v_mov_b32_e32 v113, v128
	v_mov_b32_e32 v114, v128
	v_mov_b32_e32 v115, v128
	v_mov_b32_e32 v120, v128
	v_mov_b32_e32 v121, v128
	v_mov_b32_e32 v122, v128
	v_mov_b32_e32 v123, v128
	v_mov_b32_e32 v116, v128
	v_mov_b32_e32 v117, v128
	v_mov_b32_e32 v118, v128
	v_mov_b32_e32 v119, v128
	v_mov_b32_e32 v124, v128
	v_mov_b32_e32 v125, v128
	v_mov_b32_e32 v126, v128
	v_mov_b32_e32 v127, v128
	s_waitcnt vmcnt(0) lgkmcnt(0)
	s_barrier
	v_add3_u32 v143, v138, v140, v141
	v_add3_u32 v180, v139, v140, v141
	v_add3_u32 v155, v138, v140, v142
	v_add3_u32 v222, v139, v140, v142
	v_readfirstlane_b32 s87, v129
	ds_read_b128 v[156:159], v143
	ds_read_b128 v[160:163], v143 offset:2048
	ds_read_b128 v[164:167], v143 offset:4096
	ds_read_b128 v[168:171], v143 offset:6144
	ds_read_b128 v[190:193], v180 offset:32768
	ds_read_b128 v[194:197], v180 offset:34816
	ds_read_b128 v[198:201], v180 offset:36864
	ds_read_b128 v[202:205], v180 offset:38912
	s_mov_b32 s59, 0
	s_mov_b64 s[60:61], s[34:35]
	v_subrev_u32_e32 v144, s34, v136
	v_subrev_u32_e32 v145, s34, v134
	s_add_u32 s87, s87, 0x10000
	s_add_u32 s88, s60, s16
	s_addc_u32 s89, s61, s17
	s_mov_b32 m0, s87
	global_load_lds_dwordx4 v144, s[88:89]
	s_add_u32 s88, s60, s18
	s_addc_u32 s89, s61, s19
	s_add_u32 m0, s87, 0x2000
	global_load_lds_dwordx4 v144, s[88:89]
	s_add_u32 s88, s60, s22
	s_addc_u32 s89, s61, s23
	s_add_u32 m0, s87, 0x4000
	global_load_lds_dwordx4 v144, s[88:89]
	s_add_u32 s88, s60, s40
	s_addc_u32 s89, s61, s41
	s_add_u32 m0, s87, 0x6000
	global_load_lds_dwordx4 v144, s[88:89]
	s_add_u32 s88, s60, s42
	s_addc_u32 s89, s61, s43
	s_add_u32 m0, s87, 0x8000
	global_load_lds_dwordx4 v145, s[88:89]
	s_add_u32 s88, s60, s52
	s_addc_u32 s89, s61, s53
	s_add_u32 m0, s87, 0xa000
	global_load_lds_dwordx4 v145, s[88:89]
	s_add_u32 s88, s60, s54
	s_addc_u32 s89, s61, s55
	s_add_u32 m0, s87, 0xc000
	global_load_lds_dwordx4 v145, s[88:89]
	s_add_u32 s88, s60, s56
	s_addc_u32 s89, s61, s57
	s_add_u32 m0, s87, 0xe000
	global_load_lds_dwordx4 v145, s[88:89]
	s_branch .Lg0_entry
.Lg0_top:
	s_waitcnt lgkmcnt(0)
	s_waitcnt vmcnt(0)
	s_barrier
	v_xor_b32_e32 v143, 0x10000, v143
	v_xor_b32_e32 v180, 0x10000, v180
	v_xor_b32_e32 v155, 0x10000, v155
	v_xor_b32_e32 v222, 0x10000, v222
	s_xor_b32 s87, s87, 0x10000
	ds_read_b128 v[156:159], v143
	ds_read_b128 v[160:163], v143 offset:2048
	ds_read_b128 v[164:167], v143 offset:4096
	ds_read_b128 v[168:171], v143 offset:6144
	ds_read_b128 v[190:193], v180 offset:32768
	ds_read_b128 v[194:197], v180 offset:34816
	ds_read_b128 v[198:201], v180 offset:36864
	ds_read_b128 v[202:205], v180 offset:38912
	v_mfma_f32_16x16x32_bf16 v[60:63], v[172:175], v[206:209], v[60:63]
	v_mfma_f32_16x16x32_bf16 v[52:55], v[172:175], v[210:213], v[52:55]
	s_add_u32 s88, s60, s16
	s_addc_u32 s89, s61, s17
	s_mov_b32 m0, s87
	global_load_lds_dwordx4 v144, s[88:89]
	v_mfma_f32_16x16x32_bf16 v[56:59], v[172:175], v[214:217], v[56:59]
	v_mfma_f32_16x16x32_bf16 v[48:51], v[172:175], v[218:221], v[48:51]
	s_add_u32 s88, s60, s18
	s_addc_u32 s89, s61, s19
	s_add_u32 m0, s87, 0x2000
	global_load_lds_dwordx4 v144, s[88:89]
	v_mfma_f32_16x16x32_bf16 v[44:47], v[176:179], v[206:209], v[44:47]
	v_mfma_f32_16x16x32_bf16 v[36:39], v[176:179], v[210:213], v[36:39]
	s_add_u32 s88, s60, s22
	s_addc_u32 s89, s61, s23
	s_add_u32 m0, s87, 0x4000
	global_load_lds_dwordx4 v144, s[88:89]
	v_mfma_f32_16x16x32_bf16 v[40:43], v[176:179], v[214:217], v[40:43]
	v_mfma_f32_16x16x32_bf16 v[32:35], v[176:179], v[218:221], v[32:35]
	s_add_u32 s88, s60, s40
	s_addc_u32 s89, s61, s41
	s_add_u32 m0, s87, 0x6000
	global_load_lds_dwordx4 v144, s[88:89]
	v_mfma_f32_16x16x32_bf16 v[28:31], v[182:185], v[206:209], v[28:31]
	v_mfma_f32_16x16x32_bf16 v[16:19], v[182:185], v[210:213], v[16:19]
	s_add_u32 s88, s60, s42
	s_addc_u32 s89, s61, s43
	s_add_u32 m0, s87, 0x8000
	global_load_lds_dwordx4 v145, s[88:89]
	v_mfma_f32_16x16x32_bf16 v[24:27], v[182:185], v[214:217], v[24:27]
	v_mfma_f32_16x16x32_bf16 v[12:15], v[182:185], v[218:221], v[12:15]
	s_add_u32 s88, s60, s52
	s_addc_u32 s89, s61, s53
	s_add_u32 m0, s87, 0xa000
	global_load_lds_dwordx4 v145, s[88:89]
	v_mfma_f32_16x16x32_bf16 v[4:7], v[186:189], v[206:209], v[4:7]
	v_mfma_f32_16x16x32_bf16 v[0:3], v[186:189], v[210:213], v[0:3]
	s_add_u32 s88, s60, s54
	s_addc_u32 s89, s61, s55
	s_add_u32 m0, s87, 0xc000
	global_load_lds_dwordx4 v145, s[88:89]
	v_mfma_f32_16x16x32_bf16 v[20:23], v[186:189], v[214:217], v[20:23]
	v_mfma_f32_16x16x32_bf16 v[8:11], v[186:189], v[218:221], v[8:11]
	s_add_u32 s88, s60, s56
	s_addc_u32 s89, s61, s57
	s_add_u32 m0, s87, 0xe000
	global_load_lds_dwordx4 v145, s[88:89]
.Lg0_entry:
	ds_read_b128 v[172:175], v143 offset:8192
	ds_read_b128 v[176:179], v143 offset:10240
	ds_read_b128 v[182:185], v143 offset:12288
	ds_read_b128 v[186:189], v143 offset:14336
	s_waitcnt lgkmcnt(4)
	v_mfma_f32_16x16x32_bf16 v[124:127], v[156:159], v[190:193], v[124:127]
	v_mfma_f32_16x16x32_bf16 v[116:119], v[156:159], v[194:197], v[116:119]
	v_mfma_f32_16x16x32_bf16 v[120:123], v[156:159], v[198:201], v[120:123]
	v_mfma_f32_16x16x32_bf16 v[112:115], v[156:159], v[202:205], v[112:115]
	v_mfma_f32_16x16x32_bf16 v[108:111], v[160:163], v[190:193], v[108:111]
	v_mfma_f32_16x16x32_bf16 v[100:103], v[160:163], v[194:197], v[100:103]
	v_mfma_f32_16x16x32_bf16 v[104:107], v[160:163], v[198:201], v[104:107]
	v_mfma_f32_16x16x32_bf16 v[96:99], v[160:163], v[202:205], v[96:99]
	v_mfma_f32_16x16x32_bf16 v[92:95], v[164:167], v[190:193], v[92:95]
	v_mfma_f32_16x16x32_bf16 v[84:87], v[164:167], v[194:197], v[84:87]
	v_mfma_f32_16x16x32_bf16 v[88:91], v[164:167], v[198:201], v[88:91]
	v_mfma_f32_16x16x32_bf16 v[80:83], v[164:167], v[202:205], v[80:83]
	v_mfma_f32_16x16x32_bf16 v[76:79], v[168:171], v[190:193], v[76:79]
	v_mfma_f32_16x16x32_bf16 v[68:71], v[168:171], v[194:197], v[68:71]
	v_mfma_f32_16x16x32_bf16 v[72:75], v[168:171], v[198:201], v[72:75]
	v_mfma_f32_16x16x32_bf16 v[64:67], v[168:171], v[202:205], v[64:67]
	ds_read_b128 v[156:159], v155
	ds_read_b128 v[160:163], v155 offset:2048
	ds_read_b128 v[164:167], v155 offset:4096
	ds_read_b128 v[168:171], v155 offset:6144
	ds_read_b128 v[206:209], v222 offset:32768
	ds_read_b128 v[210:213], v222 offset:34816
	ds_read_b128 v[214:217], v222 offset:36864
	ds_read_b128 v[218:221], v222 offset:38912
	s_waitcnt lgkmcnt(8)
	v_mfma_f32_16x16x32_bf16 v[60:63], v[172:175], v[190:193], v[60:63]
	v_mfma_f32_16x16x32_bf16 v[52:55], v[172:175], v[194:197], v[52:55]
	v_mfma_f32_16x16x32_bf16 v[56:59], v[172:175], v[198:201], v[56:59]
	v_mfma_f32_16x16x32_bf16 v[48:51], v[172:175], v[202:205], v[48:51]
	v_mfma_f32_16x16x32_bf16 v[44:47], v[176:179], v[190:193], v[44:47]
	v_mfma_f32_16x16x32_bf16 v[36:39], v[176:179], v[194:197], v[36:39]
	v_mfma_f32_16x16x32_bf16 v[40:43], v[176:179], v[198:201], v[40:43]
	v_mfma_f32_16x16x32_bf16 v[32:35], v[176:179], v[202:205], v[32:35]
	v_mfma_f32_16x16x32_bf16 v[28:31], v[182:185], v[190:193], v[28:31]
	v_mfma_f32_16x16x32_bf16 v[16:19], v[182:185], v[194:197], v[16:19]
	v_mfma_f32_16x16x32_bf16 v[24:27], v[182:185], v[198:201], v[24:27]
	v_mfma_f32_16x16x32_bf16 v[12:15], v[182:185], v[202:205], v[12:15]
	v_mfma_f32_16x16x32_bf16 v[4:7], v[186:189], v[190:193], v[4:7]
	v_mfma_f32_16x16x32_bf16 v[0:3], v[186:189], v[194:197], v[0:3]
	v_mfma_f32_16x16x32_bf16 v[20:23], v[186:189], v[198:201], v[20:23]
	v_mfma_f32_16x16x32_bf16 v[8:11], v[186:189], v[202:205], v[8:11]
	ds_read_b128 v[172:175], v155 offset:8192
	ds_read_b128 v[176:179], v155 offset:10240
	ds_read_b128 v[182:185], v155 offset:12288
	ds_read_b128 v[186:189], v155 offset:14336
	s_waitcnt lgkmcnt(4)
	v_mfma_f32_16x16x32_bf16 v[124:127], v[156:159], v[206:209], v[124:127]
	v_mfma_f32_16x16x32_bf16 v[116:119], v[156:159], v[210:213], v[116:119]
	v_mfma_f32_16x16x32_bf16 v[120:123], v[156:159], v[214:217], v[120:123]
	v_mfma_f32_16x16x32_bf16 v[112:115], v[156:159], v[218:221], v[112:115]
	v_mfma_f32_16x16x32_bf16 v[108:111], v[160:163], v[206:209], v[108:111]
	v_mfma_f32_16x16x32_bf16 v[100:103], v[160:163], v[210:213], v[100:103]
	v_mfma_f32_16x16x32_bf16 v[104:107], v[160:163], v[214:217], v[104:107]
	v_mfma_f32_16x16x32_bf16 v[96:99], v[160:163], v[218:221], v[96:99]
	v_mfma_f32_16x16x32_bf16 v[92:95], v[164:167], v[206:209], v[92:95]
	v_mfma_f32_16x16x32_bf16 v[84:87], v[164:167], v[210:213], v[84:87]
	v_mfma_f32_16x16x32_bf16 v[88:91], v[164:167], v[214:217], v[88:91]
	v_mfma_f32_16x16x32_bf16 v[80:83], v[164:167], v[218:221], v[80:83]
	v_mfma_f32_16x16x32_bf16 v[76:79], v[168:171], v[206:209], v[76:79]
	v_mfma_f32_16x16x32_bf16 v[68:71], v[168:171], v[210:213], v[68:71]
	v_mfma_f32_16x16x32_bf16 v[72:75], v[168:171], v[214:217], v[72:75]
	v_mfma_f32_16x16x32_bf16 v[64:67], v[168:171], v[218:221], v[64:67]
	s_add_u32 s60, s60, 0x80
	s_addc_u32 s61, s61, 0
	s_add_i32 s59, s59, 1
	s_cmp_lt_u32 s59, 15
	s_cbranch_scc1 .Lg0_top
	s_waitcnt lgkmcnt(0)
	s_waitcnt vmcnt(0)
	s_barrier
	v_xor_b32_e32 v143, 0x10000, v143
	v_xor_b32_e32 v180, 0x10000, v180
	v_xor_b32_e32 v155, 0x10000, v155
	v_xor_b32_e32 v222, 0x10000, v222
	s_xor_b32 s87, s87, 0x10000
	ds_read_b128 v[156:159], v143
	ds_read_b128 v[160:163], v143 offset:2048
	ds_read_b128 v[164:167], v143 offset:4096
	ds_read_b128 v[168:171], v143 offset:6144
	ds_read_b128 v[190:193], v180 offset:32768
	ds_read_b128 v[194:197], v180 offset:34816
	ds_read_b128 v[198:201], v180 offset:36864
	ds_read_b128 v[202:205], v180 offset:38912
	v_mfma_f32_16x16x32_bf16 v[60:63], v[172:175], v[206:209], v[60:63]
	v_mfma_f32_16x16x32_bf16 v[52:55], v[172:175], v[210:213], v[52:55]
	v_mfma_f32_16x16x32_bf16 v[56:59], v[172:175], v[214:217], v[56:59]
	v_mfma_f32_16x16x32_bf16 v[48:51], v[172:175], v[218:221], v[48:51]
	v_mfma_f32_16x16x32_bf16 v[44:47], v[176:179], v[206:209], v[44:47]
	v_mfma_f32_16x16x32_bf16 v[36:39], v[176:179], v[210:213], v[36:39]
	v_mfma_f32_16x16x32_bf16 v[40:43], v[176:179], v[214:217], v[40:43]
	v_mfma_f32_16x16x32_bf16 v[32:35], v[176:179], v[218:221], v[32:35]
	v_mfma_f32_16x16x32_bf16 v[28:31], v[182:185], v[206:209], v[28:31]
	v_mfma_f32_16x16x32_bf16 v[16:19], v[182:185], v[210:213], v[16:19]
	v_mfma_f32_16x16x32_bf16 v[24:27], v[182:185], v[214:217], v[24:27]
	v_mfma_f32_16x16x32_bf16 v[12:15], v[182:185], v[218:221], v[12:15]
	v_mfma_f32_16x16x32_bf16 v[4:7], v[186:189], v[206:209], v[4:7]
	v_mfma_f32_16x16x32_bf16 v[0:3], v[186:189], v[210:213], v[0:3]
	v_mfma_f32_16x16x32_bf16 v[20:23], v[186:189], v[214:217], v[20:23]
	v_mfma_f32_16x16x32_bf16 v[8:11], v[186:189], v[218:221], v[8:11]
	ds_read_b128 v[172:175], v143 offset:8192
	ds_read_b128 v[176:179], v143 offset:10240
	ds_read_b128 v[182:185], v143 offset:12288
	ds_read_b128 v[186:189], v143 offset:14336
	s_waitcnt lgkmcnt(4)
	v_mfma_f32_16x16x32_bf16 v[124:127], v[156:159], v[190:193], v[124:127]
	v_mfma_f32_16x16x32_bf16 v[116:119], v[156:159], v[194:197], v[116:119]
	v_mfma_f32_16x16x32_bf16 v[120:123], v[156:159], v[198:201], v[120:123]
	v_mfma_f32_16x16x32_bf16 v[112:115], v[156:159], v[202:205], v[112:115]
	v_mfma_f32_16x16x32_bf16 v[108:111], v[160:163], v[190:193], v[108:111]
	v_mfma_f32_16x16x32_bf16 v[100:103], v[160:163], v[194:197], v[100:103]
	v_mfma_f32_16x16x32_bf16 v[104:107], v[160:163], v[198:201], v[104:107]
	v_mfma_f32_16x16x32_bf16 v[96:99], v[160:163], v[202:205], v[96:99]
	v_mfma_f32_16x16x32_bf16 v[92:95], v[164:167], v[190:193], v[92:95]
	v_mfma_f32_16x16x32_bf16 v[84:87], v[164:167], v[194:197], v[84:87]
	v_mfma_f32_16x16x32_bf16 v[88:91], v[164:167], v[198:201], v[88:91]
	v_mfma_f32_16x16x32_bf16 v[80:83], v[164:167], v[202:205], v[80:83]
	v_mfma_f32_16x16x32_bf16 v[76:79], v[168:171], v[190:193], v[76:79]
	v_mfma_f32_16x16x32_bf16 v[68:71], v[168:171], v[194:197], v[68:71]
	v_mfma_f32_16x16x32_bf16 v[72:75], v[168:171], v[198:201], v[72:75]
	v_mfma_f32_16x16x32_bf16 v[64:67], v[168:171], v[202:205], v[64:67]
	ds_read_b128 v[156:159], v155
	ds_read_b128 v[160:163], v155 offset:2048
	ds_read_b128 v[164:167], v155 offset:4096
	ds_read_b128 v[168:171], v155 offset:6144
	ds_read_b128 v[206:209], v222 offset:32768
	ds_read_b128 v[210:213], v222 offset:34816
	ds_read_b128 v[214:217], v222 offset:36864
	ds_read_b128 v[218:221], v222 offset:38912
	s_waitcnt lgkmcnt(8)
	v_mfma_f32_16x16x32_bf16 v[60:63], v[172:175], v[190:193], v[60:63]
	v_mfma_f32_16x16x32_bf16 v[52:55], v[172:175], v[194:197], v[52:55]
	v_mfma_f32_16x16x32_bf16 v[56:59], v[172:175], v[198:201], v[56:59]
	v_mfma_f32_16x16x32_bf16 v[48:51], v[172:175], v[202:205], v[48:51]
	v_mfma_f32_16x16x32_bf16 v[44:47], v[176:179], v[190:193], v[44:47]
	v_mfma_f32_16x16x32_bf16 v[36:39], v[176:179], v[194:197], v[36:39]
	v_mfma_f32_16x16x32_bf16 v[40:43], v[176:179], v[198:201], v[40:43]
	v_mfma_f32_16x16x32_bf16 v[32:35], v[176:179], v[202:205], v[32:35]
	v_mfma_f32_16x16x32_bf16 v[28:31], v[182:185], v[190:193], v[28:31]
	v_mfma_f32_16x16x32_bf16 v[16:19], v[182:185], v[194:197], v[16:19]
	v_mfma_f32_16x16x32_bf16 v[24:27], v[182:185], v[198:201], v[24:27]
	v_mfma_f32_16x16x32_bf16 v[12:15], v[182:185], v[202:205], v[12:15]
	v_mfma_f32_16x16x32_bf16 v[4:7], v[186:189], v[190:193], v[4:7]
	v_mfma_f32_16x16x32_bf16 v[0:3], v[186:189], v[194:197], v[0:3]
	v_mfma_f32_16x16x32_bf16 v[20:23], v[186:189], v[198:201], v[20:23]
	v_mfma_f32_16x16x32_bf16 v[8:11], v[186:189], v[202:205], v[8:11]
	ds_read_b128 v[172:175], v155 offset:8192
	ds_read_b128 v[176:179], v155 offset:10240
	ds_read_b128 v[182:185], v155 offset:12288
	ds_read_b128 v[186:189], v155 offset:14336
	s_waitcnt lgkmcnt(4)
	v_mfma_f32_16x16x32_bf16 v[124:127], v[156:159], v[206:209], v[124:127]
	v_mfma_f32_16x16x32_bf16 v[116:119], v[156:159], v[210:213], v[116:119]
	v_mfma_f32_16x16x32_bf16 v[120:123], v[156:159], v[214:217], v[120:123]
	v_mfma_f32_16x16x32_bf16 v[112:115], v[156:159], v[218:221], v[112:115]
	v_mfma_f32_16x16x32_bf16 v[108:111], v[160:163], v[206:209], v[108:111]
	v_mfma_f32_16x16x32_bf16 v[100:103], v[160:163], v[210:213], v[100:103]
	v_mfma_f32_16x16x32_bf16 v[104:107], v[160:163], v[214:217], v[104:107]
	v_mfma_f32_16x16x32_bf16 v[96:99], v[160:163], v[218:221], v[96:99]
	v_mfma_f32_16x16x32_bf16 v[92:95], v[164:167], v[206:209], v[92:95]
	v_mfma_f32_16x16x32_bf16 v[84:87], v[164:167], v[210:213], v[84:87]
	v_mfma_f32_16x16x32_bf16 v[88:91], v[164:167], v[214:217], v[88:91]
	v_mfma_f32_16x16x32_bf16 v[80:83], v[164:167], v[218:221], v[80:83]
	v_mfma_f32_16x16x32_bf16 v[76:79], v[168:171], v[206:209], v[76:79]
	v_mfma_f32_16x16x32_bf16 v[68:71], v[168:171], v[210:213], v[68:71]
	v_mfma_f32_16x16x32_bf16 v[72:75], v[168:171], v[214:217], v[72:75]
	v_mfma_f32_16x16x32_bf16 v[64:67], v[168:171], v[218:221], v[64:67]
	s_add_u32 s60, s60, 0x80
	s_addc_u32 s61, s61, 0
	s_add_i32 s59, s59, 1
	s_waitcnt lgkmcnt(0)
	s_waitcnt vmcnt(0)
	s_barrier
	v_mfma_f32_16x16x32_bf16 v[60:63], v[172:175], v[206:209], v[60:63]
	v_mfma_f32_16x16x32_bf16 v[52:55], v[172:175], v[210:213], v[52:55]
	v_mfma_f32_16x16x32_bf16 v[56:59], v[172:175], v[214:217], v[56:59]
	v_mfma_f32_16x16x32_bf16 v[48:51], v[172:175], v[218:221], v[48:51]
	v_mfma_f32_16x16x32_bf16 v[44:47], v[176:179], v[206:209], v[44:47]
	v_mfma_f32_16x16x32_bf16 v[36:39], v[176:179], v[210:213], v[36:39]
	v_mfma_f32_16x16x32_bf16 v[40:43], v[176:179], v[214:217], v[40:43]
	v_mfma_f32_16x16x32_bf16 v[32:35], v[176:179], v[218:221], v[32:35]
	v_mfma_f32_16x16x32_bf16 v[28:31], v[182:185], v[206:209], v[28:31]
	v_mfma_f32_16x16x32_bf16 v[16:19], v[182:185], v[210:213], v[16:19]
	v_mfma_f32_16x16x32_bf16 v[24:27], v[182:185], v[214:217], v[24:27]
	v_mfma_f32_16x16x32_bf16 v[12:15], v[182:185], v[218:221], v[12:15]
	v_mfma_f32_16x16x32_bf16 v[4:7], v[186:189], v[206:209], v[4:7]
	v_mfma_f32_16x16x32_bf16 v[0:3], v[186:189], v[210:213], v[0:3]
	v_mfma_f32_16x16x32_bf16 v[20:23], v[186:189], v[214:217], v[20:23]
	v_mfma_f32_16x16x32_bf16 v[8:11], v[186:189], v[218:221], v[8:11]
	s_nop 7
	s_nop 7
	s_sub_u32 s60, s60, s34
	s_subb_u32 s61, s61, s35
	s_mov_b32 s87, 0x80000
	s_mov_b32 s96, 0x80000
	s_mov_b64 s[88:89], 0
	s_mov_b64 vcc, exec
	s_branch .LBB0_120

.LBB0_263:
	s_ashr_i32 s21, s58, 2
	v_mov_b32_e32 v6, v181
	s_and_b32 s6, s58, 7
	s_and_b32 s21, s21, -8
	s_or_b32 s48, s21, s6
	v_lshrrev_b32_e32 v7, 4, v6
	v_lshlrev_b32_e32 v1, 6, v6
	v_xor_b32_e32 v0, v7, v6
	v_and_b32_e32 v8, 0x3c0, v1
	v_lshlrev_b32_e32 v1, 8, v6
	s_ashr_i32 s49, s48, 31
	v_lshlrev_b32_e32 v0, 3, v0
	v_and_b32_e32 v1, 0xfffff800, v1
	s_and_b32 s20, s57, 7
	s_bfe_u32 s6, s58, 0x20003
	s_lshl_b64 s[50:51], s[48:49], 20
	v_and_or_b32 v0, v0, 56, v1
	s_add_u32 s50, s3, s50
	v_ashrrev_i32_e32 v1, 31, v0
	s_addc_u32 s51, s54, s51
	v_lshlrev_b64 v[0:1], 1, v[0:1]
	v_lshl_add_u32 v135, v6, 4, 0
	v_lshl_add_u64 v[2:3], s[50:51], 0, v[0:1]
	v_readfirstlane_b32 s50, v135
	v_add_u32_e32 v9, 0x2000, v135
	s_mov_b32 m0, s50
	v_readfirstlane_b32 s50, v9
	v_add_u32_e32 v9, 0x4000, v135
	s_waitcnt lgkmcnt(0)
	s_barrier
	global_load_lds_dwordx4 v[2:3], off
	v_lshl_add_u64 v[4:5], v[2:3], 0, s[8:9]
	s_mov_b32 m0, s50
	v_readfirstlane_b32 s50, v9
	global_load_lds_dwordx4 v[4:5], off
	v_lshl_add_u64 v[4:5], v[2:3], 0, s[10:11]
	s_mov_b32 m0, s50
	s_lshl_b32 s49, s6, 20
	global_load_lds_dwordx4 v[4:5], off
	v_add_u32_e32 v4, 0x6000, v135
	s_add_u32 s52, s55, s49
	v_readfirstlane_b32 s50, v4
	v_add_u32_e32 v4, 0x8000, v135
	s_addc_u32 s53, s56, 0
	v_lshl_add_u64 v[2:3], v[2:3], 0, s[12:13]
	s_mov_b32 m0, s50
	v_readfirstlane_b32 s50, v4
	v_add_u32_e32 v9, 0xa000, v135
	global_load_lds_dwordx4 v[2:3], off
	v_lshl_add_u64 v[2:3], s[52:53], 0, v[0:1]
	s_mov_b32 m0, s50
	v_readfirstlane_b32 s50, v9
	v_add_u32_e32 v9, 0xc000, v135
	global_load_lds_dwordx4 v[2:3], off
	v_lshl_add_u64 v[4:5], v[2:3], 0, s[8:9]
	s_mov_b32 m0, s50
	v_readfirstlane_b32 s50, v9
	global_load_lds_dwordx4 v[4:5], off
	v_lshl_add_u64 v[4:5], v[2:3], 0, s[10:11]
	s_mov_b32 m0, s50
	v_lshl_add_u64 v[2:3], v[2:3], 0, s[12:13]
	global_load_lds_dwordx4 v[4:5], off
	v_add_u32_e32 v4, 0xe000, v135
	v_mov_b32_e32 v12, 0
	v_readfirstlane_b32 s50, v4
	s_mov_b32 m0, s50
	v_ashrrev_i32_e32 v4, 6, v6
	global_load_lds_dwordx4 v[2:3], off
	s_or_b32 s50, s21, s20
	v_lshrrev_b32_e32 v5, 30, v4
	s_ashr_i32 s51, s50, 31
	v_add_u32_e32 v5, v4, v5
	s_lshl_b64 s[50:51], s[50:51], 20
	v_bfe_u32 v2, v6, 4, 2
	v_bfe_u32 v3, v6, 1, 3
	v_and_b32_e32 v6, 0x7fffc, v5
	s_add_u32 s50, s34, s50
	v_sub_u32_e32 v4, v4, v6
	s_addc_u32 s51, s35, s51
	v_lshlrev_b32_e32 v137, 13, v4
	v_bitop3_b32 v4, v7, v3, 3 bitop3:0x6c
	v_bitop3_b32 v2, v2, v3, 4 bitop3:0x36
	v_lshl_add_u64 v[130:131], s[50:51], 0, v[0:1]
	s_add_u32 s50, s34, s49
	v_lshlrev_b32_e32 v5, 12, v5
	v_lshlrev_b32_e32 v4, 3, v4
	v_lshlrev_b32_e32 v2, 3, v2
	s_addc_u32 s51, s35, 0
	v_and_b32_e32 v136, 0xffffc000, v5
	v_lshl_add_u64 v[132:133], s[50:51], 0, v[0:1]
	s_mov_b64 s[50:51], 0
	v_lshlrev_b32_e32 v138, 1, v8
	v_lshlrev_b32_e32 v139, 1, v4
	v_lshlrev_b32_e32 v140, 1, v2
	s_mov_b32 s59, 0
	s_mov_b32 s49, 0
	v_mov_b32_e32 v13, v12
	v_mov_b32_e32 v14, v12
	v_mov_b32_e32 v15, v12
	v_mov_b32_e32 v24, v12
	v_mov_b32_e32 v25, v12
	v_mov_b32_e32 v26, v12
	v_mov_b32_e32 v27, v12
	v_mov_b32_e32 v0, v12
	v_mov_b32_e32 v1, v12
	v_mov_b32_e32 v2, v12
	v_mov_b32_e32 v3, v12
	v_mov_b32_e32 v4, v12
	v_mov_b32_e32 v5, v12
	v_mov_b32_e32 v6, v12
	v_mov_b32_e32 v7, v12
	v_mov_b32_e32 v8, v12
	v_mov_b32_e32 v9, v12
	v_mov_b32_e32 v10, v12
	v_mov_b32_e32 v11, v12
	v_mov_b32_e32 v16, v12
	v_mov_b32_e32 v17, v12
	v_mov_b32_e32 v18, v12
	v_mov_b32_e32 v19, v12
	v_mov_b32_e32 v20, v12
	v_mov_b32_e32 v21, v12
	v_mov_b32_e32 v22, v12
	v_mov_b32_e32 v23, v12
	v_mov_b32_e32 v28, v12
	v_mov_b32_e32 v29, v12
	v_mov_b32_e32 v30, v12
	v_mov_b32_e32 v31, v12
	v_mov_b32_e32 v32, v12
	v_mov_b32_e32 v33, v12
	v_mov_b32_e32 v34, v12
	v_mov_b32_e32 v35, v12
	v_mov_b32_e32 v36, v12
	v_mov_b32_e32 v37, v12
	v_mov_b32_e32 v38, v12
	v_mov_b32_e32 v39, v12
	v_mov_b32_e32 v40, v12
	v_mov_b32_e32 v41, v12
	v_mov_b32_e32 v42, v12
	v_mov_b32_e32 v43, v12
	v_mov_b32_e32 v44, v12
	v_mov_b32_e32 v45, v12
	v_mov_b32_e32 v46, v12
	v_mov_b32_e32 v47, v12
	v_mov_b32_e32 v48, v12
	v_mov_b32_e32 v49, v12
	v_mov_b32_e32 v50, v12
	v_mov_b32_e32 v51, v12
	v_mov_b32_e32 v52, v12
	v_mov_b32_e32 v53, v12
	v_mov_b32_e32 v54, v12
	v_mov_b32_e32 v55, v12
	v_mov_b32_e32 v56, v12
	v_mov_b32_e32 v57, v12
	v_mov_b32_e32 v58, v12
	v_mov_b32_e32 v59, v12
	v_mov_b32_e32 v60, v12
	v_mov_b32_e32 v61, v12
	v_mov_b32_e32 v62, v12
	v_mov_b32_e32 v63, v12
	v_mov_b32_e32 v64, v12
	v_mov_b32_e32 v65, v12
	v_mov_b32_e32 v66, v12
	v_mov_b32_e32 v67, v12
	v_mov_b32_e32 v68, v12
	v_mov_b32_e32 v69, v12
	v_mov_b32_e32 v70, v12
	v_mov_b32_e32 v71, v12
	v_mov_b32_e32 v72, v12
	v_mov_b32_e32 v73, v12
	v_mov_b32_e32 v74, v12
	v_mov_b32_e32 v75, v12
	v_mov_b32_e32 v76, v12
	v_mov_b32_e32 v77, v12
	v_mov_b32_e32 v78, v12
	v_mov_b32_e32 v79, v12
	v_mov_b32_e32 v80, v12
	v_mov_b32_e32 v81, v12
	v_mov_b32_e32 v82, v12
	v_mov_b32_e32 v83, v12
	v_mov_b32_e32 v84, v12
	v_mov_b32_e32 v85, v12
	v_mov_b32_e32 v86, v12
	v_mov_b32_e32 v87, v12
	v_mov_b32_e32 v88, v12
	v_mov_b32_e32 v89, v12
	v_mov_b32_e32 v90, v12
	v_mov_b32_e32 v91, v12
	v_mov_b32_e32 v92, v12
	v_mov_b32_e32 v93, v12
	v_mov_b32_e32 v94, v12
	v_mov_b32_e32 v95, v12
	v_mov_b32_e32 v96, v12
	v_mov_b32_e32 v97, v12
	v_mov_b32_e32 v98, v12
	v_mov_b32_e32 v99, v12
	v_mov_b32_e32 v100, v12
	v_mov_b32_e32 v101, v12
	v_mov_b32_e32 v102, v12
	v_mov_b32_e32 v103, v12
	v_mov_b32_e32 v104, v12
	v_mov_b32_e32 v105, v12
	v_mov_b32_e32 v106, v12
	v_mov_b32_e32 v107, v12
	v_mov_b32_e32 v108, v12
	v_mov_b32_e32 v109, v12
	v_mov_b32_e32 v110, v12
	v_mov_b32_e32 v111, v12
	v_mov_b32_e32 v112, v12
	v_mov_b32_e32 v113, v12
	v_mov_b32_e32 v114, v12
	v_mov_b32_e32 v115, v12
	v_mov_b32_e32 v116, v12
	v_mov_b32_e32 v117, v12
	v_mov_b32_e32 v118, v12
	v_mov_b32_e32 v119, v12
	v_mov_b32_e32 v120, v12
	v_mov_b32_e32 v121, v12
	v_mov_b32_e32 v122, v12
	v_mov_b32_e32 v123, v12
	v_mov_b32_e32 v124, v12
	v_mov_b32_e32 v125, v12
	v_mov_b32_e32 v126, v12
	v_mov_b32_e32 v127, v12
	s_waitcnt vmcnt(0) lgkmcnt(0)
	s_barrier
	v_add3_u32 v141, v136, v138, v139
	v_add3_u32 v210, v137, v138, v139
	v_add3_u32 v180, v136, v138, v140
	v_add3_u32 v211, v137, v138, v140
	v_readfirstlane_b32 s59, v135
	ds_read_b128 v[142:145], v141
	ds_read_b128 v[146:149], v141 offset:2048
	ds_read_b128 v[150:153], v141 offset:4096
	ds_read_b128 v[154:157], v141 offset:6144
	ds_read_b128 v[174:177], v210 offset:32768
	ds_read_b128 v[182:185], v210 offset:34816
	ds_read_b128 v[186:189], v210 offset:36864
	ds_read_b128 v[190:193], v210 offset:38912
	s_mov_b32 s49, 0
	s_mov_b64 s[50:51], s[34:35]
	v_subrev_u32_e32 v178, s34, v130
	v_subrev_u32_e32 v179, s34, v132
	s_add_u32 s59, s59, 0x10000
	s_add_u32 s52, s50, s14
	s_addc_u32 s53, s51, s15
	s_mov_b32 m0, s59
	global_load_lds_dwordx4 v178, s[52:53]
	s_add_u32 s52, s50, s16
	s_addc_u32 s53, s51, s17
	s_add_u32 m0, s59, 0x2000
	global_load_lds_dwordx4 v178, s[52:53]
	s_add_u32 s52, s50, s18
	s_addc_u32 s53, s51, s19
	s_add_u32 m0, s59, 0x4000
	global_load_lds_dwordx4 v178, s[52:53]
	s_add_u32 s52, s50, s22
	s_addc_u32 s53, s51, s23
	s_add_u32 m0, s59, 0x6000
	global_load_lds_dwordx4 v178, s[52:53]
	s_add_u32 s52, s50, s40
	s_addc_u32 s53, s51, s41
	s_add_u32 m0, s59, 0x8000
	global_load_lds_dwordx4 v179, s[52:53]
	s_add_u32 s52, s50, s42
	s_addc_u32 s53, s51, s43
	s_add_u32 m0, s59, 0xa000
	global_load_lds_dwordx4 v179, s[52:53]
	s_add_u32 s52, s50, s44
	s_addc_u32 s53, s51, s45
	s_add_u32 m0, s59, 0xc000
	global_load_lds_dwordx4 v179, s[52:53]
	s_add_u32 s52, s50, s46
	s_addc_u32 s53, s51, s47
	s_add_u32 m0, s59, 0xe000
	global_load_lds_dwordx4 v179, s[52:53]
	s_branch .Lg1_entry
.Lg1_top:
	s_waitcnt lgkmcnt(0)
	s_waitcnt vmcnt(0)
	s_barrier
	v_xor_b32_e32 v141, 0x10000, v141
	v_xor_b32_e32 v210, 0x10000, v210
	v_xor_b32_e32 v180, 0x10000, v180
	v_xor_b32_e32 v211, 0x10000, v211
	s_xor_b32 s59, s59, 0x10000
	ds_read_b128 v[142:145], v141
	ds_read_b128 v[146:149], v141 offset:2048
	ds_read_b128 v[150:153], v141 offset:4096
	ds_read_b128 v[154:157], v141 offset:6144
	ds_read_b128 v[174:177], v210 offset:32768
	ds_read_b128 v[182:185], v210 offset:34816
	ds_read_b128 v[186:189], v210 offset:36864
	ds_read_b128 v[190:193], v210 offset:38912
	v_mfma_f32_16x16x32_bf16 v[60:63], v[158:161], v[194:197], v[60:63]
	v_mfma_f32_16x16x32_bf16 v[56:59], v[158:161], v[198:201], v[56:59]
	s_add_u32 s52, s50, s14
	s_addc_u32 s53, s51, s15
	s_mov_b32 m0, s59
	global_load_lds_dwordx4 v178, s[52:53]
	v_mfma_f32_16x16x32_bf16 v[52:55], v[158:161], v[202:205], v[52:55]
	v_mfma_f32_16x16x32_bf16 v[48:51], v[158:161], v[206:209], v[48:51]
	s_add_u32 s52, s50, s16
	s_addc_u32 s53, s51, s17
	s_add_u32 m0, s59, 0x2000
	global_load_lds_dwordx4 v178, s[52:53]
	v_mfma_f32_16x16x32_bf16 v[44:47], v[162:165], v[194:197], v[44:47]
	v_mfma_f32_16x16x32_bf16 v[40:43], v[162:165], v[198:201], v[40:43]
	s_add_u32 s52, s50, s18
	s_addc_u32 s53, s51, s19
	s_add_u32 m0, s59, 0x4000
	global_load_lds_dwordx4 v178, s[52:53]
	v_mfma_f32_16x16x32_bf16 v[36:39], v[162:165], v[202:205], v[36:39]
	v_mfma_f32_16x16x32_bf16 v[32:35], v[162:165], v[206:209], v[32:35]
	s_add_u32 s52, s50, s22
	s_addc_u32 s53, s51, s23
	s_add_u32 m0, s59, 0x6000
	global_load_lds_dwordx4 v178, s[52:53]
	v_mfma_f32_16x16x32_bf16 v[28:31], v[166:169], v[194:197], v[28:31]
	v_mfma_f32_16x16x32_bf16 v[20:23], v[166:169], v[198:201], v[20:23]
	s_add_u32 s52, s50, s40
	s_addc_u32 s53, s51, s41
	s_add_u32 m0, s59, 0x8000
	global_load_lds_dwordx4 v179, s[52:53]
	v_mfma_f32_16x16x32_bf16 v[16:19], v[166:169], v[202:205], v[16:19]
	v_mfma_f32_16x16x32_bf16 v[8:11], v[166:169], v[206:209], v[8:11]
	s_add_u32 s52, s50, s42
	s_addc_u32 s53, s51, s43
	s_add_u32 m0, s59, 0xa000
	global_load_lds_dwordx4 v179, s[52:53]
	v_mfma_f32_16x16x32_bf16 v[4:7], v[170:173], v[194:197], v[4:7]
	v_mfma_f32_16x16x32_bf16 v[0:3], v[170:173], v[198:201], v[0:3]
	s_add_u32 s52, s50, s44
	s_addc_u32 s53, s51, s45
	s_add_u32 m0, s59, 0xc000
	global_load_lds_dwordx4 v179, s[52:53]
	v_mfma_f32_16x16x32_bf16 v[24:27], v[170:173], v[202:205], v[24:27]
	v_mfma_f32_16x16x32_bf16 v[12:15], v[170:173], v[206:209], v[12:15]
	s_add_u32 s52, s50, s46
	s_addc_u32 s53, s51, s47
	s_add_u32 m0, s59, 0xe000
	global_load_lds_dwordx4 v179, s[52:53]
.Lg1_entry:
	ds_read_b128 v[158:161], v141 offset:8192
	ds_read_b128 v[162:165], v141 offset:10240
	ds_read_b128 v[166:169], v141 offset:12288
	ds_read_b128 v[170:173], v141 offset:14336
	s_waitcnt lgkmcnt(4)
	v_mfma_f32_16x16x32_bf16 v[124:127], v[142:145], v[174:177], v[124:127]
	v_mfma_f32_16x16x32_bf16 v[120:123], v[142:145], v[182:185], v[120:123]
	v_mfma_f32_16x16x32_bf16 v[116:119], v[142:145], v[186:189], v[116:119]
	v_mfma_f32_16x16x32_bf16 v[112:115], v[142:145], v[190:193], v[112:115]
	v_mfma_f32_16x16x32_bf16 v[108:111], v[146:149], v[174:177], v[108:111]
	v_mfma_f32_16x16x32_bf16 v[104:107], v[146:149], v[182:185], v[104:107]
	v_mfma_f32_16x16x32_bf16 v[100:103], v[146:149], v[186:189], v[100:103]
	v_mfma_f32_16x16x32_bf16 v[96:99], v[146:149], v[190:193], v[96:99]
	v_mfma_f32_16x16x32_bf16 v[92:95], v[150:153], v[174:177], v[92:95]
	v_mfma_f32_16x16x32_bf16 v[88:91], v[150:153], v[182:185], v[88:91]
	v_mfma_f32_16x16x32_bf16 v[84:87], v[150:153], v[186:189], v[84:87]
	v_mfma_f32_16x16x32_bf16 v[80:83], v[150:153], v[190:193], v[80:83]
	v_mfma_f32_16x16x32_bf16 v[76:79], v[154:157], v[174:177], v[76:79]
	v_mfma_f32_16x16x32_bf16 v[72:75], v[154:157], v[182:185], v[72:75]
	v_mfma_f32_16x16x32_bf16 v[68:71], v[154:157], v[186:189], v[68:71]
	v_mfma_f32_16x16x32_bf16 v[64:67], v[154:157], v[190:193], v[64:67]
	ds_read_b128 v[142:145], v180
	ds_read_b128 v[146:149], v180 offset:2048
	ds_read_b128 v[150:153], v180 offset:4096
	ds_read_b128 v[154:157], v180 offset:6144
	ds_read_b128 v[194:197], v211 offset:32768
	ds_read_b128 v[198:201], v211 offset:34816
	ds_read_b128 v[202:205], v211 offset:36864
	ds_read_b128 v[206:209], v211 offset:38912
	s_waitcnt lgkmcnt(8)
	v_mfma_f32_16x16x32_bf16 v[60:63], v[158:161], v[174:177], v[60:63]
	v_mfma_f32_16x16x32_bf16 v[56:59], v[158:161], v[182:185], v[56:59]
	v_mfma_f32_16x16x32_bf16 v[52:55], v[158:161], v[186:189], v[52:55]
	v_mfma_f32_16x16x32_bf16 v[48:51], v[158:161], v[190:193], v[48:51]
	v_mfma_f32_16x16x32_bf16 v[44:47], v[162:165], v[174:177], v[44:47]
	v_mfma_f32_16x16x32_bf16 v[40:43], v[162:165], v[182:185], v[40:43]
	v_mfma_f32_16x16x32_bf16 v[36:39], v[162:165], v[186:189], v[36:39]
	v_mfma_f32_16x16x32_bf16 v[32:35], v[162:165], v[190:193], v[32:35]
	v_mfma_f32_16x16x32_bf16 v[28:31], v[166:169], v[174:177], v[28:31]
	v_mfma_f32_16x16x32_bf16 v[20:23], v[166:169], v[182:185], v[20:23]
	v_mfma_f32_16x16x32_bf16 v[16:19], v[166:169], v[186:189], v[16:19]
	v_mfma_f32_16x16x32_bf16 v[8:11], v[166:169], v[190:193], v[8:11]
	v_mfma_f32_16x16x32_bf16 v[4:7], v[170:173], v[174:177], v[4:7]
	v_mfma_f32_16x16x32_bf16 v[0:3], v[170:173], v[182:185], v[0:3]
	v_mfma_f32_16x16x32_bf16 v[24:27], v[170:173], v[186:189], v[24:27]
	v_mfma_f32_16x16x32_bf16 v[12:15], v[170:173], v[190:193], v[12:15]
	ds_read_b128 v[158:161], v180 offset:8192
	ds_read_b128 v[162:165], v180 offset:10240
	ds_read_b128 v[166:169], v180 offset:12288
	ds_read_b128 v[170:173], v180 offset:14336
	s_waitcnt lgkmcnt(4)
	v_mfma_f32_16x16x32_bf16 v[124:127], v[142:145], v[194:197], v[124:127]
	v_mfma_f32_16x16x32_bf16 v[120:123], v[142:145], v[198:201], v[120:123]
	v_mfma_f32_16x16x32_bf16 v[116:119], v[142:145], v[202:205], v[116:119]
	v_mfma_f32_16x16x32_bf16 v[112:115], v[142:145], v[206:209], v[112:115]
	v_mfma_f32_16x16x32_bf16 v[108:111], v[146:149], v[194:197], v[108:111]
	v_mfma_f32_16x16x32_bf16 v[104:107], v[146:149], v[198:201], v[104:107]
	v_mfma_f32_16x16x32_bf16 v[100:103], v[146:149], v[202:205], v[100:103]
	v_mfma_f32_16x16x32_bf16 v[96:99], v[146:149], v[206:209], v[96:99]
	v_mfma_f32_16x16x32_bf16 v[92:95], v[150:153], v[194:197], v[92:95]
	v_mfma_f32_16x16x32_bf16 v[88:91], v[150:153], v[198:201], v[88:91]
	v_mfma_f32_16x16x32_bf16 v[84:87], v[150:153], v[202:205], v[84:87]
	v_mfma_f32_16x16x32_bf16 v[80:83], v[150:153], v[206:209], v[80:83]
	v_mfma_f32_16x16x32_bf16 v[76:79], v[154:157], v[194:197], v[76:79]
	v_mfma_f32_16x16x32_bf16 v[72:75], v[154:157], v[198:201], v[72:75]
	v_mfma_f32_16x16x32_bf16 v[68:71], v[154:157], v[202:205], v[68:71]
	v_mfma_f32_16x16x32_bf16 v[64:67], v[154:157], v[206:209], v[64:67]
	s_add_u32 s50, s50, 0x80
	s_addc_u32 s51, s51, 0
	s_add_i32 s49, s49, 1
	s_cmp_lt_u32 s49, 31
	s_cbranch_scc1 .Lg1_top
	s_waitcnt lgkmcnt(0)
	s_waitcnt vmcnt(0)
	s_barrier
	v_xor_b32_e32 v141, 0x10000, v141
	v_xor_b32_e32 v210, 0x10000, v210
	v_xor_b32_e32 v180, 0x10000, v180
	v_xor_b32_e32 v211, 0x10000, v211
	s_xor_b32 s59, s59, 0x10000
	ds_read_b128 v[142:145], v141
	ds_read_b128 v[146:149], v141 offset:2048
	ds_read_b128 v[150:153], v141 offset:4096
	ds_read_b128 v[154:157], v141 offset:6144
	ds_read_b128 v[174:177], v210 offset:32768
	ds_read_b128 v[182:185], v210 offset:34816
	ds_read_b128 v[186:189], v210 offset:36864
	ds_read_b128 v[190:193], v210 offset:38912
	v_mfma_f32_16x16x32_bf16 v[60:63], v[158:161], v[194:197], v[60:63]
	v_mfma_f32_16x16x32_bf16 v[56:59], v[158:161], v[198:201], v[56:59]
	v_mfma_f32_16x16x32_bf16 v[52:55], v[158:161], v[202:205], v[52:55]
	v_mfma_f32_16x16x32_bf16 v[48:51], v[158:161], v[206:209], v[48:51]
	v_mfma_f32_16x16x32_bf16 v[44:47], v[162:165], v[194:197], v[44:47]
	v_mfma_f32_16x16x32_bf16 v[40:43], v[162:165], v[198:201], v[40:43]
	v_mfma_f32_16x16x32_bf16 v[36:39], v[162:165], v[202:205], v[36:39]
	v_mfma_f32_16x16x32_bf16 v[32:35], v[162:165], v[206:209], v[32:35]
	v_mfma_f32_16x16x32_bf16 v[28:31], v[166:169], v[194:197], v[28:31]
	v_mfma_f32_16x16x32_bf16 v[20:23], v[166:169], v[198:201], v[20:23]
	v_mfma_f32_16x16x32_bf16 v[16:19], v[166:169], v[202:205], v[16:19]
	v_mfma_f32_16x16x32_bf16 v[8:11], v[166:169], v[206:209], v[8:11]
	v_mfma_f32_16x16x32_bf16 v[4:7], v[170:173], v[194:197], v[4:7]
	v_mfma_f32_16x16x32_bf16 v[0:3], v[170:173], v[198:201], v[0:3]
	v_mfma_f32_16x16x32_bf16 v[24:27], v[170:173], v[202:205], v[24:27]
	v_mfma_f32_16x16x32_bf16 v[12:15], v[170:173], v[206:209], v[12:15]
	ds_read_b128 v[158:161], v141 offset:8192
	ds_read_b128 v[162:165], v141 offset:10240
	ds_read_b128 v[166:169], v141 offset:12288
	ds_read_b128 v[170:173], v141 offset:14336
	s_waitcnt lgkmcnt(4)
	v_mfma_f32_16x16x32_bf16 v[124:127], v[142:145], v[174:177], v[124:127]
	v_mfma_f32_16x16x32_bf16 v[120:123], v[142:145], v[182:185], v[120:123]
	v_mfma_f32_16x16x32_bf16 v[116:119], v[142:145], v[186:189], v[116:119]
	v_mfma_f32_16x16x32_bf16 v[112:115], v[142:145], v[190:193], v[112:115]
	v_mfma_f32_16x16x32_bf16 v[108:111], v[146:149], v[174:177], v[108:111]
	v_mfma_f32_16x16x32_bf16 v[104:107], v[146:149], v[182:185], v[104:107]
	v_mfma_f32_16x16x32_bf16 v[100:103], v[146:149], v[186:189], v[100:103]
	v_mfma_f32_16x16x32_bf16 v[96:99], v[146:149], v[190:193], v[96:99]
	v_mfma_f32_16x16x32_bf16 v[92:95], v[150:153], v[174:177], v[92:95]
	v_mfma_f32_16x16x32_bf16 v[88:91], v[150:153], v[182:185], v[88:91]
	v_mfma_f32_16x16x32_bf16 v[84:87], v[150:153], v[186:189], v[84:87]
	v_mfma_f32_16x16x32_bf16 v[80:83], v[150:153], v[190:193], v[80:83]
	v_mfma_f32_16x16x32_bf16 v[76:79], v[154:157], v[174:177], v[76:79]
	v_mfma_f32_16x16x32_bf16 v[72:75], v[154:157], v[182:185], v[72:75]
	v_mfma_f32_16x16x32_bf16 v[68:71], v[154:157], v[186:189], v[68:71]
	v_mfma_f32_16x16x32_bf16 v[64:67], v[154:157], v[190:193], v[64:67]
	ds_read_b128 v[142:145], v180
	ds_read_b128 v[146:149], v180 offset:2048
	ds_read_b128 v[150:153], v180 offset:4096
	ds_read_b128 v[154:157], v180 offset:6144
	ds_read_b128 v[194:197], v211 offset:32768
	ds_read_b128 v[198:201], v211 offset:34816
	ds_read_b128 v[202:205], v211 offset:36864
	ds_read_b128 v[206:209], v211 offset:38912
	s_waitcnt lgkmcnt(8)
	v_mfma_f32_16x16x32_bf16 v[60:63], v[158:161], v[174:177], v[60:63]
	v_mfma_f32_16x16x32_bf16 v[56:59], v[158:161], v[182:185], v[56:59]
	v_mfma_f32_16x16x32_bf16 v[52:55], v[158:161], v[186:189], v[52:55]
	v_mfma_f32_16x16x32_bf16 v[48:51], v[158:161], v[190:193], v[48:51]
	v_mfma_f32_16x16x32_bf16 v[44:47], v[162:165], v[174:177], v[44:47]
	v_mfma_f32_16x16x32_bf16 v[40:43], v[162:165], v[182:185], v[40:43]
	v_mfma_f32_16x16x32_bf16 v[36:39], v[162:165], v[186:189], v[36:39]
	v_mfma_f32_16x16x32_bf16 v[32:35], v[162:165], v[190:193], v[32:35]
	v_mfma_f32_16x16x32_bf16 v[28:31], v[166:169], v[174:177], v[28:31]
	v_mfma_f32_16x16x32_bf16 v[20:23], v[166:169], v[182:185], v[20:23]
	v_mfma_f32_16x16x32_bf16 v[16:19], v[166:169], v[186:189], v[16:19]
	v_mfma_f32_16x16x32_bf16 v[8:11], v[166:169], v[190:193], v[8:11]
	v_mfma_f32_16x16x32_bf16 v[4:7], v[170:173], v[174:177], v[4:7]
	v_mfma_f32_16x16x32_bf16 v[0:3], v[170:173], v[182:185], v[0:3]
	v_mfma_f32_16x16x32_bf16 v[24:27], v[170:173], v[186:189], v[24:27]
	v_mfma_f32_16x16x32_bf16 v[12:15], v[170:173], v[190:193], v[12:15]
	ds_read_b128 v[158:161], v180 offset:8192
	ds_read_b128 v[162:165], v180 offset:10240
	ds_read_b128 v[166:169], v180 offset:12288
	ds_read_b128 v[170:173], v180 offset:14336
	s_waitcnt lgkmcnt(4)
	v_mfma_f32_16x16x32_bf16 v[124:127], v[142:145], v[194:197], v[124:127]
	v_mfma_f32_16x16x32_bf16 v[120:123], v[142:145], v[198:201], v[120:123]
	v_mfma_f32_16x16x32_bf16 v[116:119], v[142:145], v[202:205], v[116:119]
	v_mfma_f32_16x16x32_bf16 v[112:115], v[142:145], v[206:209], v[112:115]
	v_mfma_f32_16x16x32_bf16 v[108:111], v[146:149], v[194:197], v[108:111]
	v_mfma_f32_16x16x32_bf16 v[104:107], v[146:149], v[198:201], v[104:107]
	v_mfma_f32_16x16x32_bf16 v[100:103], v[146:149], v[202:205], v[100:103]
	v_mfma_f32_16x16x32_bf16 v[96:99], v[146:149], v[206:209], v[96:99]
	v_mfma_f32_16x16x32_bf16 v[92:95], v[150:153], v[194:197], v[92:95]
	v_mfma_f32_16x16x32_bf16 v[88:91], v[150:153], v[198:201], v[88:91]
	v_mfma_f32_16x16x32_bf16 v[84:87], v[150:153], v[202:205], v[84:87]
	v_mfma_f32_16x16x32_bf16 v[80:83], v[150:153], v[206:209], v[80:83]
	v_mfma_f32_16x16x32_bf16 v[76:79], v[154:157], v[194:197], v[76:79]
	v_mfma_f32_16x16x32_bf16 v[72:75], v[154:157], v[198:201], v[72:75]
	v_mfma_f32_16x16x32_bf16 v[68:71], v[154:157], v[202:205], v[68:71]
	v_mfma_f32_16x16x32_bf16 v[64:67], v[154:157], v[206:209], v[64:67]
	s_add_u32 s50, s50, 0x80
	s_addc_u32 s51, s51, 0
	s_add_i32 s49, s49, 1
	s_waitcnt lgkmcnt(0)
	s_waitcnt vmcnt(0)
	s_barrier
	v_mfma_f32_16x16x32_bf16 v[60:63], v[158:161], v[194:197], v[60:63]
	v_mfma_f32_16x16x32_bf16 v[56:59], v[158:161], v[198:201], v[56:59]
	v_mfma_f32_16x16x32_bf16 v[52:55], v[158:161], v[202:205], v[52:55]
	v_mfma_f32_16x16x32_bf16 v[48:51], v[158:161], v[206:209], v[48:51]
	v_mfma_f32_16x16x32_bf16 v[44:47], v[162:165], v[194:197], v[44:47]
	v_mfma_f32_16x16x32_bf16 v[40:43], v[162:165], v[198:201], v[40:43]
	v_mfma_f32_16x16x32_bf16 v[36:39], v[162:165], v[202:205], v[36:39]
	v_mfma_f32_16x16x32_bf16 v[32:35], v[162:165], v[206:209], v[32:35]
	v_mfma_f32_16x16x32_bf16 v[28:31], v[166:169], v[194:197], v[28:31]
	v_mfma_f32_16x16x32_bf16 v[20:23], v[166:169], v[198:201], v[20:23]
	v_mfma_f32_16x16x32_bf16 v[16:19], v[166:169], v[202:205], v[16:19]
	v_mfma_f32_16x16x32_bf16 v[8:11], v[166:169], v[206:209], v[8:11]
	v_mfma_f32_16x16x32_bf16 v[4:7], v[170:173], v[194:197], v[4:7]
	v_mfma_f32_16x16x32_bf16 v[0:3], v[170:173], v[198:201], v[0:3]
	v_mfma_f32_16x16x32_bf16 v[24:27], v[170:173], v[202:205], v[24:27]
	v_mfma_f32_16x16x32_bf16 v[12:15], v[170:173], v[206:209], v[12:15]
	s_nop 7
	s_nop 7
	s_sub_u32 s50, s50, s34
	s_subb_u32 s51, s51, s35
	s_mov_b32 s59, 0x100000
	s_mov_b32 s60, 0x100000
	s_mov_b64 s[52:53], 0
	s_mov_b64 vcc, exec
	s_branch .LBB0_262

.LBB0_452:
	s_ashr_i32 s46, s60, 3
	s_and_b32 s21, s60, 7
	s_and_b32 s62, s46, -8
	v_mov_b32_e32 v6, v181
	s_or_b32 s46, s62, s21
	s_ashr_i32 s47, s46, 31
	v_lshrrev_b32_e32 v7, 4, v6
	v_lshlrev_b32_e32 v1, 6, v6
	v_xor_b32_e32 v0, v7, v6
	v_and_b32_e32 v8, 0x3c0, v1
	v_lshlrev_b32_e32 v1, 7, v6
	s_and_b32 s20, s55, 7
	s_bfe_u32 s61, s60, 0x30003
	s_lshl_b64 s[48:49], s[46:47], 19
	v_lshlrev_b32_e32 v0, 3, v0
	v_and_b32_e32 v1, 0xfffffc00, v1
	s_add_u32 s48, s3, s48
	v_and_or_b32 v0, v0, 56, v1
	s_addc_u32 s49, s54, s49
	s_lshl_b32 s21, s61, 19
	v_ashrrev_i32_e32 v1, 31, v0
	v_lshl_add_u32 v140, v6, 4, 0
	s_add_u32 s50, s34, s21
	v_lshlrev_b64 v[0:1], 1, v[0:1]
	v_readfirstlane_b32 s21, v140
	v_add_u32_e32 v9, 0x2000, v140
	v_lshl_add_u64 v[2:3], s[48:49], 0, v[0:1]
	s_mov_b32 m0, s21
	v_readfirstlane_b32 s21, v9
	v_add_u32_e32 v9, 0x4000, v140
	s_barrier
	global_load_lds_dwordx4 v[2:3], off
	v_lshl_add_u64 v[4:5], v[2:3], 0, s[6:7]
	s_mov_b32 m0, s21
	v_readfirstlane_b32 s21, v9
	global_load_lds_dwordx4 v[4:5], off
	v_lshl_add_u64 v[4:5], v[2:3], 0, s[8:9]
	s_mov_b32 m0, s21
	v_lshl_add_u64 v[2:3], v[2:3], 0, s[10:11]
	global_load_lds_dwordx4 v[4:5], off
	v_add_u32_e32 v4, 0x6000, v140
	s_addc_u32 s51, s35, 0
	v_readfirstlane_b32 s21, v4
	s_mov_b32 m0, s21
	v_add_u32_e32 v4, 0xa000, v140
	global_load_lds_dwordx4 v[2:3], off
	v_add_u32_e32 v2, 0x8000, v140
	v_lshl_add_u64 v[132:133], s[50:51], 0, v[0:1]
	v_readfirstlane_b32 s21, v2
	s_mov_b32 m0, s21
	v_readfirstlane_b32 s21, v4
	v_add_u32_e32 v4, 0xc000, v140
	global_load_lds_dwordx4 v[132:133], off
	v_lshl_add_u64 v[2:3], v[132:133], 0, s[6:7]
	s_mov_b32 m0, s21
	v_readfirstlane_b32 s21, v4
	v_add_u32_e32 v4, 0xe000, v140
	global_load_lds_dwordx4 v[2:3], off
	v_lshl_add_u64 v[2:3], v[132:133], 0, s[8:9]
	s_mov_b32 m0, s21
	v_readfirstlane_b32 s21, v4
	global_load_lds_dwordx4 v[2:3], off
	v_lshl_add_u64 v[2:3], v[132:133], 0, s[10:11]
	s_mov_b32 m0, s21
	v_ashrrev_i32_e32 v4, 6, v6
	global_load_lds_dwordx4 v[2:3], off
	v_lshrrev_b32_e32 v5, 30, v4
	v_add_u32_e32 v5, v4, v5
	s_or_b32 s48, s62, s20
	v_bfe_u32 v2, v6, 4, 2
	v_bfe_u32 v3, v6, 1, 3
	v_and_b32_e32 v6, 0x7fffc, v5
	s_ashr_i32 s49, s48, 31
	v_sub_u32_e32 v4, v4, v6
	s_lshl_b64 s[48:49], s[48:49], 19
	v_lshlrev_b32_e32 v142, 13, v4
	v_bitop3_b32 v4, v7, v3, 3 bitop3:0x6c
	v_bitop3_b32 v2, v2, v3, 4 bitop3:0x36
	s_add_u32 s48, s34, s48
	v_lshlrev_b32_e32 v5, 12, v5
	v_lshlrev_b32_e32 v4, 3, v4
	v_lshlrev_b32_e32 v2, 3, v2
	s_addc_u32 s49, s35, s49
	v_and_b32_e32 v141, 0xffffc000, v5
	v_lshl_add_u64 v[134:135], s[48:49], 0, v[0:1]
	s_mov_b64 s[48:49], 0
	v_lshlrev_b32_e32 v143, 1, v8
	v_lshlrev_b32_e32 v144, 1, v4
	v_lshlrev_b32_e32 v145, 1, v2
	s_mov_b32 s62, 0
	s_mov_b32 s47, 0
	v_mov_b32_e32 v40, 0
	v_mov_b32_e32 v41, v129
	v_mov_b32_e32 v42, v129
	v_mov_b32_e32 v43, v129
	v_mov_b32_e32 v48, 0
	v_mov_b32_e32 v49, v129
	v_mov_b32_e32 v50, v129
	v_mov_b32_e32 v51, v129
	v_mov_b32_e32 v0, 0
	v_mov_b32_e32 v1, v129
	v_mov_b32_e32 v2, v129
	v_mov_b32_e32 v3, v129
	v_mov_b32_e32 v4, 0
	v_mov_b32_e32 v5, v129
	v_mov_b32_e32 v6, v129
	v_mov_b32_e32 v7, v129
	v_mov_b32_e32 v8, 0
	v_mov_b32_e32 v9, v129
	v_mov_b32_e32 v10, v129
	v_mov_b32_e32 v11, v129
	v_mov_b32_e32 v12, 0
	v_mov_b32_e32 v13, v129
	v_mov_b32_e32 v14, v129
	v_mov_b32_e32 v15, v129
	v_mov_b32_e32 v16, 0
	v_mov_b32_e32 v17, v129
	v_mov_b32_e32 v18, v129
	v_mov_b32_e32 v19, v129
	v_mov_b32_e32 v20, 0
	v_mov_b32_e32 v21, v129
	v_mov_b32_e32 v22, v129
	v_mov_b32_e32 v23, v129
	v_mov_b32_e32 v24, 0
	v_mov_b32_e32 v25, v129
	v_mov_b32_e32 v26, v129
	v_mov_b32_e32 v27, v129
	v_mov_b32_e32 v28, 0
	v_mov_b32_e32 v29, v129
	v_mov_b32_e32 v30, v129
	v_mov_b32_e32 v31, v129
	v_mov_b32_e32 v32, 0
	v_mov_b32_e32 v33, v129
	v_mov_b32_e32 v34, v129
	v_mov_b32_e32 v35, v129
	v_mov_b32_e32 v36, 0
	v_mov_b32_e32 v37, v129
	v_mov_b32_e32 v38, v129
	v_mov_b32_e32 v39, v129
	v_mov_b32_e32 v44, 0
	v_mov_b32_e32 v45, v129
	v_mov_b32_e32 v46, v129
	v_mov_b32_e32 v47, v129
	v_mov_b32_e32 v52, 0
	v_mov_b32_e32 v53, v129
	v_mov_b32_e32 v54, v129
	v_mov_b32_e32 v55, v129
	v_mov_b32_e32 v56, 0
	v_mov_b32_e32 v57, v129
	v_mov_b32_e32 v58, v129
	v_mov_b32_e32 v59, v129
	v_mov_b32_e32 v60, 0
	v_mov_b32_e32 v61, v129
	v_mov_b32_e32 v62, v129
	v_mov_b32_e32 v63, v129
	v_mov_b32_e32 v64, 0
	v_mov_b32_e32 v65, v129
	v_mov_b32_e32 v66, v129
	v_mov_b32_e32 v67, v129
	v_mov_b32_e32 v68, 0
	v_mov_b32_e32 v69, v129
	v_mov_b32_e32 v70, v129
	v_mov_b32_e32 v71, v129
	v_mov_b32_e32 v72, 0
	v_mov_b32_e32 v73, v129
	v_mov_b32_e32 v74, v129
	v_mov_b32_e32 v75, v129
	v_mov_b32_e32 v76, 0
	v_mov_b32_e32 v77, v129
	v_mov_b32_e32 v78, v129
	v_mov_b32_e32 v79, v129
	v_mov_b32_e32 v80, 0
	v_mov_b32_e32 v81, v129
	v_mov_b32_e32 v82, v129
	v_mov_b32_e32 v83, v129
	v_mov_b32_e32 v84, 0
	v_mov_b32_e32 v85, v129
	v_mov_b32_e32 v86, v129
	v_mov_b32_e32 v87, v129
	v_mov_b32_e32 v88, 0
	v_mov_b32_e32 v89, v129
	v_mov_b32_e32 v90, v129
	v_mov_b32_e32 v91, v129
	v_mov_b32_e32 v92, 0
	v_mov_b32_e32 v93, v129
	v_mov_b32_e32 v94, v129
	v_mov_b32_e32 v95, v129
	v_mov_b32_e32 v96, 0
	v_mov_b32_e32 v97, v129
	v_mov_b32_e32 v98, v129
	v_mov_b32_e32 v99, v129
	v_mov_b32_e32 v100, 0
	v_mov_b32_e32 v101, v129
	v_mov_b32_e32 v102, v129
	v_mov_b32_e32 v103, v129
	v_mov_b32_e32 v104, 0
	v_mov_b32_e32 v105, v129
	v_mov_b32_e32 v106, v129
	v_mov_b32_e32 v107, v129
	v_mov_b32_e32 v108, 0
	v_mov_b32_e32 v109, v129
	v_mov_b32_e32 v110, v129
	v_mov_b32_e32 v111, v129
	v_mov_b32_e32 v112, 0
	v_mov_b32_e32 v113, v129
	v_mov_b32_e32 v114, v129
	v_mov_b32_e32 v115, v129
	v_mov_b32_e32 v116, 0
	v_mov_b32_e32 v117, v129
	v_mov_b32_e32 v118, v129
	v_mov_b32_e32 v119, v129
	v_mov_b32_e32 v120, 0
	v_mov_b32_e32 v121, v129
	v_mov_b32_e32 v122, v129
	v_mov_b32_e32 v123, v129
	v_mov_b32_e32 v124, 0
	v_mov_b32_e32 v125, v129
	v_mov_b32_e32 v126, v129
	v_mov_b32_e32 v127, v129
	s_waitcnt vmcnt(0) lgkmcnt(0)
	s_barrier
	v_add3_u32 v180, v141, v143, v144
	v_add3_u32 v215, v142, v143, v144
	v_add3_u32 v214, v141, v143, v145
	v_add3_u32 v216, v142, v143, v145
	v_readfirstlane_b32 s62, v140
	ds_read_b128 v[146:149], v180
	ds_read_b128 v[150:153], v180 offset:2048
	ds_read_b128 v[154:157], v180 offset:4096
	ds_read_b128 v[158:161], v180 offset:6144
	ds_read_b128 v[182:185], v215 offset:32768
	ds_read_b128 v[186:189], v215 offset:34816
	ds_read_b128 v[190:193], v215 offset:36864
	ds_read_b128 v[194:197], v215 offset:38912
	s_mov_b32 s47, 0
	s_mov_b64 s[48:49], s[34:35]
	v_subrev_u32_e32 v178, s34, v134
	v_subrev_u32_e32 v179, s34, v132
	s_add_u32 s62, s62, 0x10000
	s_add_u32 s50, s48, s12
	s_addc_u32 s51, s49, s13
	s_mov_b32 m0, s62
	global_load_lds_dwordx4 v178, s[50:51]
	s_add_u32 s50, s48, s14
	s_addc_u32 s51, s49, s15
	s_add_u32 m0, s62, 0x2000
	global_load_lds_dwordx4 v178, s[50:51]
	s_add_u32 s50, s48, s16
	s_addc_u32 s51, s49, s17
	s_add_u32 m0, s62, 0x4000
	global_load_lds_dwordx4 v178, s[50:51]
	s_add_u32 s50, s48, s18
	s_addc_u32 s51, s49, s19
	s_add_u32 m0, s62, 0x6000
	global_load_lds_dwordx4 v178, s[50:51]
	s_add_u32 s50, s48, s22
	s_addc_u32 s51, s49, s23
	s_add_u32 m0, s62, 0x8000
	global_load_lds_dwordx4 v179, s[50:51]
	s_add_u32 s50, s48, s36
	s_addc_u32 s51, s49, s37
	s_add_u32 m0, s62, 0xa000
	global_load_lds_dwordx4 v179, s[50:51]
	s_add_u32 s50, s48, s40
	s_addc_u32 s51, s49, s41
	s_add_u32 m0, s62, 0xc000
	global_load_lds_dwordx4 v179, s[50:51]
	s_add_u32 s50, s48, s42
	s_addc_u32 s51, s49, s43
	s_add_u32 m0, s62, 0xe000
	global_load_lds_dwordx4 v179, s[50:51]
	s_branch .Lg2_entry
.Lg2_top:
	s_waitcnt lgkmcnt(0)
	s_waitcnt vmcnt(0)
	s_barrier
	v_xor_b32_e32 v180, 0x10000, v180
	v_xor_b32_e32 v215, 0x10000, v215
	v_xor_b32_e32 v214, 0x10000, v214
	v_xor_b32_e32 v216, 0x10000, v216
	s_xor_b32 s62, s62, 0x10000
	ds_read_b128 v[146:149], v180
	ds_read_b128 v[150:153], v180 offset:2048
	ds_read_b128 v[154:157], v180 offset:4096
	ds_read_b128 v[158:161], v180 offset:6144
	ds_read_b128 v[182:185], v215 offset:32768
	ds_read_b128 v[186:189], v215 offset:34816
	ds_read_b128 v[190:193], v215 offset:36864
	ds_read_b128 v[194:197], v215 offset:38912
	v_mfma_f32_16x16x32_bf16 v[60:63], v[162:165], v[198:201], v[60:63]
	v_mfma_f32_16x16x32_bf16 v[56:59], v[162:165], v[202:205], v[56:59]
	s_add_u32 s50, s48, s12
	s_addc_u32 s51, s49, s13
	s_mov_b32 m0, s62
	global_load_lds_dwordx4 v178, s[50:51]
	v_mfma_f32_16x16x32_bf16 v[52:55], v[162:165], v[206:209], v[52:55]
	v_mfma_f32_16x16x32_bf16 v[44:47], v[162:165], v[210:213], v[44:47]
	s_add_u32 s50, s48, s14
	s_addc_u32 s51, s49, s15
	s_add_u32 m0, s62, 0x2000
	global_load_lds_dwordx4 v178, s[50:51]
	v_mfma_f32_16x16x32_bf16 v[36:39], v[166:169], v[198:201], v[36:39]
	v_mfma_f32_16x16x32_bf16 v[32:35], v[166:169], v[202:205], v[32:35]
	s_add_u32 s50, s48, s16
	s_addc_u32 s51, s49, s17
	s_add_u32 m0, s62, 0x4000
	global_load_lds_dwordx4 v178, s[50:51]
	v_mfma_f32_16x16x32_bf16 v[28:31], v[166:169], v[206:209], v[28:31]
	v_mfma_f32_16x16x32_bf16 v[24:27], v[166:169], v[210:213], v[24:27]
	s_add_u32 s50, s48, s18
	s_addc_u32 s51, s49, s19
	s_add_u32 m0, s62, 0x6000
	global_load_lds_dwordx4 v178, s[50:51]
	v_mfma_f32_16x16x32_bf16 v[20:23], v[170:173], v[198:201], v[20:23]
	v_mfma_f32_16x16x32_bf16 v[16:19], v[170:173], v[202:205], v[16:19]
	s_add_u32 s50, s48, s22
	s_addc_u32 s51, s49, s23
	s_add_u32 m0, s62, 0x8000
	global_load_lds_dwordx4 v179, s[50:51]
	v_mfma_f32_16x16x32_bf16 v[12:15], v[170:173], v[206:209], v[12:15]
	v_mfma_f32_16x16x32_bf16 v[8:11], v[170:173], v[210:213], v[8:11]
	s_add_u32 s50, s48, s36
	s_addc_u32 s51, s49, s37
	s_add_u32 m0, s62, 0xa000
	global_load_lds_dwordx4 v179, s[50:51]
	v_mfma_f32_16x16x32_bf16 v[4:7], v[174:177], v[198:201], v[4:7]
	v_mfma_f32_16x16x32_bf16 v[0:3], v[174:177], v[202:205], v[0:3]
	s_add_u32 s50, s48, s40
	s_addc_u32 s51, s49, s41
	s_add_u32 m0, s62, 0xc000
	global_load_lds_dwordx4 v179, s[50:51]
	v_mfma_f32_16x16x32_bf16 v[48:51], v[174:177], v[206:209], v[48:51]
	v_mfma_f32_16x16x32_bf16 v[40:43], v[174:177], v[210:213], v[40:43]
	s_add_u32 s50, s48, s42
	s_addc_u32 s51, s49, s43
	s_add_u32 m0, s62, 0xe000
	global_load_lds_dwordx4 v179, s[50:51]
.Lg2_entry:
	ds_read_b128 v[162:165], v180 offset:8192
	ds_read_b128 v[166:169], v180 offset:10240
	ds_read_b128 v[170:173], v180 offset:12288
	ds_read_b128 v[174:177], v180 offset:14336
	s_waitcnt lgkmcnt(4)
	v_mfma_f32_16x16x32_bf16 v[124:127], v[146:149], v[182:185], v[124:127]
	v_mfma_f32_16x16x32_bf16 v[120:123], v[146:149], v[186:189], v[120:123]
	v_mfma_f32_16x16x32_bf16 v[116:119], v[146:149], v[190:193], v[116:119]
	v_mfma_f32_16x16x32_bf16 v[112:115], v[146:149], v[194:197], v[112:115]
	v_mfma_f32_16x16x32_bf16 v[108:111], v[150:153], v[182:185], v[108:111]
	v_mfma_f32_16x16x32_bf16 v[104:107], v[150:153], v[186:189], v[104:107]
	v_mfma_f32_16x16x32_bf16 v[100:103], v[150:153], v[190:193], v[100:103]
	v_mfma_f32_16x16x32_bf16 v[96:99], v[150:153], v[194:197], v[96:99]
	v_mfma_f32_16x16x32_bf16 v[92:95], v[154:157], v[182:185], v[92:95]
	v_mfma_f32_16x16x32_bf16 v[88:91], v[154:157], v[186:189], v[88:91]
	v_mfma_f32_16x16x32_bf16 v[84:87], v[154:157], v[190:193], v[84:87]
	v_mfma_f32_16x16x32_bf16 v[80:83], v[154:157], v[194:197], v[80:83]
	v_mfma_f32_16x16x32_bf16 v[76:79], v[158:161], v[182:185], v[76:79]
	v_mfma_f32_16x16x32_bf16 v[72:75], v[158:161], v[186:189], v[72:75]
	v_mfma_f32_16x16x32_bf16 v[68:71], v[158:161], v[190:193], v[68:71]
	v_mfma_f32_16x16x32_bf16 v[64:67], v[158:161], v[194:197], v[64:67]
	ds_read_b128 v[146:149], v214
	ds_read_b128 v[150:153], v214 offset:2048
	ds_read_b128 v[154:157], v214 offset:4096
	ds_read_b128 v[158:161], v214 offset:6144
	ds_read_b128 v[198:201], v216 offset:32768
	ds_read_b128 v[202:205], v216 offset:34816
	ds_read_b128 v[206:209], v216 offset:36864
	ds_read_b128 v[210:213], v216 offset:38912
	s_waitcnt lgkmcnt(8)
	v_mfma_f32_16x16x32_bf16 v[60:63], v[162:165], v[182:185], v[60:63]
	v_mfma_f32_16x16x32_bf16 v[56:59], v[162:165], v[186:189], v[56:59]
	v_mfma_f32_16x16x32_bf16 v[52:55], v[162:165], v[190:193], v[52:55]
	v_mfma_f32_16x16x32_bf16 v[44:47], v[162:165], v[194:197], v[44:47]
	v_mfma_f32_16x16x32_bf16 v[36:39], v[166:169], v[182:185], v[36:39]
	v_mfma_f32_16x16x32_bf16 v[32:35], v[166:169], v[186:189], v[32:35]
	v_mfma_f32_16x16x32_bf16 v[28:31], v[166:169], v[190:193], v[28:31]
	v_mfma_f32_16x16x32_bf16 v[24:27], v[166:169], v[194:197], v[24:27]
	v_mfma_f32_16x16x32_bf16 v[20:23], v[170:173], v[182:185], v[20:23]
	v_mfma_f32_16x16x32_bf16 v[16:19], v[170:173], v[186:189], v[16:19]
	v_mfma_f32_16x16x32_bf16 v[12:15], v[170:173], v[190:193], v[12:15]
	v_mfma_f32_16x16x32_bf16 v[8:11], v[170:173], v[194:197], v[8:11]
	v_mfma_f32_16x16x32_bf16 v[4:7], v[174:177], v[182:185], v[4:7]
	v_mfma_f32_16x16x32_bf16 v[0:3], v[174:177], v[186:189], v[0:3]
	v_mfma_f32_16x16x32_bf16 v[48:51], v[174:177], v[190:193], v[48:51]
	v_mfma_f32_16x16x32_bf16 v[40:43], v[174:177], v[194:197], v[40:43]
	ds_read_b128 v[162:165], v214 offset:8192
	ds_read_b128 v[166:169], v214 offset:10240
	ds_read_b128 v[170:173], v214 offset:12288
	ds_read_b128 v[174:177], v214 offset:14336
	s_waitcnt lgkmcnt(4)
	v_mfma_f32_16x16x32_bf16 v[124:127], v[146:149], v[198:201], v[124:127]
	v_mfma_f32_16x16x32_bf16 v[120:123], v[146:149], v[202:205], v[120:123]
	v_mfma_f32_16x16x32_bf16 v[116:119], v[146:149], v[206:209], v[116:119]
	v_mfma_f32_16x16x32_bf16 v[112:115], v[146:149], v[210:213], v[112:115]
	v_mfma_f32_16x16x32_bf16 v[108:111], v[150:153], v[198:201], v[108:111]
	v_mfma_f32_16x16x32_bf16 v[104:107], v[150:153], v[202:205], v[104:107]
	v_mfma_f32_16x16x32_bf16 v[100:103], v[150:153], v[206:209], v[100:103]
	v_mfma_f32_16x16x32_bf16 v[96:99], v[150:153], v[210:213], v[96:99]
	v_mfma_f32_16x16x32_bf16 v[92:95], v[154:157], v[198:201], v[92:95]
	v_mfma_f32_16x16x32_bf16 v[88:91], v[154:157], v[202:205], v[88:91]
	v_mfma_f32_16x16x32_bf16 v[84:87], v[154:157], v[206:209], v[84:87]
	v_mfma_f32_16x16x32_bf16 v[80:83], v[154:157], v[210:213], v[80:83]
	v_mfma_f32_16x16x32_bf16 v[76:79], v[158:161], v[198:201], v[76:79]
	v_mfma_f32_16x16x32_bf16 v[72:75], v[158:161], v[202:205], v[72:75]
	v_mfma_f32_16x16x32_bf16 v[68:71], v[158:161], v[206:209], v[68:71]
	v_mfma_f32_16x16x32_bf16 v[64:67], v[158:161], v[210:213], v[64:67]
	s_add_u32 s48, s48, 0x80
	s_addc_u32 s49, s49, 0
	s_add_i32 s47, s47, 1
	s_cmp_lt_u32 s47, 15
	s_cbranch_scc1 .Lg2_top
	s_waitcnt lgkmcnt(0)
	s_waitcnt vmcnt(0)
	s_barrier
	v_xor_b32_e32 v180, 0x10000, v180
	v_xor_b32_e32 v215, 0x10000, v215
	v_xor_b32_e32 v214, 0x10000, v214
	v_xor_b32_e32 v216, 0x10000, v216
	s_xor_b32 s62, s62, 0x10000
	ds_read_b128 v[146:149], v180
	ds_read_b128 v[150:153], v180 offset:2048
	ds_read_b128 v[154:157], v180 offset:4096
	ds_read_b128 v[158:161], v180 offset:6144
	ds_read_b128 v[182:185], v215 offset:32768
	ds_read_b128 v[186:189], v215 offset:34816
	ds_read_b128 v[190:193], v215 offset:36864
	ds_read_b128 v[194:197], v215 offset:38912
	v_mfma_f32_16x16x32_bf16 v[60:63], v[162:165], v[198:201], v[60:63]
	v_mfma_f32_16x16x32_bf16 v[56:59], v[162:165], v[202:205], v[56:59]
	v_mfma_f32_16x16x32_bf16 v[52:55], v[162:165], v[206:209], v[52:55]
	v_mfma_f32_16x16x32_bf16 v[44:47], v[162:165], v[210:213], v[44:47]
	v_mfma_f32_16x16x32_bf16 v[36:39], v[166:169], v[198:201], v[36:39]
	v_mfma_f32_16x16x32_bf16 v[32:35], v[166:169], v[202:205], v[32:35]
	v_mfma_f32_16x16x32_bf16 v[28:31], v[166:169], v[206:209], v[28:31]
	v_mfma_f32_16x16x32_bf16 v[24:27], v[166:169], v[210:213], v[24:27]
	v_mfma_f32_16x16x32_bf16 v[20:23], v[170:173], v[198:201], v[20:23]
	v_mfma_f32_16x16x32_bf16 v[16:19], v[170:173], v[202:205], v[16:19]
	v_mfma_f32_16x16x32_bf16 v[12:15], v[170:173], v[206:209], v[12:15]
	v_mfma_f32_16x16x32_bf16 v[8:11], v[170:173], v[210:213], v[8:11]
	v_mfma_f32_16x16x32_bf16 v[4:7], v[174:177], v[198:201], v[4:7]
	v_mfma_f32_16x16x32_bf16 v[0:3], v[174:177], v[202:205], v[0:3]
	v_mfma_f32_16x16x32_bf16 v[48:51], v[174:177], v[206:209], v[48:51]
	v_mfma_f32_16x16x32_bf16 v[40:43], v[174:177], v[210:213], v[40:43]
	ds_read_b128 v[162:165], v180 offset:8192
	ds_read_b128 v[166:169], v180 offset:10240
	ds_read_b128 v[170:173], v180 offset:12288
	ds_read_b128 v[174:177], v180 offset:14336
	s_waitcnt lgkmcnt(4)
	v_mfma_f32_16x16x32_bf16 v[124:127], v[146:149], v[182:185], v[124:127]
	v_mfma_f32_16x16x32_bf16 v[120:123], v[146:149], v[186:189], v[120:123]
	v_mfma_f32_16x16x32_bf16 v[116:119], v[146:149], v[190:193], v[116:119]
	v_mfma_f32_16x16x32_bf16 v[112:115], v[146:149], v[194:197], v[112:115]
	v_mfma_f32_16x16x32_bf16 v[108:111], v[150:153], v[182:185], v[108:111]
	v_mfma_f32_16x16x32_bf16 v[104:107], v[150:153], v[186:189], v[104:107]
	v_mfma_f32_16x16x32_bf16 v[100:103], v[150:153], v[190:193], v[100:103]
	v_mfma_f32_16x16x32_bf16 v[96:99], v[150:153], v[194:197], v[96:99]
	v_mfma_f32_16x16x32_bf16 v[92:95], v[154:157], v[182:185], v[92:95]
	v_mfma_f32_16x16x32_bf16 v[88:91], v[154:157], v[186:189], v[88:91]
	v_mfma_f32_16x16x32_bf16 v[84:87], v[154:157], v[190:193], v[84:87]
	v_mfma_f32_16x16x32_bf16 v[80:83], v[154:157], v[194:197], v[80:83]
	v_mfma_f32_16x16x32_bf16 v[76:79], v[158:161], v[182:185], v[76:79]
	v_mfma_f32_16x16x32_bf16 v[72:75], v[158:161], v[186:189], v[72:75]
	v_mfma_f32_16x16x32_bf16 v[68:71], v[158:161], v[190:193], v[68:71]
	v_mfma_f32_16x16x32_bf16 v[64:67], v[158:161], v[194:197], v[64:67]
	ds_read_b128 v[146:149], v214
	ds_read_b128 v[150:153], v214 offset:2048
	ds_read_b128 v[154:157], v214 offset:4096
	ds_read_b128 v[158:161], v214 offset:6144
	ds_read_b128 v[198:201], v216 offset:32768
	ds_read_b128 v[202:205], v216 offset:34816
	ds_read_b128 v[206:209], v216 offset:36864
	ds_read_b128 v[210:213], v216 offset:38912
	s_waitcnt lgkmcnt(8)
	v_mfma_f32_16x16x32_bf16 v[60:63], v[162:165], v[182:185], v[60:63]
	v_mfma_f32_16x16x32_bf16 v[56:59], v[162:165], v[186:189], v[56:59]
	v_mfma_f32_16x16x32_bf16 v[52:55], v[162:165], v[190:193], v[52:55]
	v_mfma_f32_16x16x32_bf16 v[44:47], v[162:165], v[194:197], v[44:47]
	v_mfma_f32_16x16x32_bf16 v[36:39], v[166:169], v[182:185], v[36:39]
	v_mfma_f32_16x16x32_bf16 v[32:35], v[166:169], v[186:189], v[32:35]
	v_mfma_f32_16x16x32_bf16 v[28:31], v[166:169], v[190:193], v[28:31]
	v_mfma_f32_16x16x32_bf16 v[24:27], v[166:169], v[194:197], v[24:27]
	v_mfma_f32_16x16x32_bf16 v[20:23], v[170:173], v[182:185], v[20:23]
	v_mfma_f32_16x16x32_bf16 v[16:19], v[170:173], v[186:189], v[16:19]
	v_mfma_f32_16x16x32_bf16 v[12:15], v[170:173], v[190:193], v[12:15]
	v_mfma_f32_16x16x32_bf16 v[8:11], v[170:173], v[194:197], v[8:11]
	v_mfma_f32_16x16x32_bf16 v[4:7], v[174:177], v[182:185], v[4:7]
	v_mfma_f32_16x16x32_bf16 v[0:3], v[174:177], v[186:189], v[0:3]
	v_mfma_f32_16x16x32_bf16 v[48:51], v[174:177], v[190:193], v[48:51]
	v_mfma_f32_16x16x32_bf16 v[40:43], v[174:177], v[194:197], v[40:43]
	ds_read_b128 v[162:165], v214 offset:8192
	ds_read_b128 v[166:169], v214 offset:10240
	ds_read_b128 v[170:173], v214 offset:12288
	ds_read_b128 v[174:177], v214 offset:14336
	s_waitcnt lgkmcnt(4)
	v_mfma_f32_16x16x32_bf16 v[124:127], v[146:149], v[198:201], v[124:127]
	v_mfma_f32_16x16x32_bf16 v[120:123], v[146:149], v[202:205], v[120:123]
	v_mfma_f32_16x16x32_bf16 v[116:119], v[146:149], v[206:209], v[116:119]
	v_mfma_f32_16x16x32_bf16 v[112:115], v[146:149], v[210:213], v[112:115]
	v_mfma_f32_16x16x32_bf16 v[108:111], v[150:153], v[198:201], v[108:111]
	v_mfma_f32_16x16x32_bf16 v[104:107], v[150:153], v[202:205], v[104:107]
	v_mfma_f32_16x16x32_bf16 v[100:103], v[150:153], v[206:209], v[100:103]
	v_mfma_f32_16x16x32_bf16 v[96:99], v[150:153], v[210:213], v[96:99]
	v_mfma_f32_16x16x32_bf16 v[92:95], v[154:157], v[198:201], v[92:95]
	v_mfma_f32_16x16x32_bf16 v[88:91], v[154:157], v[202:205], v[88:91]
	v_mfma_f32_16x16x32_bf16 v[84:87], v[154:157], v[206:209], v[84:87]
	v_mfma_f32_16x16x32_bf16 v[80:83], v[154:157], v[210:213], v[80:83]
	v_mfma_f32_16x16x32_bf16 v[76:79], v[158:161], v[198:201], v[76:79]
	v_mfma_f32_16x16x32_bf16 v[72:75], v[158:161], v[202:205], v[72:75]
	v_mfma_f32_16x16x32_bf16 v[68:71], v[158:161], v[206:209], v[68:71]
	v_mfma_f32_16x16x32_bf16 v[64:67], v[158:161], v[210:213], v[64:67]
	s_add_u32 s48, s48, 0x80
	s_addc_u32 s49, s49, 0
	s_add_i32 s47, s47, 1
	s_waitcnt lgkmcnt(0)
	s_waitcnt vmcnt(0)
	s_barrier
	v_mfma_f32_16x16x32_bf16 v[60:63], v[162:165], v[198:201], v[60:63]
	v_mfma_f32_16x16x32_bf16 v[56:59], v[162:165], v[202:205], v[56:59]
	v_mfma_f32_16x16x32_bf16 v[52:55], v[162:165], v[206:209], v[52:55]
	v_mfma_f32_16x16x32_bf16 v[44:47], v[162:165], v[210:213], v[44:47]
	v_mfma_f32_16x16x32_bf16 v[36:39], v[166:169], v[198:201], v[36:39]
	v_mfma_f32_16x16x32_bf16 v[32:35], v[166:169], v[202:205], v[32:35]
	v_mfma_f32_16x16x32_bf16 v[28:31], v[166:169], v[206:209], v[28:31]
	v_mfma_f32_16x16x32_bf16 v[24:27], v[166:169], v[210:213], v[24:27]
	v_mfma_f32_16x16x32_bf16 v[20:23], v[170:173], v[198:201], v[20:23]
	v_mfma_f32_16x16x32_bf16 v[16:19], v[170:173], v[202:205], v[16:19]
	v_mfma_f32_16x16x32_bf16 v[12:15], v[170:173], v[206:209], v[12:15]
	v_mfma_f32_16x16x32_bf16 v[8:11], v[170:173], v[210:213], v[8:11]
	v_mfma_f32_16x16x32_bf16 v[4:7], v[174:177], v[198:201], v[4:7]
	v_mfma_f32_16x16x32_bf16 v[0:3], v[174:177], v[202:205], v[0:3]
	v_mfma_f32_16x16x32_bf16 v[48:51], v[174:177], v[206:209], v[48:51]
	v_mfma_f32_16x16x32_bf16 v[40:43], v[174:177], v[210:213], v[40:43]
	s_nop 7
	s_nop 7
	s_sub_u32 s48, s48, s34
	s_subb_u32 s49, s49, s35
	s_mov_b32 s62, 0x80000
	s_mov_b32 s63, 0x80000
	s_mov_b64 s[50:51], 0
	s_mov_b64 vcc, exec
	s_branch .LBB0_458

.LBB0_660:
	s_ashr_i32 s96, s94, 3
	s_and_b32 s21, s94, 7
	s_and_b32 s70, s96, -8
	s_or_b32 s64, s70, s21
	s_lshl_b32 s20, s91, 11
	s_ashr_i32 s65, s64, 31
	v_mov_b32_e32 v6, v181
	s_and_b32 s97, s93, 7
	s_bfe_u32 s6, s91, 0x30008
	s_and_b32 s20, s20, 0x380000
	s_lshl_b64 s[66:67], s[64:65], 19
	s_add_u32 s66, s3, s66
	v_lshrrev_b32_e32 v7, 4, v6
	v_lshlrev_b32_e32 v1, 6, v6
	v_xor_b32_e32 v0, v7, v6
	v_and_b32_e32 v8, 0x3c0, v1
	v_lshlrev_b32_e32 v1, 7, v6
	s_addc_u32 s67, s72, s67
	s_lshl_b32 s21, s94, 5
	v_lshlrev_b32_e32 v0, 3, v0
	v_and_b32_e32 v1, 0xfffffc00, v1
	s_and_b32 s95, s21, 0x700
	v_and_or_b32 v0, v0, 56, v1
	s_lshl_b32 s21, s95, 11
	v_ashrrev_i32_e32 v1, 31, v0
	v_lshl_add_u32 v142, v6, 4, 0
	s_add_u32 s68, s73, s21
	v_lshlrev_b64 v[0:1], 1, v[0:1]
	v_readfirstlane_b32 s21, v142
	v_add_u32_e32 v9, 0x2000, v142
	v_lshl_add_u64 v[2:3], s[66:67], 0, v[0:1]
	s_mov_b32 m0, s21
	v_readfirstlane_b32 s21, v9
	v_add_u32_e32 v9, 0x4000, v142
	s_waitcnt vmcnt(63) expcnt(7) lgkmcnt(15)
	s_barrier
	global_load_lds_dwordx4 v[2:3], off
	v_lshl_add_u64 v[4:5], v[2:3], 0, s[8:9]
	s_mov_b32 m0, s21
	v_readfirstlane_b32 s21, v9
	global_load_lds_dwordx4 v[4:5], off
	v_lshl_add_u64 v[4:5], v[2:3], 0, s[10:11]
	s_mov_b32 m0, s21
	s_addc_u32 s69, s74, 0
	global_load_lds_dwordx4 v[4:5], off
	v_add_u32_e32 v4, 0x6000, v142
	v_lshl_add_u64 v[2:3], v[2:3], 0, s[12:13]
	v_readfirstlane_b32 s21, v4
	v_add_u32_e32 v4, 0x8000, v142
	s_mov_b32 m0, s21
	v_readfirstlane_b32 s21, v4
	v_add_u32_e32 v9, 0xa000, v142
	global_load_lds_dwordx4 v[2:3], off
	v_lshl_add_u64 v[2:3], s[68:69], 0, v[0:1]
	s_mov_b32 m0, s21
	v_readfirstlane_b32 s21, v9
	v_add_u32_e32 v9, 0xc000, v142
	global_load_lds_dwordx4 v[2:3], off
	v_lshl_add_u64 v[4:5], v[2:3], 0, s[8:9]
	s_mov_b32 m0, s21
	v_readfirstlane_b32 s21, v9
	global_load_lds_dwordx4 v[4:5], off
	v_lshl_add_u64 v[4:5], v[2:3], 0, s[10:11]
	s_mov_b32 m0, s21
	v_lshl_add_u64 v[2:3], v[2:3], 0, s[12:13]
	global_load_lds_dwordx4 v[4:5], off
	v_add_u32_e32 v4, 0xe000, v142
	s_or_b32 s66, s70, s97
	v_readfirstlane_b32 s21, v4
	s_mov_b32 m0, s21
	v_ashrrev_i32_e32 v4, 6, v6
	global_load_lds_dwordx4 v[2:3], off
	v_lshrrev_b32_e32 v5, 30, v4
	s_ashr_i32 s67, s66, 31
	v_add_u32_e32 v5, v4, v5
	s_lshl_b64 s[68:69], s[66:67], 19
	v_bfe_u32 v2, v6, 4, 2
	v_bfe_u32 v3, v6, 1, 3
	v_and_b32_e32 v6, 0x7fffc, v5
	s_add_u32 s68, s34, s68
	v_sub_u32_e32 v4, v4, v6
	s_addc_u32 s69, s35, s69
	v_lshlrev_b32_e32 v144, 13, v4
	v_bitop3_b32 v4, v7, v3, 3 bitop3:0x6c
	v_bitop3_b32 v2, v2, v3, 4 bitop3:0x36
	v_lshl_add_u64 v[138:139], s[68:69], 0, v[0:1]
	s_add_u32 s68, s34, s20
	v_lshlrev_b32_e32 v5, 12, v5
	v_lshlrev_b32_e32 v4, 3, v4
	v_lshlrev_b32_e32 v2, 3, v2
	s_addc_u32 s69, s35, 0
	v_and_b32_e32 v143, 0xffffc000, v5
	v_lshl_add_u64 v[140:141], s[68:69], 0, v[0:1]
	s_mov_b64 s[68:69], 0
	v_lshlrev_b32_e32 v145, 1, v8
	v_lshlrev_b32_e32 v174, 1, v4
	v_lshlrev_b32_e32 v175, 1, v2
	s_mov_b32 vcc_lo, 0
	s_mov_b32 s86, 0
	v_mov_b32_e32 v4, 0
	v_mov_b32_e32 v5, v131
	v_mov_b32_e32 v6, v131
	v_mov_b32_e32 v7, v131
	v_mov_b32_e32 v12, 0
	v_mov_b32_e32 v13, v131
	v_mov_b32_e32 v14, v131
	v_mov_b32_e32 v15, v131
	v_mov_b32_e32 v0, 0
	v_mov_b32_e32 v1, v131
	v_mov_b32_e32 v2, v131
	v_mov_b32_e32 v3, v131
	v_mov_b32_e32 v8, 0
	v_mov_b32_e32 v9, v131
	v_mov_b32_e32 v10, v131
	v_mov_b32_e32 v11, v131
	v_mov_b32_e32 v16, 0
	v_mov_b32_e32 v17, v131
	v_mov_b32_e32 v18, v131
	v_mov_b32_e32 v19, v131
	v_mov_b32_e32 v20, 0
	v_mov_b32_e32 v21, v131
	v_mov_b32_e32 v22, v131
	v_mov_b32_e32 v23, v131
	v_mov_b32_e32 v24, 0
	v_mov_b32_e32 v25, v131
	v_mov_b32_e32 v26, v131
	v_mov_b32_e32 v27, v131
	v_mov_b32_e32 v28, 0
	v_mov_b32_e32 v29, v131
	v_mov_b32_e32 v30, v131
	v_mov_b32_e32 v31, v131
	v_mov_b32_e32 v32, 0
	v_mov_b32_e32 v33, v131
	v_mov_b32_e32 v34, v131
	v_mov_b32_e32 v35, v131
	v_mov_b32_e32 v36, 0
	v_mov_b32_e32 v37, v131
	v_mov_b32_e32 v38, v131
	v_mov_b32_e32 v39, v131
	v_mov_b32_e32 v40, 0
	v_mov_b32_e32 v41, v131
	v_mov_b32_e32 v42, v131
	v_mov_b32_e32 v43, v131
	v_mov_b32_e32 v44, 0
	v_mov_b32_e32 v45, v131
	v_mov_b32_e32 v46, v131
	v_mov_b32_e32 v47, v131
	v_mov_b32_e32 v48, 0
	v_mov_b32_e32 v49, v131
	v_mov_b32_e32 v50, v131
	v_mov_b32_e32 v51, v131
	v_mov_b32_e32 v52, 0
	v_mov_b32_e32 v53, v131
	v_mov_b32_e32 v54, v131
	v_mov_b32_e32 v55, v131
	v_mov_b32_e32 v56, 0
	v_mov_b32_e32 v57, v131
	v_mov_b32_e32 v58, v131
	v_mov_b32_e32 v59, v131
	v_mov_b32_e32 v60, 0
	v_mov_b32_e32 v61, v131
	v_mov_b32_e32 v62, v131
	v_mov_b32_e32 v63, v131
	v_mov_b32_e32 v64, 0
	v_mov_b32_e32 v65, v131
	v_mov_b32_e32 v66, v131
	v_mov_b32_e32 v67, v131
	v_mov_b32_e32 v68, 0
	v_mov_b32_e32 v69, v131
	v_mov_b32_e32 v70, v131
	v_mov_b32_e32 v71, v131
	v_mov_b32_e32 v72, 0
	v_mov_b32_e32 v73, v131
	v_mov_b32_e32 v74, v131
	v_mov_b32_e32 v75, v131
	v_mov_b32_e32 v76, 0
	v_mov_b32_e32 v77, v131
	v_mov_b32_e32 v78, v131
	v_mov_b32_e32 v79, v131
	v_mov_b32_e32 v80, 0
	v_mov_b32_e32 v81, v131
	v_mov_b32_e32 v82, v131
	v_mov_b32_e32 v83, v131
	v_mov_b32_e32 v84, 0
	v_mov_b32_e32 v85, v131
	v_mov_b32_e32 v86, v131
	v_mov_b32_e32 v87, v131
	v_mov_b32_e32 v88, 0
	v_mov_b32_e32 v89, v131
	v_mov_b32_e32 v90, v131
	v_mov_b32_e32 v91, v131
	v_mov_b32_e32 v92, 0
	v_mov_b32_e32 v93, v131
	v_mov_b32_e32 v94, v131
	v_mov_b32_e32 v95, v131
	v_mov_b32_e32 v96, 0
	v_mov_b32_e32 v97, v131
	v_mov_b32_e32 v98, v131
	v_mov_b32_e32 v99, v131
	v_mov_b32_e32 v100, 0
	v_mov_b32_e32 v101, v131
	v_mov_b32_e32 v102, v131
	v_mov_b32_e32 v103, v131
	v_mov_b32_e32 v104, 0
	v_mov_b32_e32 v105, v131
	v_mov_b32_e32 v106, v131
	v_mov_b32_e32 v107, v131
	v_mov_b32_e32 v108, 0
	v_mov_b32_e32 v109, v131
	v_mov_b32_e32 v110, v131
	v_mov_b32_e32 v111, v131
	v_mov_b32_e32 v112, 0
	v_mov_b32_e32 v113, v131
	v_mov_b32_e32 v114, v131
	v_mov_b32_e32 v115, v131
	v_mov_b32_e32 v116, 0
	v_mov_b32_e32 v117, v131
	v_mov_b32_e32 v118, v131
	v_mov_b32_e32 v119, v131
	v_mov_b32_e32 v120, 0
	v_mov_b32_e32 v121, v131
	v_mov_b32_e32 v122, v131
	v_mov_b32_e32 v123, v131
	v_mov_b32_e32 v124, 0
	v_mov_b32_e32 v125, v131
	v_mov_b32_e32 v126, v131
	v_mov_b32_e32 v127, v131
	s_waitcnt vmcnt(0) lgkmcnt(0)
	s_barrier
	v_add3_u32 v180, v143, v145, v174
	v_add3_u32 v245, v144, v145, v174
	v_add3_u32 v244, v143, v145, v175
	v_add3_u32 v246, v144, v145, v175
	v_readfirstlane_b32 s87, v142
	ds_read_b128 v[176:179], v180
	ds_read_b128 v[182:185], v180 offset:2048
	ds_read_b128 v[186:189], v180 offset:4096
	ds_read_b128 v[190:193], v180 offset:6144
	ds_read_b128 v[210:213], v245 offset:32768
	ds_read_b128 v[214:217], v245 offset:34816
	ds_read_b128 v[218:221], v245 offset:36864
	ds_read_b128 v[222:225], v245 offset:38912
	s_mov_b32 s86, 0
	s_mov_b64 s[68:69], s[34:35]
	v_subrev_u32_e32 v242, s34, v138
	v_subrev_u32_e32 v243, s34, v140
	s_add_u32 s87, s87, 0x10000
	s_add_u32 s70, s68, 0x4000080
	s_addc_u32 s71, s69, 0
	s_mov_b32 m0, s87
	global_load_lds_dwordx4 v242, s[70:71]
	s_add_u32 s70, s68, 0x4020080
	s_addc_u32 s71, s69, 0
	s_add_u32 m0, s87, 0x2000
	global_load_lds_dwordx4 v242, s[70:71]
	s_add_u32 s70, s68, 0x4040080
	s_addc_u32 s71, s69, 0
	s_add_u32 m0, s87, 0x4000
	global_load_lds_dwordx4 v242, s[70:71]
	s_add_u32 s70, s68, s14
	s_addc_u32 s71, s69, s15
	s_add_u32 m0, s87, 0x6000
	global_load_lds_dwordx4 v242, s[70:71]
	s_add_u32 s70, s68, s16
	s_addc_u32 s71, s69, s17
	s_add_u32 m0, s87, 0x8000
	global_load_lds_dwordx4 v243, s[70:71]
	s_add_u32 s70, s68, s18
	s_addc_u32 s71, s69, s19
	s_add_u32 m0, s87, 0xa000
	global_load_lds_dwordx4 v243, s[70:71]
	s_add_u32 s70, s68, s22
	s_addc_u32 s71, s69, s23
	s_add_u32 m0, s87, 0xc000
	global_load_lds_dwordx4 v243, s[70:71]
	s_add_u32 s70, s68, s36
	s_addc_u32 s71, s69, s37
	s_add_u32 m0, s87, 0xe000
	global_load_lds_dwordx4 v243, s[70:71]
	s_branch .Lg5_entry
.Lg5_top:
	s_waitcnt lgkmcnt(0)
	s_waitcnt vmcnt(0)
	s_barrier
	v_xor_b32_e32 v180, 0x10000, v180
	v_xor_b32_e32 v245, 0x10000, v245
	v_xor_b32_e32 v244, 0x10000, v244
	v_xor_b32_e32 v246, 0x10000, v246
	s_xor_b32 s87, s87, 0x10000
	ds_read_b128 v[176:179], v180
	ds_read_b128 v[182:185], v180 offset:2048
	ds_read_b128 v[186:189], v180 offset:4096
	ds_read_b128 v[190:193], v180 offset:6144
	ds_read_b128 v[210:213], v245 offset:32768
	ds_read_b128 v[214:217], v245 offset:34816
	ds_read_b128 v[218:221], v245 offset:36864
	ds_read_b128 v[222:225], v245 offset:38912
	v_mfma_f32_16x16x32_bf16 v[60:63], v[194:197], v[226:229], v[60:63]
	v_mfma_f32_16x16x32_bf16 v[56:59], v[194:197], v[230:233], v[56:59]
	s_add_u32 s70, s68, 0x4000080
	s_addc_u32 s71, s69, 0
	s_mov_b32 m0, s87
	global_load_lds_dwordx4 v242, s[70:71]
	v_mfma_f32_16x16x32_bf16 v[52:55], v[194:197], v[234:237], v[52:55]
	v_mfma_f32_16x16x32_bf16 v[48:51], v[194:197], v[238:241], v[48:51]
	s_add_u32 s70, s68, 0x4020080
	s_addc_u32 s71, s69, 0
	s_add_u32 m0, s87, 0x2000
	global_load_lds_dwordx4 v242, s[70:71]
	v_mfma_f32_16x16x32_bf16 v[44:47], v[198:201], v[226:229], v[44:47]
	v_mfma_f32_16x16x32_bf16 v[40:43], v[198:201], v[230:233], v[40:43]
	s_add_u32 s70, s68, 0x4040080
	s_addc_u32 s71, s69, 0
	s_add_u32 m0, s87, 0x4000
	global_load_lds_dwordx4 v242, s[70:71]
	v_mfma_f32_16x16x32_bf16 v[36:39], v[198:201], v[234:237], v[36:39]
	v_mfma_f32_16x16x32_bf16 v[32:35], v[198:201], v[238:241], v[32:35]
	s_add_u32 s70, s68, s14
	s_addc_u32 s71, s69, s15
	s_add_u32 m0, s87, 0x6000
	global_load_lds_dwordx4 v242, s[70:71]
	v_mfma_f32_16x16x32_bf16 v[28:31], v[202:205], v[226:229], v[28:31]
	v_mfma_f32_16x16x32_bf16 v[24:27], v[202:205], v[230:233], v[24:27]
	s_add_u32 s70, s68, s16
	s_addc_u32 s71, s69, s17
	s_add_u32 m0, s87, 0x8000
	global_load_lds_dwordx4 v243, s[70:71]
	v_mfma_f32_16x16x32_bf16 v[20:23], v[202:205], v[234:237], v[20:23]
	v_mfma_f32_16x16x32_bf16 v[16:19], v[202:205], v[238:241], v[16:19]
	s_add_u32 s70, s68, s18
	s_addc_u32 s71, s69, s19
	s_add_u32 m0, s87, 0xa000
	global_load_lds_dwordx4 v243, s[70:71]
	v_mfma_f32_16x16x32_bf16 v[8:11], v[206:209], v[226:229], v[8:11]
	v_mfma_f32_16x16x32_bf16 v[0:3], v[206:209], v[230:233], v[0:3]
	s_add_u32 s70, s68, s22
	s_addc_u32 s71, s69, s23
	s_add_u32 m0, s87, 0xc000
	global_load_lds_dwordx4 v243, s[70:71]
	v_mfma_f32_16x16x32_bf16 v[12:15], v[206:209], v[234:237], v[12:15]
	v_mfma_f32_16x16x32_bf16 v[4:7], v[206:209], v[238:241], v[4:7]
	s_add_u32 s70, s68, s36
	s_addc_u32 s71, s69, s37
	s_add_u32 m0, s87, 0xe000
	global_load_lds_dwordx4 v243, s[70:71]
.Lg5_entry:
	ds_read_b128 v[194:197], v180 offset:8192
	ds_read_b128 v[198:201], v180 offset:10240
	ds_read_b128 v[202:205], v180 offset:12288
	ds_read_b128 v[206:209], v180 offset:14336
	s_waitcnt lgkmcnt(4)
	v_mfma_f32_16x16x32_bf16 v[124:127], v[176:179], v[210:213], v[124:127]
	v_mfma_f32_16x16x32_bf16 v[120:123], v[176:179], v[214:217], v[120:123]
	v_mfma_f32_16x16x32_bf16 v[116:119], v[176:179], v[218:221], v[116:119]
	v_mfma_f32_16x16x32_bf16 v[112:115], v[176:179], v[222:225], v[112:115]
	v_mfma_f32_16x16x32_bf16 v[108:111], v[182:185], v[210:213], v[108:111]
	v_mfma_f32_16x16x32_bf16 v[104:107], v[182:185], v[214:217], v[104:107]
	v_mfma_f32_16x16x32_bf16 v[100:103], v[182:185], v[218:221], v[100:103]
	v_mfma_f32_16x16x32_bf16 v[96:99], v[182:185], v[222:225], v[96:99]
	v_mfma_f32_16x16x32_bf16 v[92:95], v[186:189], v[210:213], v[92:95]
	v_mfma_f32_16x16x32_bf16 v[88:91], v[186:189], v[214:217], v[88:91]
	v_mfma_f32_16x16x32_bf16 v[84:87], v[186:189], v[218:221], v[84:87]
	v_mfma_f32_16x16x32_bf16 v[80:83], v[186:189], v[222:225], v[80:83]
	v_mfma_f32_16x16x32_bf16 v[76:79], v[190:193], v[210:213], v[76:79]
	v_mfma_f32_16x16x32_bf16 v[72:75], v[190:193], v[214:217], v[72:75]
	v_mfma_f32_16x16x32_bf16 v[68:71], v[190:193], v[218:221], v[68:71]
	v_mfma_f32_16x16x32_bf16 v[64:67], v[190:193], v[222:225], v[64:67]
	ds_read_b128 v[176:179], v244
	ds_read_b128 v[182:185], v244 offset:2048
	ds_read_b128 v[186:189], v244 offset:4096
	ds_read_b128 v[190:193], v244 offset:6144
	ds_read_b128 v[226:229], v246 offset:32768
	ds_read_b128 v[230:233], v246 offset:34816
	ds_read_b128 v[234:237], v246 offset:36864
	ds_read_b128 v[238:241], v246 offset:38912
	s_waitcnt lgkmcnt(8)
	v_mfma_f32_16x16x32_bf16 v[60:63], v[194:197], v[210:213], v[60:63]
	v_mfma_f32_16x16x32_bf16 v[56:59], v[194:197], v[214:217], v[56:59]
	v_mfma_f32_16x16x32_bf16 v[52:55], v[194:197], v[218:221], v[52:55]
	v_mfma_f32_16x16x32_bf16 v[48:51], v[194:197], v[222:225], v[48:51]
	v_mfma_f32_16x16x32_bf16 v[44:47], v[198:201], v[210:213], v[44:47]
	v_mfma_f32_16x16x32_bf16 v[40:43], v[198:201], v[214:217], v[40:43]
	v_mfma_f32_16x16x32_bf16 v[36:39], v[198:201], v[218:221], v[36:39]
	v_mfma_f32_16x16x32_bf16 v[32:35], v[198:201], v[222:225], v[32:35]
	v_mfma_f32_16x16x32_bf16 v[28:31], v[202:205], v[210:213], v[28:31]
	v_mfma_f32_16x16x32_bf16 v[24:27], v[202:205], v[214:217], v[24:27]
	v_mfma_f32_16x16x32_bf16 v[20:23], v[202:205], v[218:221], v[20:23]
	v_mfma_f32_16x16x32_bf16 v[16:19], v[202:205], v[222:225], v[16:19]
	v_mfma_f32_16x16x32_bf16 v[8:11], v[206:209], v[210:213], v[8:11]
	v_mfma_f32_16x16x32_bf16 v[0:3], v[206:209], v[214:217], v[0:3]
	v_mfma_f32_16x16x32_bf16 v[12:15], v[206:209], v[218:221], v[12:15]
	v_mfma_f32_16x16x32_bf16 v[4:7], v[206:209], v[222:225], v[4:7]
	ds_read_b128 v[194:197], v244 offset:8192
	ds_read_b128 v[198:201], v244 offset:10240
	ds_read_b128 v[202:205], v244 offset:12288
	ds_read_b128 v[206:209], v244 offset:14336
	s_waitcnt lgkmcnt(4)
	v_mfma_f32_16x16x32_bf16 v[124:127], v[176:179], v[226:229], v[124:127]
	v_mfma_f32_16x16x32_bf16 v[120:123], v[176:179], v[230:233], v[120:123]
	v_mfma_f32_16x16x32_bf16 v[116:119], v[176:179], v[234:237], v[116:119]
	v_mfma_f32_16x16x32_bf16 v[112:115], v[176:179], v[238:241], v[112:115]
	v_mfma_f32_16x16x32_bf16 v[108:111], v[182:185], v[226:229], v[108:111]
	v_mfma_f32_16x16x32_bf16 v[104:107], v[182:185], v[230:233], v[104:107]
	v_mfma_f32_16x16x32_bf16 v[100:103], v[182:185], v[234:237], v[100:103]
	v_mfma_f32_16x16x32_bf16 v[96:99], v[182:185], v[238:241], v[96:99]
	v_mfma_f32_16x16x32_bf16 v[92:95], v[186:189], v[226:229], v[92:95]
	v_mfma_f32_16x16x32_bf16 v[88:91], v[186:189], v[230:233], v[88:91]
	v_mfma_f32_16x16x32_bf16 v[84:87], v[186:189], v[234:237], v[84:87]
	v_mfma_f32_16x16x32_bf16 v[80:83], v[186:189], v[238:241], v[80:83]
	v_mfma_f32_16x16x32_bf16 v[76:79], v[190:193], v[226:229], v[76:79]
	v_mfma_f32_16x16x32_bf16 v[72:75], v[190:193], v[230:233], v[72:75]
	v_mfma_f32_16x16x32_bf16 v[68:71], v[190:193], v[234:237], v[68:71]
	v_mfma_f32_16x16x32_bf16 v[64:67], v[190:193], v[238:241], v[64:67]
	s_add_u32 s68, s68, 0x80
	s_addc_u32 s69, s69, 0
	s_add_i32 s86, s86, 1
	s_cmp_lt_u32 s86, 15
	s_cbranch_scc1 .Lg5_top
	s_waitcnt lgkmcnt(0)
	s_waitcnt vmcnt(0)
	s_barrier
	v_xor_b32_e32 v180, 0x10000, v180
	v_xor_b32_e32 v245, 0x10000, v245
	v_xor_b32_e32 v244, 0x10000, v244
	v_xor_b32_e32 v246, 0x10000, v246
	s_xor_b32 s87, s87, 0x10000
	ds_read_b128 v[176:179], v180
	ds_read_b128 v[182:185], v180 offset:2048
	ds_read_b128 v[186:189], v180 offset:4096
	ds_read_b128 v[190:193], v180 offset:6144
	ds_read_b128 v[210:213], v245 offset:32768
	ds_read_b128 v[214:217], v245 offset:34816
	ds_read_b128 v[218:221], v245 offset:36864
	ds_read_b128 v[222:225], v245 offset:38912
	v_mfma_f32_16x16x32_bf16 v[60:63], v[194:197], v[226:229], v[60:63]
	v_mfma_f32_16x16x32_bf16 v[56:59], v[194:197], v[230:233], v[56:59]
	v_mfma_f32_16x16x32_bf16 v[52:55], v[194:197], v[234:237], v[52:55]
	v_mfma_f32_16x16x32_bf16 v[48:51], v[194:197], v[238:241], v[48:51]
	v_mfma_f32_16x16x32_bf16 v[44:47], v[198:201], v[226:229], v[44:47]
	v_mfma_f32_16x16x32_bf16 v[40:43], v[198:201], v[230:233], v[40:43]
	v_mfma_f32_16x16x32_bf16 v[36:39], v[198:201], v[234:237], v[36:39]
	v_mfma_f32_16x16x32_bf16 v[32:35], v[198:201], v[238:241], v[32:35]
	v_mfma_f32_16x16x32_bf16 v[28:31], v[202:205], v[226:229], v[28:31]
	v_mfma_f32_16x16x32_bf16 v[24:27], v[202:205], v[230:233], v[24:27]
	v_mfma_f32_16x16x32_bf16 v[20:23], v[202:205], v[234:237], v[20:23]
	v_mfma_f32_16x16x32_bf16 v[16:19], v[202:205], v[238:241], v[16:19]
	v_mfma_f32_16x16x32_bf16 v[8:11], v[206:209], v[226:229], v[8:11]
	v_mfma_f32_16x16x32_bf16 v[0:3], v[206:209], v[230:233], v[0:3]
	v_mfma_f32_16x16x32_bf16 v[12:15], v[206:209], v[234:237], v[12:15]
	v_mfma_f32_16x16x32_bf16 v[4:7], v[206:209], v[238:241], v[4:7]
	ds_read_b128 v[194:197], v180 offset:8192
	ds_read_b128 v[198:201], v180 offset:10240
	ds_read_b128 v[202:205], v180 offset:12288
	ds_read_b128 v[206:209], v180 offset:14336
	s_waitcnt lgkmcnt(4)
	v_mfma_f32_16x16x32_bf16 v[124:127], v[176:179], v[210:213], v[124:127]
	v_mfma_f32_16x16x32_bf16 v[120:123], v[176:179], v[214:217], v[120:123]
	v_mfma_f32_16x16x32_bf16 v[116:119], v[176:179], v[218:221], v[116:119]
	v_mfma_f32_16x16x32_bf16 v[112:115], v[176:179], v[222:225], v[112:115]
	v_mfma_f32_16x16x32_bf16 v[108:111], v[182:185], v[210:213], v[108:111]
	v_mfma_f32_16x16x32_bf16 v[104:107], v[182:185], v[214:217], v[104:107]
	v_mfma_f32_16x16x32_bf16 v[100:103], v[182:185], v[218:221], v[100:103]
	v_mfma_f32_16x16x32_bf16 v[96:99], v[182:185], v[222:225], v[96:99]
	v_mfma_f32_16x16x32_bf16 v[92:95], v[186:189], v[210:213], v[92:95]
	v_mfma_f32_16x16x32_bf16 v[88:91], v[186:189], v[214:217], v[88:91]
	v_mfma_f32_16x16x32_bf16 v[84:87], v[186:189], v[218:221], v[84:87]
	v_mfma_f32_16x16x32_bf16 v[80:83], v[186:189], v[222:225], v[80:83]
	v_mfma_f32_16x16x32_bf16 v[76:79], v[190:193], v[210:213], v[76:79]
	v_mfma_f32_16x16x32_bf16 v[72:75], v[190:193], v[214:217], v[72:75]
	v_mfma_f32_16x16x32_bf16 v[68:71], v[190:193], v[218:221], v[68:71]
	v_mfma_f32_16x16x32_bf16 v[64:67], v[190:193], v[222:225], v[64:67]
	ds_read_b128 v[176:179], v244
	ds_read_b128 v[182:185], v244 offset:2048
	ds_read_b128 v[186:189], v244 offset:4096
	ds_read_b128 v[190:193], v244 offset:6144
	ds_read_b128 v[226:229], v246 offset:32768
	ds_read_b128 v[230:233], v246 offset:34816
	ds_read_b128 v[234:237], v246 offset:36864
	ds_read_b128 v[238:241], v246 offset:38912
	s_waitcnt lgkmcnt(8)
	v_mfma_f32_16x16x32_bf16 v[60:63], v[194:197], v[210:213], v[60:63]
	v_mfma_f32_16x16x32_bf16 v[56:59], v[194:197], v[214:217], v[56:59]
	v_mfma_f32_16x16x32_bf16 v[52:55], v[194:197], v[218:221], v[52:55]
	v_mfma_f32_16x16x32_bf16 v[48:51], v[194:197], v[222:225], v[48:51]
	v_mfma_f32_16x16x32_bf16 v[44:47], v[198:201], v[210:213], v[44:47]
	v_mfma_f32_16x16x32_bf16 v[40:43], v[198:201], v[214:217], v[40:43]
	v_mfma_f32_16x16x32_bf16 v[36:39], v[198:201], v[218:221], v[36:39]
	v_mfma_f32_16x16x32_bf16 v[32:35], v[198:201], v[222:225], v[32:35]
	v_mfma_f32_16x16x32_bf16 v[28:31], v[202:205], v[210:213], v[28:31]
	v_mfma_f32_16x16x32_bf16 v[24:27], v[202:205], v[214:217], v[24:27]
	v_mfma_f32_16x16x32_bf16 v[20:23], v[202:205], v[218:221], v[20:23]
	v_mfma_f32_16x16x32_bf16 v[16:19], v[202:205], v[222:225], v[16:19]
	v_mfma_f32_16x16x32_bf16 v[8:11], v[206:209], v[210:213], v[8:11]
	v_mfma_f32_16x16x32_bf16 v[0:3], v[206:209], v[214:217], v[0:3]
	v_mfma_f32_16x16x32_bf16 v[12:15], v[206:209], v[218:221], v[12:15]
	v_mfma_f32_16x16x32_bf16 v[4:7], v[206:209], v[222:225], v[4:7]
	ds_read_b128 v[194:197], v244 offset:8192
	ds_read_b128 v[198:201], v244 offset:10240
	ds_read_b128 v[202:205], v244 offset:12288
	ds_read_b128 v[206:209], v244 offset:14336
	s_waitcnt lgkmcnt(4)
	v_mfma_f32_16x16x32_bf16 v[124:127], v[176:179], v[226:229], v[124:127]
	v_mfma_f32_16x16x32_bf16 v[120:123], v[176:179], v[230:233], v[120:123]
	v_mfma_f32_16x16x32_bf16 v[116:119], v[176:179], v[234:237], v[116:119]
	v_mfma_f32_16x16x32_bf16 v[112:115], v[176:179], v[238:241], v[112:115]
	v_mfma_f32_16x16x32_bf16 v[108:111], v[182:185], v[226:229], v[108:111]
	v_mfma_f32_16x16x32_bf16 v[104:107], v[182:185], v[230:233], v[104:107]
	v_mfma_f32_16x16x32_bf16 v[100:103], v[182:185], v[234:237], v[100:103]
	v_mfma_f32_16x16x32_bf16 v[96:99], v[182:185], v[238:241], v[96:99]
	v_mfma_f32_16x16x32_bf16 v[92:95], v[186:189], v[226:229], v[92:95]
	v_mfma_f32_16x16x32_bf16 v[88:91], v[186:189], v[230:233], v[88:91]
	v_mfma_f32_16x16x32_bf16 v[84:87], v[186:189], v[234:237], v[84:87]
	v_mfma_f32_16x16x32_bf16 v[80:83], v[186:189], v[238:241], v[80:83]
	v_mfma_f32_16x16x32_bf16 v[76:79], v[190:193], v[226:229], v[76:79]
	v_mfma_f32_16x16x32_bf16 v[72:75], v[190:193], v[230:233], v[72:75]
	v_mfma_f32_16x16x32_bf16 v[68:71], v[190:193], v[234:237], v[68:71]
	v_mfma_f32_16x16x32_bf16 v[64:67], v[190:193], v[238:241], v[64:67]
	s_add_u32 s68, s68, 0x80
	s_addc_u32 s69, s69, 0
	s_add_i32 s86, s86, 1
	s_waitcnt lgkmcnt(0)
	s_waitcnt vmcnt(0)
	s_barrier
	v_mfma_f32_16x16x32_bf16 v[60:63], v[194:197], v[226:229], v[60:63]
	v_mfma_f32_16x16x32_bf16 v[56:59], v[194:197], v[230:233], v[56:59]
	v_mfma_f32_16x16x32_bf16 v[52:55], v[194:197], v[234:237], v[52:55]
	v_mfma_f32_16x16x32_bf16 v[48:51], v[194:197], v[238:241], v[48:51]
	v_mfma_f32_16x16x32_bf16 v[44:47], v[198:201], v[226:229], v[44:47]
	v_mfma_f32_16x16x32_bf16 v[40:43], v[198:201], v[230:233], v[40:43]
	v_mfma_f32_16x16x32_bf16 v[36:39], v[198:201], v[234:237], v[36:39]
	v_mfma_f32_16x16x32_bf16 v[32:35], v[198:201], v[238:241], v[32:35]
	v_mfma_f32_16x16x32_bf16 v[28:31], v[202:205], v[226:229], v[28:31]
	v_mfma_f32_16x16x32_bf16 v[24:27], v[202:205], v[230:233], v[24:27]
	v_mfma_f32_16x16x32_bf16 v[20:23], v[202:205], v[234:237], v[20:23]
	v_mfma_f32_16x16x32_bf16 v[16:19], v[202:205], v[238:241], v[16:19]
	v_mfma_f32_16x16x32_bf16 v[8:11], v[206:209], v[226:229], v[8:11]
	v_mfma_f32_16x16x32_bf16 v[0:3], v[206:209], v[230:233], v[0:3]
	v_mfma_f32_16x16x32_bf16 v[12:15], v[206:209], v[234:237], v[12:15]
	v_mfma_f32_16x16x32_bf16 v[4:7], v[206:209], v[238:241], v[4:7]
	s_nop 7
	s_nop 7
	s_sub_u32 s68, s68, s34
	s_subb_u32 s69, s69, s35
	s_mov_b32 s87, 0x80000
	s_mov_b32 s87, 0x80000
	s_mov_b64 s[70:71], 0
	s_mov_b64 vcc, exec
	s_branch .LBB0_666

.LBB0_667:
	ds_read_b128 v[2:5], v0
	v_lshl_add_u64 v[6:7], v[138:139], 0, s[68:69]
	v_add_co_u32_e32 v8, vcc, 0x6000000, v6
	s_add_u32 s68, s68, 0x20000
	s_nop 0
	v_addc_co_u32_e32 v9, vcc, 0, v7, vcc
	s_waitcnt lgkmcnt(0)
	global_store_dwordx4 v[8:9], v[2:5], off sc1
	ds_read_b128 v[2:5], v0 offset:1152
	v_add_co_u32_e32 v8, vcc, 0x6008000, v6
	s_addc_u32 s69, s69, 0
	s_nop 0
	v_addc_co_u32_e32 v9, vcc, 0, v7, vcc
	s_waitcnt lgkmcnt(0)
	global_store_dwordx4 v[8:9], v[2:5], off sc1
	ds_read_b128 v[2:5], v0 offset:2304
	v_add_co_u32_e32 v8, vcc, 0x6010000, v6
	s_cmp_lg_u32 s68, 0x80000
	s_nop 0
	v_addc_co_u32_e32 v9, vcc, 0, v7, vcc
	s_waitcnt lgkmcnt(0)
	global_store_dwordx4 v[8:9], v[2:5], off sc1
	ds_read_b128 v[2:5], v0 offset:3456
	v_add_co_u32_e32 v6, vcc, 0x6018000, v6
	v_add_u32_e32 v0, 0x1200, v0
	s_nop 0
	v_addc_co_u32_e32 v7, vcc, 0, v7, vcc
	s_waitcnt lgkmcnt(0)
	global_store_dwordx4 v[6:7], v[2:5], off sc1
	s_cbranch_scc1 .LBB0_667
	v_mov_b32_e32 v6, v181
	s_waitcnt lgkmcnt(0)
	s_lshl_b32 s68, s6, 20
	v_lshrrev_b32_e32 v7, 4, v6
	v_lshlrev_b32_e32 v1, 6, v6
	v_xor_b32_e32 v0, v7, v6
	v_and_b32_e32 v8, 0x3c0, v1
	v_lshlrev_b32_e32 v1, 8, v6
	v_lshlrev_b32_e32 v0, 3, v0
	v_and_b32_e32 v1, 0xfffff800, v1
	s_lshl_b64 s[20:21], s[64:65], 20
	v_and_or_b32 v0, v0, 56, v1
	s_add_u32 s20, s75, s20
	v_ashrrev_i32_e32 v1, 31, v0
	s_addc_u32 s21, s88, s21
	v_lshlrev_b64 v[0:1], 1, v[0:1]
	v_lshl_add_u32 v174, v6, 4, 0
	v_lshl_add_u64 v[2:3], s[20:21], 0, v[0:1]
	v_readfirstlane_b32 s20, v174
	v_add_u32_e32 v9, 0x2000, v174
	s_mov_b32 m0, s20
	v_readfirstlane_b32 s20, v9
	v_add_u32_e32 v9, 0x4000, v174
	s_barrier
	global_load_lds_dwordx4 v[2:3], off
	v_lshl_add_u64 v[4:5], v[2:3], 0, s[10:11]
	s_mov_b32 m0, s20
	v_readfirstlane_b32 s20, v9
	global_load_lds_dwordx4 v[4:5], off
	v_lshl_add_u64 v[4:5], v[2:3], 0, s[40:41]
	s_mov_b32 m0, s20
	s_lshl_b32 s64, s95, 12
	global_load_lds_dwordx4 v[4:5], off
	v_add_u32_e32 v4, 0x6000, v174
	s_add_u32 s64, s89, s64
	v_readfirstlane_b32 s20, v4
	v_add_u32_e32 v4, 0x8000, v174
	s_addc_u32 s65, s90, 0
	v_lshl_add_u64 v[2:3], v[2:3], 0, s[42:43]
	s_mov_b32 m0, s20
	v_readfirstlane_b32 s20, v4
	v_add_u32_e32 v9, 0xa000, v174
	global_load_lds_dwordx4 v[2:3], off
	v_lshl_add_u64 v[2:3], s[64:65], 0, v[0:1]
	s_mov_b32 m0, s20
	v_readfirstlane_b32 s20, v9
	v_add_u32_e32 v9, 0xc000, v174
	global_load_lds_dwordx4 v[2:3], off
	v_lshl_add_u64 v[4:5], v[2:3], 0, s[10:11]
	s_mov_b32 m0, s20
	v_readfirstlane_b32 s20, v9
	global_load_lds_dwordx4 v[4:5], off
	v_lshl_add_u64 v[4:5], v[2:3], 0, s[40:41]
	s_mov_b32 m0, s20
	v_lshl_add_u64 v[2:3], v[2:3], 0, s[42:43]
	global_load_lds_dwordx4 v[4:5], off
	v_add_u32_e32 v4, 0xe000, v174
	s_mov_b32 s69, 0
	v_readfirstlane_b32 s20, v4
	s_mov_b32 m0, s20
	v_ashrrev_i32_e32 v4, 6, v6
	global_load_lds_dwordx4 v[2:3], off
	v_lshrrev_b32_e32 v5, 30, v4
	v_add_u32_e32 v5, v4, v5
	s_lshl_b64 s[20:21], s[66:67], 20
	v_bfe_u32 v2, v6, 4, 2
	v_bfe_u32 v3, v6, 1, 3
	v_and_b32_e32 v6, 0x7fffc, v5
	s_add_u32 s20, s34, s20
	v_sub_u32_e32 v4, v4, v6
	s_addc_u32 s21, s35, s21
	v_lshlrev_b32_e32 v5, 12, v5
	v_lshlrev_b32_e32 v176, 13, v4
	v_bitop3_b32 v4, v7, v3, 3 bitop3:0x6c
	v_bitop3_b32 v2, v2, v3, 4 bitop3:0x36
	v_lshl_add_u64 v[142:143], s[20:21], 0, v[0:1]
	s_add_u32 s20, s34, s68
	v_and_b32_e32 v175, 0xffffc000, v5
	v_lshlrev_b32_e32 v5, 3, v4
	v_lshlrev_b32_e32 v2, 3, v2
	s_addc_u32 s21, s35, 0
	v_mov_b32_e32 v4, 0
	v_lshl_add_u64 v[144:145], s[20:21], 0, v[0:1]
	s_mov_b64 s[64:65], 0
	v_lshlrev_b32_e32 v177, 1, v8
	v_lshlrev_b32_e32 v178, 1, v5
	v_lshlrev_b32_e32 v179, 1, v2
	s_mov_b32 s68, 0
	v_mov_b32_e32 v5, v4
	v_mov_b32_e32 v6, v4
	v_mov_b32_e32 v7, v4
	v_mov_b32_e32 v8, v4
	v_mov_b32_e32 v9, v4
	v_mov_b32_e32 v10, v4
	v_mov_b32_e32 v11, v4
	v_mov_b32_e32 v0, v4
	v_mov_b32_e32 v1, v4
	v_mov_b32_e32 v2, v4
	v_mov_b32_e32 v3, v4
	v_mov_b32_e32 v12, v4
	v_mov_b32_e32 v13, v4
	v_mov_b32_e32 v14, v4
	v_mov_b32_e32 v15, v4
	v_mov_b32_e32 v16, v4
	v_mov_b32_e32 v17, v4
	v_mov_b32_e32 v18, v4
	v_mov_b32_e32 v19, v4
	v_mov_b32_e32 v20, v4
	v_mov_b32_e32 v21, v4
	v_mov_b32_e32 v22, v4
	v_mov_b32_e32 v23, v4
	v_mov_b32_e32 v24, v4
	v_mov_b32_e32 v25, v4
	v_mov_b32_e32 v26, v4
	v_mov_b32_e32 v27, v4
	v_mov_b32_e32 v28, v4
	v_mov_b32_e32 v29, v4
	v_mov_b32_e32 v30, v4
	v_mov_b32_e32 v31, v4
	v_mov_b32_e32 v32, v4
	v_mov_b32_e32 v33, v4
	v_mov_b32_e32 v34, v4
	v_mov_b32_e32 v35, v4
	v_mov_b32_e32 v36, v4
	v_mov_b32_e32 v37, v4
	v_mov_b32_e32 v38, v4
	v_mov_b32_e32 v39, v4
	v_mov_b32_e32 v40, v4
	v_mov_b32_e32 v41, v4
	v_mov_b32_e32 v42, v4
	v_mov_b32_e32 v43, v4
	v_mov_b32_e32 v44, v4
	v_mov_b32_e32 v45, v4
	v_mov_b32_e32 v46, v4
	v_mov_b32_e32 v47, v4
	v_mov_b32_e32 v48, v4
	v_mov_b32_e32 v49, v4
	v_mov_b32_e32 v50, v4
	v_mov_b32_e32 v51, v4
	v_mov_b32_e32 v52, v4
	v_mov_b32_e32 v53, v4
	v_mov_b32_e32 v54, v4
	v_mov_b32_e32 v55, v4
	v_mov_b32_e32 v56, v4
	v_mov_b32_e32 v57, v4
	v_mov_b32_e32 v58, v4
	v_mov_b32_e32 v59, v4
	v_mov_b32_e32 v60, v4
	v_mov_b32_e32 v61, v4
	v_mov_b32_e32 v62, v4
	v_mov_b32_e32 v63, v4
	v_mov_b32_e32 v64, v4
	v_mov_b32_e32 v65, v4
	v_mov_b32_e32 v66, v4
	v_mov_b32_e32 v67, v4
	v_mov_b32_e32 v68, v4
	v_mov_b32_e32 v69, v4
	v_mov_b32_e32 v70, v4
	v_mov_b32_e32 v71, v4
	v_mov_b32_e32 v72, v4
	v_mov_b32_e32 v73, v4
	v_mov_b32_e32 v74, v4
	v_mov_b32_e32 v75, v4
	v_mov_b32_e32 v76, v4
	v_mov_b32_e32 v77, v4
	v_mov_b32_e32 v78, v4
	v_mov_b32_e32 v79, v4
	v_mov_b32_e32 v80, v4
	v_mov_b32_e32 v81, v4
	v_mov_b32_e32 v82, v4
	v_mov_b32_e32 v83, v4
	v_mov_b32_e32 v84, v4
	v_mov_b32_e32 v85, v4
	v_mov_b32_e32 v86, v4
	v_mov_b32_e32 v87, v4
	v_mov_b32_e32 v88, v4
	v_mov_b32_e32 v89, v4
	v_mov_b32_e32 v90, v4
	v_mov_b32_e32 v91, v4
	v_mov_b32_e32 v92, v4
	v_mov_b32_e32 v93, v4
	v_mov_b32_e32 v94, v4
	v_mov_b32_e32 v95, v4
	v_mov_b32_e32 v96, v4
	v_mov_b32_e32 v97, v4
	v_mov_b32_e32 v98, v4
	v_mov_b32_e32 v99, v4
	v_mov_b32_e32 v100, v4
	v_mov_b32_e32 v101, v4
	v_mov_b32_e32 v102, v4
	v_mov_b32_e32 v103, v4
	v_mov_b32_e32 v104, v4
	v_mov_b32_e32 v105, v4
	v_mov_b32_e32 v106, v4
	v_mov_b32_e32 v107, v4
	v_mov_b32_e32 v108, v4
	v_mov_b32_e32 v109, v4
	v_mov_b32_e32 v110, v4
	v_mov_b32_e32 v111, v4
	v_mov_b32_e32 v112, v4
	v_mov_b32_e32 v113, v4
	v_mov_b32_e32 v114, v4
	v_mov_b32_e32 v115, v4
	v_mov_b32_e32 v116, v4
	v_mov_b32_e32 v117, v4
	v_mov_b32_e32 v118, v4
	v_mov_b32_e32 v119, v4
	v_mov_b32_e32 v120, v4
	v_mov_b32_e32 v121, v4
	v_mov_b32_e32 v122, v4
	v_mov_b32_e32 v123, v4
	v_mov_b32_e32 v124, v4
	v_mov_b32_e32 v125, v4
	v_mov_b32_e32 v126, v4
	v_mov_b32_e32 v127, v4
	s_waitcnt vmcnt(0) lgkmcnt(0)
	s_barrier
	v_add3_u32 v180, v175, v177, v178
	v_add3_u32 v249, v176, v177, v178
	v_add3_u32 v248, v175, v177, v179
	v_add3_u32 v250, v176, v177, v179
	v_readfirstlane_b32 s69, v174
	ds_read_b128 v[182:185], v180
	ds_read_b128 v[186:189], v180 offset:2048
	ds_read_b128 v[190:193], v180 offset:4096
	ds_read_b128 v[194:197], v180 offset:6144
	ds_read_b128 v[214:217], v249 offset:32768
	ds_read_b128 v[218:221], v249 offset:34816
	ds_read_b128 v[222:225], v249 offset:36864
	ds_read_b128 v[226:229], v249 offset:38912
	s_mov_b32 s68, 0
	s_mov_b64 s[64:65], s[34:35]
	v_subrev_u32_e32 v246, s34, v142
	v_subrev_u32_e32 v247, s34, v144
	s_add_u32 s69, s69, 0x10000
	s_add_u32 s66, s64, s44
	s_addc_u32 s67, s65, s45
	s_mov_b32 m0, s69
	global_load_lds_dwordx4 v246, s[66:67]
	s_add_u32 s66, s64, s46
	s_addc_u32 s67, s65, s47
	s_add_u32 m0, s69, 0x2000
	global_load_lds_dwordx4 v246, s[66:67]
	s_add_u32 s66, s64, s48
	s_addc_u32 s67, s65, s49
	s_add_u32 m0, s69, 0x4000
	global_load_lds_dwordx4 v246, s[66:67]
	s_add_u32 s66, s64, s50
	s_addc_u32 s67, s65, s51
	s_add_u32 m0, s69, 0x6000
	global_load_lds_dwordx4 v246, s[66:67]
	s_add_u32 s66, s64, s52
	s_addc_u32 s67, s65, s53
	s_add_u32 m0, s69, 0x8000
	global_load_lds_dwordx4 v247, s[66:67]
	s_add_u32 s66, s64, s54
	s_addc_u32 s67, s65, s55
	s_add_u32 m0, s69, 0xa000
	global_load_lds_dwordx4 v247, s[66:67]
	s_add_u32 s66, s64, s60
	s_addc_u32 s67, s65, s61
	s_add_u32 m0, s69, 0xc000
	global_load_lds_dwordx4 v247, s[66:67]
	s_add_u32 s66, s64, s62
	s_addc_u32 s67, s65, s63
	s_add_u32 m0, s69, 0xe000
	global_load_lds_dwordx4 v247, s[66:67]
	s_branch .Lg6_entry
.Lg6_top:
	s_waitcnt lgkmcnt(0)
	s_waitcnt vmcnt(0)
	s_barrier
	v_xor_b32_e32 v180, 0x10000, v180
	v_xor_b32_e32 v249, 0x10000, v249
	v_xor_b32_e32 v248, 0x10000, v248
	v_xor_b32_e32 v250, 0x10000, v250
	s_xor_b32 s69, s69, 0x10000
	ds_read_b128 v[182:185], v180
	ds_read_b128 v[186:189], v180 offset:2048
	ds_read_b128 v[190:193], v180 offset:4096
	ds_read_b128 v[194:197], v180 offset:6144
	ds_read_b128 v[214:217], v249 offset:32768
	ds_read_b128 v[218:221], v249 offset:34816
	ds_read_b128 v[222:225], v249 offset:36864
	ds_read_b128 v[226:229], v249 offset:38912
	v_mfma_f32_16x16x32_bf16 v[60:63], v[198:201], v[230:233], v[60:63]
	v_mfma_f32_16x16x32_bf16 v[56:59], v[198:201], v[234:237], v[56:59]
	s_add_u32 s66, s64, s44
	s_addc_u32 s67, s65, s45
	s_mov_b32 m0, s69
	global_load_lds_dwordx4 v246, s[66:67]
	v_mfma_f32_16x16x32_bf16 v[52:55], v[198:201], v[238:241], v[52:55]
	v_mfma_f32_16x16x32_bf16 v[48:51], v[198:201], v[242:245], v[48:51]
	s_add_u32 s66, s64, s46
	s_addc_u32 s67, s65, s47
	s_add_u32 m0, s69, 0x2000
	global_load_lds_dwordx4 v246, s[66:67]
	v_mfma_f32_16x16x32_bf16 v[44:47], v[202:205], v[230:233], v[44:47]
	v_mfma_f32_16x16x32_bf16 v[40:43], v[202:205], v[234:237], v[40:43]
	s_add_u32 s66, s64, s48
	s_addc_u32 s67, s65, s49
	s_add_u32 m0, s69, 0x4000
	global_load_lds_dwordx4 v246, s[66:67]
	v_mfma_f32_16x16x32_bf16 v[36:39], v[202:205], v[238:241], v[36:39]
	v_mfma_f32_16x16x32_bf16 v[32:35], v[202:205], v[242:245], v[32:35]
	s_add_u32 s66, s64, s50
	s_addc_u32 s67, s65, s51
	s_add_u32 m0, s69, 0x6000
	global_load_lds_dwordx4 v246, s[66:67]
	v_mfma_f32_16x16x32_bf16 v[28:31], v[206:209], v[230:233], v[28:31]
	v_mfma_f32_16x16x32_bf16 v[24:27], v[206:209], v[234:237], v[24:27]
	s_add_u32 s66, s64, s52
	s_addc_u32 s67, s65, s53
	s_add_u32 m0, s69, 0x8000
	global_load_lds_dwordx4 v247, s[66:67]
	v_mfma_f32_16x16x32_bf16 v[20:23], v[206:209], v[238:241], v[20:23]
	v_mfma_f32_16x16x32_bf16 v[16:19], v[206:209], v[242:245], v[16:19]
	s_add_u32 s66, s64, s54
	s_addc_u32 s67, s65, s55
	s_add_u32 m0, s69, 0xa000
	global_load_lds_dwordx4 v247, s[66:67]
	v_mfma_f32_16x16x32_bf16 v[12:15], v[210:213], v[230:233], v[12:15]
	v_mfma_f32_16x16x32_bf16 v[0:3], v[210:213], v[234:237], v[0:3]
	s_add_u32 s66, s64, s60
	s_addc_u32 s67, s65, s61
	s_add_u32 m0, s69, 0xc000
	global_load_lds_dwordx4 v247, s[66:67]
	v_mfma_f32_16x16x32_bf16 v[8:11], v[210:213], v[238:241], v[8:11]
	v_mfma_f32_16x16x32_bf16 v[4:7], v[210:213], v[242:245], v[4:7]
	s_add_u32 s66, s64, s62
	s_addc_u32 s67, s65, s63
	s_add_u32 m0, s69, 0xe000
	global_load_lds_dwordx4 v247, s[66:67]
.Lg6_entry:
	ds_read_b128 v[198:201], v180 offset:8192
	ds_read_b128 v[202:205], v180 offset:10240
	ds_read_b128 v[206:209], v180 offset:12288
	ds_read_b128 v[210:213], v180 offset:14336
	s_waitcnt lgkmcnt(4)
	v_mfma_f32_16x16x32_bf16 v[124:127], v[182:185], v[214:217], v[124:127]
	v_mfma_f32_16x16x32_bf16 v[120:123], v[182:185], v[218:221], v[120:123]
	v_mfma_f32_16x16x32_bf16 v[116:119], v[182:185], v[222:225], v[116:119]
	v_mfma_f32_16x16x32_bf16 v[112:115], v[182:185], v[226:229], v[112:115]
	v_mfma_f32_16x16x32_bf16 v[108:111], v[186:189], v[214:217], v[108:111]
	v_mfma_f32_16x16x32_bf16 v[104:107], v[186:189], v[218:221], v[104:107]
	v_mfma_f32_16x16x32_bf16 v[100:103], v[186:189], v[222:225], v[100:103]
	v_mfma_f32_16x16x32_bf16 v[96:99], v[186:189], v[226:229], v[96:99]
	v_mfma_f32_16x16x32_bf16 v[92:95], v[190:193], v[214:217], v[92:95]
	v_mfma_f32_16x16x32_bf16 v[88:91], v[190:193], v[218:221], v[88:91]
	v_mfma_f32_16x16x32_bf16 v[84:87], v[190:193], v[222:225], v[84:87]
	v_mfma_f32_16x16x32_bf16 v[80:83], v[190:193], v[226:229], v[80:83]
	v_mfma_f32_16x16x32_bf16 v[76:79], v[194:197], v[214:217], v[76:79]
	v_mfma_f32_16x16x32_bf16 v[72:75], v[194:197], v[218:221], v[72:75]
	v_mfma_f32_16x16x32_bf16 v[68:71], v[194:197], v[222:225], v[68:71]
	v_mfma_f32_16x16x32_bf16 v[64:67], v[194:197], v[226:229], v[64:67]
	ds_read_b128 v[182:185], v248
	ds_read_b128 v[186:189], v248 offset:2048
	ds_read_b128 v[190:193], v248 offset:4096
	ds_read_b128 v[194:197], v248 offset:6144
	ds_read_b128 v[230:233], v250 offset:32768
	ds_read_b128 v[234:237], v250 offset:34816
	ds_read_b128 v[238:241], v250 offset:36864
	ds_read_b128 v[242:245], v250 offset:38912
	s_waitcnt lgkmcnt(8)
	v_mfma_f32_16x16x32_bf16 v[60:63], v[198:201], v[214:217], v[60:63]
	v_mfma_f32_16x16x32_bf16 v[56:59], v[198:201], v[218:221], v[56:59]
	v_mfma_f32_16x16x32_bf16 v[52:55], v[198:201], v[222:225], v[52:55]
	v_mfma_f32_16x16x32_bf16 v[48:51], v[198:201], v[226:229], v[48:51]
	v_mfma_f32_16x16x32_bf16 v[44:47], v[202:205], v[214:217], v[44:47]
	v_mfma_f32_16x16x32_bf16 v[40:43], v[202:205], v[218:221], v[40:43]
	v_mfma_f32_16x16x32_bf16 v[36:39], v[202:205], v[222:225], v[36:39]
	v_mfma_f32_16x16x32_bf16 v[32:35], v[202:205], v[226:229], v[32:35]
	v_mfma_f32_16x16x32_bf16 v[28:31], v[206:209], v[214:217], v[28:31]
	v_mfma_f32_16x16x32_bf16 v[24:27], v[206:209], v[218:221], v[24:27]
	v_mfma_f32_16x16x32_bf16 v[20:23], v[206:209], v[222:225], v[20:23]
	v_mfma_f32_16x16x32_bf16 v[16:19], v[206:209], v[226:229], v[16:19]
	v_mfma_f32_16x16x32_bf16 v[12:15], v[210:213], v[214:217], v[12:15]
	v_mfma_f32_16x16x32_bf16 v[0:3], v[210:213], v[218:221], v[0:3]
	v_mfma_f32_16x16x32_bf16 v[8:11], v[210:213], v[222:225], v[8:11]
	v_mfma_f32_16x16x32_bf16 v[4:7], v[210:213], v[226:229], v[4:7]
	ds_read_b128 v[198:201], v248 offset:8192
	ds_read_b128 v[202:205], v248 offset:10240
	ds_read_b128 v[206:209], v248 offset:12288
	ds_read_b128 v[210:213], v248 offset:14336
	s_waitcnt lgkmcnt(4)
	v_mfma_f32_16x16x32_bf16 v[124:127], v[182:185], v[230:233], v[124:127]
	v_mfma_f32_16x16x32_bf16 v[120:123], v[182:185], v[234:237], v[120:123]
	v_mfma_f32_16x16x32_bf16 v[116:119], v[182:185], v[238:241], v[116:119]
	v_mfma_f32_16x16x32_bf16 v[112:115], v[182:185], v[242:245], v[112:115]
	v_mfma_f32_16x16x32_bf16 v[108:111], v[186:189], v[230:233], v[108:111]
	v_mfma_f32_16x16x32_bf16 v[104:107], v[186:189], v[234:237], v[104:107]
	v_mfma_f32_16x16x32_bf16 v[100:103], v[186:189], v[238:241], v[100:103]
	v_mfma_f32_16x16x32_bf16 v[96:99], v[186:189], v[242:245], v[96:99]
	v_mfma_f32_16x16x32_bf16 v[92:95], v[190:193], v[230:233], v[92:95]
	v_mfma_f32_16x16x32_bf16 v[88:91], v[190:193], v[234:237], v[88:91]
	v_mfma_f32_16x16x32_bf16 v[84:87], v[190:193], v[238:241], v[84:87]
	v_mfma_f32_16x16x32_bf16 v[80:83], v[190:193], v[242:245], v[80:83]
	v_mfma_f32_16x16x32_bf16 v[76:79], v[194:197], v[230:233], v[76:79]
	v_mfma_f32_16x16x32_bf16 v[72:75], v[194:197], v[234:237], v[72:75]
	v_mfma_f32_16x16x32_bf16 v[68:71], v[194:197], v[238:241], v[68:71]
	v_mfma_f32_16x16x32_bf16 v[64:67], v[194:197], v[242:245], v[64:67]
	s_add_u32 s64, s64, 0x80
	s_addc_u32 s65, s65, 0
	s_add_i32 s68, s68, 1
	s_cmp_lt_u32 s68, 31
	s_cbranch_scc1 .Lg6_top
	s_waitcnt lgkmcnt(0)
	s_waitcnt vmcnt(0)
	s_barrier
	v_xor_b32_e32 v180, 0x10000, v180
	v_xor_b32_e32 v249, 0x10000, v249
	v_xor_b32_e32 v248, 0x10000, v248
	v_xor_b32_e32 v250, 0x10000, v250
	s_xor_b32 s69, s69, 0x10000
	ds_read_b128 v[182:185], v180
	ds_read_b128 v[186:189], v180 offset:2048
	ds_read_b128 v[190:193], v180 offset:4096
	ds_read_b128 v[194:197], v180 offset:6144
	ds_read_b128 v[214:217], v249 offset:32768
	ds_read_b128 v[218:221], v249 offset:34816
	ds_read_b128 v[222:225], v249 offset:36864
	ds_read_b128 v[226:229], v249 offset:38912
	v_mfma_f32_16x16x32_bf16 v[60:63], v[198:201], v[230:233], v[60:63]
	v_mfma_f32_16x16x32_bf16 v[56:59], v[198:201], v[234:237], v[56:59]
	v_mfma_f32_16x16x32_bf16 v[52:55], v[198:201], v[238:241], v[52:55]
	v_mfma_f32_16x16x32_bf16 v[48:51], v[198:201], v[242:245], v[48:51]
	v_mfma_f32_16x16x32_bf16 v[44:47], v[202:205], v[230:233], v[44:47]
	v_mfma_f32_16x16x32_bf16 v[40:43], v[202:205], v[234:237], v[40:43]
	v_mfma_f32_16x16x32_bf16 v[36:39], v[202:205], v[238:241], v[36:39]
	v_mfma_f32_16x16x32_bf16 v[32:35], v[202:205], v[242:245], v[32:35]
	v_mfma_f32_16x16x32_bf16 v[28:31], v[206:209], v[230:233], v[28:31]
	v_mfma_f32_16x16x32_bf16 v[24:27], v[206:209], v[234:237], v[24:27]
	v_mfma_f32_16x16x32_bf16 v[20:23], v[206:209], v[238:241], v[20:23]
	v_mfma_f32_16x16x32_bf16 v[16:19], v[206:209], v[242:245], v[16:19]
	v_mfma_f32_16x16x32_bf16 v[12:15], v[210:213], v[230:233], v[12:15]
	v_mfma_f32_16x16x32_bf16 v[0:3], v[210:213], v[234:237], v[0:3]
	v_mfma_f32_16x16x32_bf16 v[8:11], v[210:213], v[238:241], v[8:11]
	v_mfma_f32_16x16x32_bf16 v[4:7], v[210:213], v[242:245], v[4:7]
	ds_read_b128 v[198:201], v180 offset:8192
	ds_read_b128 v[202:205], v180 offset:10240
	ds_read_b128 v[206:209], v180 offset:12288
	ds_read_b128 v[210:213], v180 offset:14336
	s_waitcnt lgkmcnt(4)
	v_mfma_f32_16x16x32_bf16 v[124:127], v[182:185], v[214:217], v[124:127]
	v_mfma_f32_16x16x32_bf16 v[120:123], v[182:185], v[218:221], v[120:123]
	v_mfma_f32_16x16x32_bf16 v[116:119], v[182:185], v[222:225], v[116:119]
	v_mfma_f32_16x16x32_bf16 v[112:115], v[182:185], v[226:229], v[112:115]
	v_mfma_f32_16x16x32_bf16 v[108:111], v[186:189], v[214:217], v[108:111]
	v_mfma_f32_16x16x32_bf16 v[104:107], v[186:189], v[218:221], v[104:107]
	v_mfma_f32_16x16x32_bf16 v[100:103], v[186:189], v[222:225], v[100:103]
	v_mfma_f32_16x16x32_bf16 v[96:99], v[186:189], v[226:229], v[96:99]
	v_mfma_f32_16x16x32_bf16 v[92:95], v[190:193], v[214:217], v[92:95]
	v_mfma_f32_16x16x32_bf16 v[88:91], v[190:193], v[218:221], v[88:91]
	v_mfma_f32_16x16x32_bf16 v[84:87], v[190:193], v[222:225], v[84:87]
	v_mfma_f32_16x16x32_bf16 v[80:83], v[190:193], v[226:229], v[80:83]
	v_mfma_f32_16x16x32_bf16 v[76:79], v[194:197], v[214:217], v[76:79]
	v_mfma_f32_16x16x32_bf16 v[72:75], v[194:197], v[218:221], v[72:75]
	v_mfma_f32_16x16x32_bf16 v[68:71], v[194:197], v[222:225], v[68:71]
	v_mfma_f32_16x16x32_bf16 v[64:67], v[194:197], v[226:229], v[64:67]
	ds_read_b128 v[182:185], v248
	ds_read_b128 v[186:189], v248 offset:2048
	ds_read_b128 v[190:193], v248 offset:4096
	ds_read_b128 v[194:197], v248 offset:6144
	ds_read_b128 v[230:233], v250 offset:32768
	ds_read_b128 v[234:237], v250 offset:34816
	ds_read_b128 v[238:241], v250 offset:36864
	ds_read_b128 v[242:245], v250 offset:38912
	s_waitcnt lgkmcnt(8)
	v_mfma_f32_16x16x32_bf16 v[60:63], v[198:201], v[214:217], v[60:63]
	v_mfma_f32_16x16x32_bf16 v[56:59], v[198:201], v[218:221], v[56:59]
	v_mfma_f32_16x16x32_bf16 v[52:55], v[198:201], v[222:225], v[52:55]
	v_mfma_f32_16x16x32_bf16 v[48:51], v[198:201], v[226:229], v[48:51]
	v_mfma_f32_16x16x32_bf16 v[44:47], v[202:205], v[214:217], v[44:47]
	v_mfma_f32_16x16x32_bf16 v[40:43], v[202:205], v[218:221], v[40:43]
	v_mfma_f32_16x16x32_bf16 v[36:39], v[202:205], v[222:225], v[36:39]
	v_mfma_f32_16x16x32_bf16 v[32:35], v[202:205], v[226:229], v[32:35]
	v_mfma_f32_16x16x32_bf16 v[28:31], v[206:209], v[214:217], v[28:31]
	v_mfma_f32_16x16x32_bf16 v[24:27], v[206:209], v[218:221], v[24:27]
	v_mfma_f32_16x16x32_bf16 v[20:23], v[206:209], v[222:225], v[20:23]
	v_mfma_f32_16x16x32_bf16 v[16:19], v[206:209], v[226:229], v[16:19]
	v_mfma_f32_16x16x32_bf16 v[12:15], v[210:213], v[214:217], v[12:15]
	v_mfma_f32_16x16x32_bf16 v[0:3], v[210:213], v[218:221], v[0:3]
	v_mfma_f32_16x16x32_bf16 v[8:11], v[210:213], v[222:225], v[8:11]
	v_mfma_f32_16x16x32_bf16 v[4:7], v[210:213], v[226:229], v[4:7]
	ds_read_b128 v[198:201], v248 offset:8192
	ds_read_b128 v[202:205], v248 offset:10240
	ds_read_b128 v[206:209], v248 offset:12288
	ds_read_b128 v[210:213], v248 offset:14336
	s_waitcnt lgkmcnt(4)
	v_mfma_f32_16x16x32_bf16 v[124:127], v[182:185], v[230:233], v[124:127]
	v_mfma_f32_16x16x32_bf16 v[120:123], v[182:185], v[234:237], v[120:123]
	v_mfma_f32_16x16x32_bf16 v[116:119], v[182:185], v[238:241], v[116:119]
	v_mfma_f32_16x16x32_bf16 v[112:115], v[182:185], v[242:245], v[112:115]
	v_mfma_f32_16x16x32_bf16 v[108:111], v[186:189], v[230:233], v[108:111]
	v_mfma_f32_16x16x32_bf16 v[104:107], v[186:189], v[234:237], v[104:107]
	v_mfma_f32_16x16x32_bf16 v[100:103], v[186:189], v[238:241], v[100:103]
	v_mfma_f32_16x16x32_bf16 v[96:99], v[186:189], v[242:245], v[96:99]
	v_mfma_f32_16x16x32_bf16 v[92:95], v[190:193], v[230:233], v[92:95]
	v_mfma_f32_16x16x32_bf16 v[88:91], v[190:193], v[234:237], v[88:91]
	v_mfma_f32_16x16x32_bf16 v[84:87], v[190:193], v[238:241], v[84:87]
	v_mfma_f32_16x16x32_bf16 v[80:83], v[190:193], v[242:245], v[80:83]
	v_mfma_f32_16x16x32_bf16 v[76:79], v[194:197], v[230:233], v[76:79]
	v_mfma_f32_16x16x32_bf16 v[72:75], v[194:197], v[234:237], v[72:75]
	v_mfma_f32_16x16x32_bf16 v[68:71], v[194:197], v[238:241], v[68:71]
	v_mfma_f32_16x16x32_bf16 v[64:67], v[194:197], v[242:245], v[64:67]
	s_add_u32 s64, s64, 0x80
	s_addc_u32 s65, s65, 0
	s_add_i32 s68, s68, 1
	s_waitcnt lgkmcnt(0)
	s_waitcnt vmcnt(0)
	s_barrier
	v_mfma_f32_16x16x32_bf16 v[60:63], v[198:201], v[230:233], v[60:63]
	v_mfma_f32_16x16x32_bf16 v[56:59], v[198:201], v[234:237], v[56:59]
	v_mfma_f32_16x16x32_bf16 v[52:55], v[198:201], v[238:241], v[52:55]
	v_mfma_f32_16x16x32_bf16 v[48:51], v[198:201], v[242:245], v[48:51]
	v_mfma_f32_16x16x32_bf16 v[44:47], v[202:205], v[230:233], v[44:47]
	v_mfma_f32_16x16x32_bf16 v[40:43], v[202:205], v[234:237], v[40:43]
	v_mfma_f32_16x16x32_bf16 v[36:39], v[202:205], v[238:241], v[36:39]
	v_mfma_f32_16x16x32_bf16 v[32:35], v[202:205], v[242:245], v[32:35]
	v_mfma_f32_16x16x32_bf16 v[28:31], v[206:209], v[230:233], v[28:31]
	v_mfma_f32_16x16x32_bf16 v[24:27], v[206:209], v[234:237], v[24:27]
	v_mfma_f32_16x16x32_bf16 v[20:23], v[206:209], v[238:241], v[20:23]
	v_mfma_f32_16x16x32_bf16 v[16:19], v[206:209], v[242:245], v[16:19]
	v_mfma_f32_16x16x32_bf16 v[12:15], v[210:213], v[230:233], v[12:15]
	v_mfma_f32_16x16x32_bf16 v[0:3], v[210:213], v[234:237], v[0:3]
	v_mfma_f32_16x16x32_bf16 v[8:11], v[210:213], v[238:241], v[8:11]
	v_mfma_f32_16x16x32_bf16 v[4:7], v[210:213], v[242:245], v[4:7]
	s_nop 7
	s_nop 7
	s_sub_u32 s64, s64, s34
	s_subb_u32 s65, s65, s35
	s_mov_b32 s69, 0x100000
	s_mov_b32 s70, 0x100000
	s_mov_b64 s[66:67], 0
	s_mov_b64 vcc, exec
	s_branch .LBB0_674

.LBB0_746:
	s_ashr_i32 s20, s60, 2
	v_mov_b32_e32 v6, v181
	s_and_b32 s6, s60, 7
	s_and_b32 s51, s20, -8
	s_or_b32 s46, s51, s6
	v_lshrrev_b32_e32 v7, 4, v6
	v_lshlrev_b32_e32 v1, 6, v6
	v_xor_b32_e32 v0, v7, v6
	v_and_b32_e32 v8, 0x3c0, v1
	v_lshlrev_b32_e32 v1, 8, v6
	s_ashr_i32 s47, s46, 31
	v_lshlrev_b32_e32 v0, 3, v0
	v_and_b32_e32 v1, 0xfffff800, v1
	s_and_b32 s50, s55, 7
	s_bfe_u32 s6, s60, 0x20003
	s_lshl_b64 s[20:21], s[46:47], 20
	v_and_or_b32 v0, v0, 56, v1
	s_add_u32 s20, s3, s20
	v_ashrrev_i32_e32 v1, 31, v0
	s_addc_u32 s21, s52, s21
	v_lshlrev_b64 v[0:1], 1, v[0:1]
	v_lshl_add_u32 v134, v6, 4, 0
	v_lshl_add_u64 v[2:3], s[20:21], 0, v[0:1]
	v_readfirstlane_b32 s20, v134
	v_add_u32_e32 v9, 0x2000, v134
	s_mov_b32 m0, s20
	v_readfirstlane_b32 s20, v9
	v_add_u32_e32 v9, 0x4000, v134
	s_waitcnt vmcnt(63) expcnt(7) lgkmcnt(15)
	s_barrier
	global_load_lds_dwordx4 v[2:3], off
	v_lshl_add_u64 v[4:5], v[2:3], 0, s[8:9]
	s_mov_b32 m0, s20
	v_readfirstlane_b32 s20, v9
	global_load_lds_dwordx4 v[4:5], off
	v_lshl_add_u64 v[4:5], v[2:3], 0, s[10:11]
	s_mov_b32 m0, s20
	s_lshl_b32 s47, s6, 20
	global_load_lds_dwordx4 v[4:5], off
	v_add_u32_e32 v4, 0x6000, v134
	s_add_u32 s48, s53, s47
	v_readfirstlane_b32 s20, v4
	v_add_u32_e32 v4, 0x8000, v134
	s_addc_u32 s49, s54, 0
	v_lshl_add_u64 v[2:3], v[2:3], 0, s[12:13]
	s_mov_b32 m0, s20
	v_readfirstlane_b32 s20, v4
	v_add_u32_e32 v9, 0xa000, v134
	global_load_lds_dwordx4 v[2:3], off
	v_lshl_add_u64 v[2:3], s[48:49], 0, v[0:1]
	s_mov_b32 m0, s20
	v_readfirstlane_b32 s20, v9
	v_add_u32_e32 v9, 0xc000, v134
	global_load_lds_dwordx4 v[2:3], off
	v_lshl_add_u64 v[4:5], v[2:3], 0, s[8:9]
	s_mov_b32 m0, s20
	v_readfirstlane_b32 s20, v9
	global_load_lds_dwordx4 v[4:5], off
	v_lshl_add_u64 v[4:5], v[2:3], 0, s[10:11]
	s_mov_b32 m0, s20
	v_lshl_add_u64 v[2:3], v[2:3], 0, s[12:13]
	global_load_lds_dwordx4 v[4:5], off
	v_add_u32_e32 v4, 0xe000, v134
	v_mov_b32_e32 v36, 0
	v_readfirstlane_b32 s20, v4
	s_mov_b32 m0, s20
	v_ashrrev_i32_e32 v4, 6, v6
	global_load_lds_dwordx4 v[2:3], off
	s_or_b32 s20, s51, s50
	v_lshrrev_b32_e32 v5, 30, v4
	s_ashr_i32 s21, s20, 31
	v_add_u32_e32 v5, v4, v5
	s_lshl_b64 s[20:21], s[20:21], 20
	v_bfe_u32 v2, v6, 4, 2
	v_bfe_u32 v3, v6, 1, 3
	v_and_b32_e32 v6, 0x7fffc, v5
	s_add_u32 s20, s34, s20
	v_sub_u32_e32 v4, v4, v6
	s_addc_u32 s21, s35, s21
	v_lshlrev_b32_e32 v136, 13, v4
	v_bitop3_b32 v4, v7, v3, 3 bitop3:0x6c
	v_bitop3_b32 v2, v2, v3, 4 bitop3:0x36
	v_lshl_add_u64 v[130:131], s[20:21], 0, v[0:1]
	s_add_u32 s20, s34, s47
	v_lshlrev_b32_e32 v5, 12, v5
	v_lshlrev_b32_e32 v4, 3, v4
	v_lshlrev_b32_e32 v2, 3, v2
	s_addc_u32 s21, s35, 0
	v_and_b32_e32 v135, 0xffffc000, v5
	v_lshl_add_u64 v[132:133], s[20:21], 0, v[0:1]
	s_mov_b64 s[48:49], 0
	v_lshlrev_b32_e32 v137, 1, v8
	v_lshlrev_b32_e32 v138, 1, v4
	v_lshlrev_b32_e32 v139, 1, v2
	s_mov_b32 s61, 0
	s_mov_b32 s47, 0
	v_mov_b32_e32 v37, v36
	v_mov_b32_e32 v38, v36
	v_mov_b32_e32 v39, v36
	v_mov_b32_e32 v40, v36
	v_mov_b32_e32 v41, v36
	v_mov_b32_e32 v42, v36
	v_mov_b32_e32 v43, v36
	v_mov_b32_e32 v0, v36
	v_mov_b32_e32 v1, v36
	v_mov_b32_e32 v2, v36
	v_mov_b32_e32 v3, v36
	v_mov_b32_e32 v4, v36
	v_mov_b32_e32 v5, v36
	v_mov_b32_e32 v6, v36
	v_mov_b32_e32 v7, v36
	v_mov_b32_e32 v8, v36
	v_mov_b32_e32 v9, v36
	v_mov_b32_e32 v10, v36
	v_mov_b32_e32 v11, v36
	v_mov_b32_e32 v12, v36
	v_mov_b32_e32 v13, v36
	v_mov_b32_e32 v14, v36
	v_mov_b32_e32 v15, v36
	v_mov_b32_e32 v16, v36
	v_mov_b32_e32 v17, v36
	v_mov_b32_e32 v18, v36
	v_mov_b32_e32 v19, v36
	v_mov_b32_e32 v20, v36
	v_mov_b32_e32 v21, v36
	v_mov_b32_e32 v22, v36
	v_mov_b32_e32 v23, v36
	v_mov_b32_e32 v24, v36
	v_mov_b32_e32 v25, v36
	v_mov_b32_e32 v26, v36
	v_mov_b32_e32 v27, v36
	v_mov_b32_e32 v28, v36
	v_mov_b32_e32 v29, v36
	v_mov_b32_e32 v30, v36
	v_mov_b32_e32 v31, v36
	v_mov_b32_e32 v32, v36
	v_mov_b32_e32 v33, v36
	v_mov_b32_e32 v34, v36
	v_mov_b32_e32 v35, v36
	v_mov_b32_e32 v44, v36
	v_mov_b32_e32 v45, v36
	v_mov_b32_e32 v46, v36
	v_mov_b32_e32 v47, v36
	v_mov_b32_e32 v48, v36
	v_mov_b32_e32 v49, v36
	v_mov_b32_e32 v50, v36
	v_mov_b32_e32 v51, v36
	v_mov_b32_e32 v52, v36
	v_mov_b32_e32 v53, v36
	v_mov_b32_e32 v54, v36
	v_mov_b32_e32 v55, v36
	v_mov_b32_e32 v56, v36
	v_mov_b32_e32 v57, v36
	v_mov_b32_e32 v58, v36
	v_mov_b32_e32 v59, v36
	v_mov_b32_e32 v60, v36
	v_mov_b32_e32 v61, v36
	v_mov_b32_e32 v62, v36
	v_mov_b32_e32 v63, v36
	v_mov_b32_e32 v64, v36
	v_mov_b32_e32 v65, v36
	v_mov_b32_e32 v66, v36
	v_mov_b32_e32 v67, v36
	v_mov_b32_e32 v68, v36
	v_mov_b32_e32 v69, v36
	v_mov_b32_e32 v70, v36
	v_mov_b32_e32 v71, v36
	v_mov_b32_e32 v72, v36
	v_mov_b32_e32 v73, v36
	v_mov_b32_e32 v74, v36
	v_mov_b32_e32 v75, v36
	v_mov_b32_e32 v76, v36
	v_mov_b32_e32 v77, v36
	v_mov_b32_e32 v78, v36
	v_mov_b32_e32 v79, v36
	v_mov_b32_e32 v80, v36
	v_mov_b32_e32 v81, v36
	v_mov_b32_e32 v82, v36
	v_mov_b32_e32 v83, v36
	v_mov_b32_e32 v84, v36
	v_mov_b32_e32 v85, v36
	v_mov_b32_e32 v86, v36
	v_mov_b32_e32 v87, v36
	v_mov_b32_e32 v88, v36
	v_mov_b32_e32 v89, v36
	v_mov_b32_e32 v90, v36
	v_mov_b32_e32 v91, v36
	v_mov_b32_e32 v92, v36
	v_mov_b32_e32 v93, v36
	v_mov_b32_e32 v94, v36
	v_mov_b32_e32 v95, v36
	v_mov_b32_e32 v96, v36
	v_mov_b32_e32 v97, v36
	v_mov_b32_e32 v98, v36
	v_mov_b32_e32 v99, v36
	v_mov_b32_e32 v100, v36
	v_mov_b32_e32 v101, v36
	v_mov_b32_e32 v102, v36
	v_mov_b32_e32 v103, v36
	v_mov_b32_e32 v104, v36
	v_mov_b32_e32 v105, v36
	v_mov_b32_e32 v106, v36
	v_mov_b32_e32 v107, v36
	v_mov_b32_e32 v108, v36
	v_mov_b32_e32 v109, v36
	v_mov_b32_e32 v110, v36
	v_mov_b32_e32 v111, v36
	v_mov_b32_e32 v112, v36
	v_mov_b32_e32 v113, v36
	v_mov_b32_e32 v114, v36
	v_mov_b32_e32 v115, v36
	v_mov_b32_e32 v116, v36
	v_mov_b32_e32 v117, v36
	v_mov_b32_e32 v118, v36
	v_mov_b32_e32 v119, v36
	v_mov_b32_e32 v120, v36
	v_mov_b32_e32 v121, v36
	v_mov_b32_e32 v122, v36
	v_mov_b32_e32 v123, v36
	v_mov_b32_e32 v124, v36
	v_mov_b32_e32 v125, v36
	v_mov_b32_e32 v126, v36
	v_mov_b32_e32 v127, v36
	s_waitcnt vmcnt(0) lgkmcnt(0)
	s_barrier
	v_add3_u32 v141, v135, v137, v138
	v_add3_u32 v210, v136, v137, v138
	v_add3_u32 v180, v135, v137, v139
	v_add3_u32 v211, v136, v137, v139
	v_readfirstlane_b32 s61, v134
	ds_read_b128 v[142:145], v141
	ds_read_b128 v[146:149], v141 offset:2048
	ds_read_b128 v[150:153], v141 offset:4096
	ds_read_b128 v[154:157], v141 offset:6144
	ds_read_b128 v[174:177], v210 offset:32768
	ds_read_b128 v[182:185], v210 offset:34816
	ds_read_b128 v[186:189], v210 offset:36864
	ds_read_b128 v[190:193], v210 offset:38912
	s_mov_b32 s47, 0
	s_mov_b64 s[48:49], s[34:35]
	v_subrev_u32_e32 v178, s34, v130
	v_subrev_u32_e32 v179, s34, v132
	s_add_u32 s61, s61, 0x10000
	s_add_u32 s50, s48, s14
	s_addc_u32 s51, s49, s15
	s_mov_b32 m0, s61
	global_load_lds_dwordx4 v178, s[50:51]
	s_add_u32 s50, s48, s16
	s_addc_u32 s51, s49, s17
	s_add_u32 m0, s61, 0x2000
	global_load_lds_dwordx4 v178, s[50:51]
	s_add_u32 s50, s48, s18
	s_addc_u32 s51, s49, s19
	s_add_u32 m0, s61, 0x4000
	global_load_lds_dwordx4 v178, s[50:51]
	s_add_u32 s50, s48, s22
	s_addc_u32 s51, s49, s23
	s_add_u32 m0, s61, 0x6000
	global_load_lds_dwordx4 v178, s[50:51]
	s_add_u32 s50, s48, s36
	s_addc_u32 s51, s49, s37
	s_add_u32 m0, s61, 0x8000
	global_load_lds_dwordx4 v179, s[50:51]
	s_add_u32 s50, s48, s40
	s_addc_u32 s51, s49, s41
	s_add_u32 m0, s61, 0xa000
	global_load_lds_dwordx4 v179, s[50:51]
	s_add_u32 s50, s48, s42
	s_addc_u32 s51, s49, s43
	s_add_u32 m0, s61, 0xc000
	global_load_lds_dwordx4 v179, s[50:51]
	s_add_u32 s50, s48, s44
	s_addc_u32 s51, s49, s45
	s_add_u32 m0, s61, 0xe000
	global_load_lds_dwordx4 v179, s[50:51]
	s_branch .Lg7_entry
.Lg7_top:
	s_waitcnt lgkmcnt(0)
	s_waitcnt vmcnt(0)
	s_barrier
	v_xor_b32_e32 v141, 0x10000, v141
	v_xor_b32_e32 v210, 0x10000, v210
	v_xor_b32_e32 v180, 0x10000, v180
	v_xor_b32_e32 v211, 0x10000, v211
	s_xor_b32 s61, s61, 0x10000
	ds_read_b128 v[142:145], v141
	ds_read_b128 v[146:149], v141 offset:2048
	ds_read_b128 v[150:153], v141 offset:4096
	ds_read_b128 v[154:157], v141 offset:6144
	ds_read_b128 v[174:177], v210 offset:32768
	ds_read_b128 v[182:185], v210 offset:34816
	ds_read_b128 v[186:189], v210 offset:36864
	ds_read_b128 v[190:193], v210 offset:38912
	v_mfma_f32_16x16x32_bf16 v[60:63], v[158:161], v[194:197], v[60:63]
	v_mfma_f32_16x16x32_bf16 v[56:59], v[158:161], v[198:201], v[56:59]
	s_add_u32 s50, s48, s14
	s_addc_u32 s51, s49, s15
	s_mov_b32 m0, s61
	global_load_lds_dwordx4 v178, s[50:51]
	v_mfma_f32_16x16x32_bf16 v[52:55], v[158:161], v[202:205], v[52:55]
	v_mfma_f32_16x16x32_bf16 v[48:51], v[158:161], v[206:209], v[48:51]
	s_add_u32 s50, s48, s16
	s_addc_u32 s51, s49, s17
	s_add_u32 m0, s61, 0x2000
	global_load_lds_dwordx4 v178, s[50:51]
	v_mfma_f32_16x16x32_bf16 v[44:47], v[162:165], v[194:197], v[44:47]
	v_mfma_f32_16x16x32_bf16 v[32:35], v[162:165], v[198:201], v[32:35]
	s_add_u32 s50, s48, s18
	s_addc_u32 s51, s49, s19
	s_add_u32 m0, s61, 0x4000
	global_load_lds_dwordx4 v178, s[50:51]
	v_mfma_f32_16x16x32_bf16 v[28:31], v[162:165], v[202:205], v[28:31]
	v_mfma_f32_16x16x32_bf16 v[24:27], v[162:165], v[206:209], v[24:27]
	s_add_u32 s50, s48, s22
	s_addc_u32 s51, s49, s23
	s_add_u32 m0, s61, 0x6000
	global_load_lds_dwordx4 v178, s[50:51]
	v_mfma_f32_16x16x32_bf16 v[20:23], v[166:169], v[194:197], v[20:23]
	v_mfma_f32_16x16x32_bf16 v[16:19], v[166:169], v[198:201], v[16:19]
	s_add_u32 s50, s48, s36
	s_addc_u32 s51, s49, s37
	s_add_u32 m0, s61, 0x8000
	global_load_lds_dwordx4 v179, s[50:51]
	v_mfma_f32_16x16x32_bf16 v[12:15], v[166:169], v[202:205], v[12:15]
	v_mfma_f32_16x16x32_bf16 v[8:11], v[166:169], v[206:209], v[8:11]
	s_add_u32 s50, s48, s40
	s_addc_u32 s51, s49, s41
	s_add_u32 m0, s61, 0xa000
	global_load_lds_dwordx4 v179, s[50:51]
	v_mfma_f32_16x16x32_bf16 v[4:7], v[170:173], v[194:197], v[4:7]
	v_mfma_f32_16x16x32_bf16 v[0:3], v[170:173], v[198:201], v[0:3]
	s_add_u32 s50, s48, s42
	s_addc_u32 s51, s49, s43
	s_add_u32 m0, s61, 0xc000
	global_load_lds_dwordx4 v179, s[50:51]
	v_mfma_f32_16x16x32_bf16 v[40:43], v[170:173], v[202:205], v[40:43]
	v_mfma_f32_16x16x32_bf16 v[36:39], v[170:173], v[206:209], v[36:39]
	s_add_u32 s50, s48, s44
	s_addc_u32 s51, s49, s45
	s_add_u32 m0, s61, 0xe000
	global_load_lds_dwordx4 v179, s[50:51]
.Lg7_entry:
	ds_read_b128 v[158:161], v141 offset:8192
	ds_read_b128 v[162:165], v141 offset:10240
	ds_read_b128 v[166:169], v141 offset:12288
	ds_read_b128 v[170:173], v141 offset:14336
	s_waitcnt lgkmcnt(4)
	v_mfma_f32_16x16x32_bf16 v[124:127], v[142:145], v[174:177], v[124:127]
	v_mfma_f32_16x16x32_bf16 v[120:123], v[142:145], v[182:185], v[120:123]
	v_mfma_f32_16x16x32_bf16 v[116:119], v[142:145], v[186:189], v[116:119]
	v_mfma_f32_16x16x32_bf16 v[112:115], v[142:145], v[190:193], v[112:115]
	v_mfma_f32_16x16x32_bf16 v[108:111], v[146:149], v[174:177], v[108:111]
	v_mfma_f32_16x16x32_bf16 v[104:107], v[146:149], v[182:185], v[104:107]
	v_mfma_f32_16x16x32_bf16 v[100:103], v[146:149], v[186:189], v[100:103]
	v_mfma_f32_16x16x32_bf16 v[96:99], v[146:149], v[190:193], v[96:99]
	v_mfma_f32_16x16x32_bf16 v[92:95], v[150:153], v[174:177], v[92:95]
	v_mfma_f32_16x16x32_bf16 v[88:91], v[150:153], v[182:185], v[88:91]
	v_mfma_f32_16x16x32_bf16 v[84:87], v[150:153], v[186:189], v[84:87]
	v_mfma_f32_16x16x32_bf16 v[80:83], v[150:153], v[190:193], v[80:83]
	v_mfma_f32_16x16x32_bf16 v[76:79], v[154:157], v[174:177], v[76:79]
	v_mfma_f32_16x16x32_bf16 v[72:75], v[154:157], v[182:185], v[72:75]
	v_mfma_f32_16x16x32_bf16 v[68:71], v[154:157], v[186:189], v[68:71]
	v_mfma_f32_16x16x32_bf16 v[64:67], v[154:157], v[190:193], v[64:67]
	ds_read_b128 v[142:145], v180
	ds_read_b128 v[146:149], v180 offset:2048
	ds_read_b128 v[150:153], v180 offset:4096
	ds_read_b128 v[154:157], v180 offset:6144
	ds_read_b128 v[194:197], v211 offset:32768
	ds_read_b128 v[198:201], v211 offset:34816
	ds_read_b128 v[202:205], v211 offset:36864
	ds_read_b128 v[206:209], v211 offset:38912
	s_waitcnt lgkmcnt(8)
	v_mfma_f32_16x16x32_bf16 v[60:63], v[158:161], v[174:177], v[60:63]
	v_mfma_f32_16x16x32_bf16 v[56:59], v[158:161], v[182:185], v[56:59]
	v_mfma_f32_16x16x32_bf16 v[52:55], v[158:161], v[186:189], v[52:55]
	v_mfma_f32_16x16x32_bf16 v[48:51], v[158:161], v[190:193], v[48:51]
	v_mfma_f32_16x16x32_bf16 v[44:47], v[162:165], v[174:177], v[44:47]
	v_mfma_f32_16x16x32_bf16 v[32:35], v[162:165], v[182:185], v[32:35]
	v_mfma_f32_16x16x32_bf16 v[28:31], v[162:165], v[186:189], v[28:31]
	v_mfma_f32_16x16x32_bf16 v[24:27], v[162:165], v[190:193], v[24:27]
	v_mfma_f32_16x16x32_bf16 v[20:23], v[166:169], v[174:177], v[20:23]
	v_mfma_f32_16x16x32_bf16 v[16:19], v[166:169], v[182:185], v[16:19]
	v_mfma_f32_16x16x32_bf16 v[12:15], v[166:169], v[186:189], v[12:15]
	v_mfma_f32_16x16x32_bf16 v[8:11], v[166:169], v[190:193], v[8:11]
	v_mfma_f32_16x16x32_bf16 v[4:7], v[170:173], v[174:177], v[4:7]
	v_mfma_f32_16x16x32_bf16 v[0:3], v[170:173], v[182:185], v[0:3]
	v_mfma_f32_16x16x32_bf16 v[40:43], v[170:173], v[186:189], v[40:43]
	v_mfma_f32_16x16x32_bf16 v[36:39], v[170:173], v[190:193], v[36:39]
	ds_read_b128 v[158:161], v180 offset:8192
	ds_read_b128 v[162:165], v180 offset:10240
	ds_read_b128 v[166:169], v180 offset:12288
	ds_read_b128 v[170:173], v180 offset:14336
	s_waitcnt lgkmcnt(4)
	v_mfma_f32_16x16x32_bf16 v[124:127], v[142:145], v[194:197], v[124:127]
	v_mfma_f32_16x16x32_bf16 v[120:123], v[142:145], v[198:201], v[120:123]
	v_mfma_f32_16x16x32_bf16 v[116:119], v[142:145], v[202:205], v[116:119]
	v_mfma_f32_16x16x32_bf16 v[112:115], v[142:145], v[206:209], v[112:115]
	v_mfma_f32_16x16x32_bf16 v[108:111], v[146:149], v[194:197], v[108:111]
	v_mfma_f32_16x16x32_bf16 v[104:107], v[146:149], v[198:201], v[104:107]
	v_mfma_f32_16x16x32_bf16 v[100:103], v[146:149], v[202:205], v[100:103]
	v_mfma_f32_16x16x32_bf16 v[96:99], v[146:149], v[206:209], v[96:99]
	v_mfma_f32_16x16x32_bf16 v[92:95], v[150:153], v[194:197], v[92:95]
	v_mfma_f32_16x16x32_bf16 v[88:91], v[150:153], v[198:201], v[88:91]
	v_mfma_f32_16x16x32_bf16 v[84:87], v[150:153], v[202:205], v[84:87]
	v_mfma_f32_16x16x32_bf16 v[80:83], v[150:153], v[206:209], v[80:83]
	v_mfma_f32_16x16x32_bf16 v[76:79], v[154:157], v[194:197], v[76:79]
	v_mfma_f32_16x16x32_bf16 v[72:75], v[154:157], v[198:201], v[72:75]
	v_mfma_f32_16x16x32_bf16 v[68:71], v[154:157], v[202:205], v[68:71]
	v_mfma_f32_16x16x32_bf16 v[64:67], v[154:157], v[206:209], v[64:67]
	s_add_u32 s48, s48, 0x80
	s_addc_u32 s49, s49, 0
	s_add_i32 s47, s47, 1
	s_cmp_lt_u32 s47, 31
	s_cbranch_scc1 .Lg7_top
	s_waitcnt lgkmcnt(0)
	s_waitcnt vmcnt(0)
	s_barrier
	v_xor_b32_e32 v141, 0x10000, v141
	v_xor_b32_e32 v210, 0x10000, v210
	v_xor_b32_e32 v180, 0x10000, v180
	v_xor_b32_e32 v211, 0x10000, v211
	s_xor_b32 s61, s61, 0x10000
	ds_read_b128 v[142:145], v141
	ds_read_b128 v[146:149], v141 offset:2048
	ds_read_b128 v[150:153], v141 offset:4096
	ds_read_b128 v[154:157], v141 offset:6144
	ds_read_b128 v[174:177], v210 offset:32768
	ds_read_b128 v[182:185], v210 offset:34816
	ds_read_b128 v[186:189], v210 offset:36864
	ds_read_b128 v[190:193], v210 offset:38912
	v_mfma_f32_16x16x32_bf16 v[60:63], v[158:161], v[194:197], v[60:63]
	v_mfma_f32_16x16x32_bf16 v[56:59], v[158:161], v[198:201], v[56:59]
	v_mfma_f32_16x16x32_bf16 v[52:55], v[158:161], v[202:205], v[52:55]
	v_mfma_f32_16x16x32_bf16 v[48:51], v[158:161], v[206:209], v[48:51]
	v_mfma_f32_16x16x32_bf16 v[44:47], v[162:165], v[194:197], v[44:47]
	v_mfma_f32_16x16x32_bf16 v[32:35], v[162:165], v[198:201], v[32:35]
	v_mfma_f32_16x16x32_bf16 v[28:31], v[162:165], v[202:205], v[28:31]
	v_mfma_f32_16x16x32_bf16 v[24:27], v[162:165], v[206:209], v[24:27]
	v_mfma_f32_16x16x32_bf16 v[20:23], v[166:169], v[194:197], v[20:23]
	v_mfma_f32_16x16x32_bf16 v[16:19], v[166:169], v[198:201], v[16:19]
	v_mfma_f32_16x16x32_bf16 v[12:15], v[166:169], v[202:205], v[12:15]
	v_mfma_f32_16x16x32_bf16 v[8:11], v[166:169], v[206:209], v[8:11]
	v_mfma_f32_16x16x32_bf16 v[4:7], v[170:173], v[194:197], v[4:7]
	v_mfma_f32_16x16x32_bf16 v[0:3], v[170:173], v[198:201], v[0:3]
	v_mfma_f32_16x16x32_bf16 v[40:43], v[170:173], v[202:205], v[40:43]
	v_mfma_f32_16x16x32_bf16 v[36:39], v[170:173], v[206:209], v[36:39]
	ds_read_b128 v[158:161], v141 offset:8192
	ds_read_b128 v[162:165], v141 offset:10240
	ds_read_b128 v[166:169], v141 offset:12288
	ds_read_b128 v[170:173], v141 offset:14336
	s_waitcnt lgkmcnt(4)
	v_mfma_f32_16x16x32_bf16 v[124:127], v[142:145], v[174:177], v[124:127]
	v_mfma_f32_16x16x32_bf16 v[120:123], v[142:145], v[182:185], v[120:123]
	v_mfma_f32_16x16x32_bf16 v[116:119], v[142:145], v[186:189], v[116:119]
	v_mfma_f32_16x16x32_bf16 v[112:115], v[142:145], v[190:193], v[112:115]
	v_mfma_f32_16x16x32_bf16 v[108:111], v[146:149], v[174:177], v[108:111]
	v_mfma_f32_16x16x32_bf16 v[104:107], v[146:149], v[182:185], v[104:107]
	v_mfma_f32_16x16x32_bf16 v[100:103], v[146:149], v[186:189], v[100:103]
	v_mfma_f32_16x16x32_bf16 v[96:99], v[146:149], v[190:193], v[96:99]
	v_mfma_f32_16x16x32_bf16 v[92:95], v[150:153], v[174:177], v[92:95]
	v_mfma_f32_16x16x32_bf16 v[88:91], v[150:153], v[182:185], v[88:91]
	v_mfma_f32_16x16x32_bf16 v[84:87], v[150:153], v[186:189], v[84:87]
	v_mfma_f32_16x16x32_bf16 v[80:83], v[150:153], v[190:193], v[80:83]
	v_mfma_f32_16x16x32_bf16 v[76:79], v[154:157], v[174:177], v[76:79]
	v_mfma_f32_16x16x32_bf16 v[72:75], v[154:157], v[182:185], v[72:75]
	v_mfma_f32_16x16x32_bf16 v[68:71], v[154:157], v[186:189], v[68:71]
	v_mfma_f32_16x16x32_bf16 v[64:67], v[154:157], v[190:193], v[64:67]
	ds_read_b128 v[142:145], v180
	ds_read_b128 v[146:149], v180 offset:2048
	ds_read_b128 v[150:153], v180 offset:4096
	ds_read_b128 v[154:157], v180 offset:6144
	ds_read_b128 v[194:197], v211 offset:32768
	ds_read_b128 v[198:201], v211 offset:34816
	ds_read_b128 v[202:205], v211 offset:36864
	ds_read_b128 v[206:209], v211 offset:38912
	s_waitcnt lgkmcnt(8)
	v_mfma_f32_16x16x32_bf16 v[60:63], v[158:161], v[174:177], v[60:63]
	v_mfma_f32_16x16x32_bf16 v[56:59], v[158:161], v[182:185], v[56:59]
	v_mfma_f32_16x16x32_bf16 v[52:55], v[158:161], v[186:189], v[52:55]
	v_mfma_f32_16x16x32_bf16 v[48:51], v[158:161], v[190:193], v[48:51]
	v_mfma_f32_16x16x32_bf16 v[44:47], v[162:165], v[174:177], v[44:47]
	v_mfma_f32_16x16x32_bf16 v[32:35], v[162:165], v[182:185], v[32:35]
	v_mfma_f32_16x16x32_bf16 v[28:31], v[162:165], v[186:189], v[28:31]
	v_mfma_f32_16x16x32_bf16 v[24:27], v[162:165], v[190:193], v[24:27]
	v_mfma_f32_16x16x32_bf16 v[20:23], v[166:169], v[174:177], v[20:23]
	v_mfma_f32_16x16x32_bf16 v[16:19], v[166:169], v[182:185], v[16:19]
	v_mfma_f32_16x16x32_bf16 v[12:15], v[166:169], v[186:189], v[12:15]
	v_mfma_f32_16x16x32_bf16 v[8:11], v[166:169], v[190:193], v[8:11]
	v_mfma_f32_16x16x32_bf16 v[4:7], v[170:173], v[174:177], v[4:7]
	v_mfma_f32_16x16x32_bf16 v[0:3], v[170:173], v[182:185], v[0:3]
	v_mfma_f32_16x16x32_bf16 v[40:43], v[170:173], v[186:189], v[40:43]
	v_mfma_f32_16x16x32_bf16 v[36:39], v[170:173], v[190:193], v[36:39]
	ds_read_b128 v[158:161], v180 offset:8192
	ds_read_b128 v[162:165], v180 offset:10240
	ds_read_b128 v[166:169], v180 offset:12288
	ds_read_b128 v[170:173], v180 offset:14336
	s_waitcnt lgkmcnt(4)
	v_mfma_f32_16x16x32_bf16 v[124:127], v[142:145], v[194:197], v[124:127]
	v_mfma_f32_16x16x32_bf16 v[120:123], v[142:145], v[198:201], v[120:123]
	v_mfma_f32_16x16x32_bf16 v[116:119], v[142:145], v[202:205], v[116:119]
	v_mfma_f32_16x16x32_bf16 v[112:115], v[142:145], v[206:209], v[112:115]
	v_mfma_f32_16x16x32_bf16 v[108:111], v[146:149], v[194:197], v[108:111]
	v_mfma_f32_16x16x32_bf16 v[104:107], v[146:149], v[198:201], v[104:107]
	v_mfma_f32_16x16x32_bf16 v[100:103], v[146:149], v[202:205], v[100:103]
	v_mfma_f32_16x16x32_bf16 v[96:99], v[146:149], v[206:209], v[96:99]
	v_mfma_f32_16x16x32_bf16 v[92:95], v[150:153], v[194:197], v[92:95]
	v_mfma_f32_16x16x32_bf16 v[88:91], v[150:153], v[198:201], v[88:91]
	v_mfma_f32_16x16x32_bf16 v[84:87], v[150:153], v[202:205], v[84:87]
	v_mfma_f32_16x16x32_bf16 v[80:83], v[150:153], v[206:209], v[80:83]
	v_mfma_f32_16x16x32_bf16 v[76:79], v[154:157], v[194:197], v[76:79]
	v_mfma_f32_16x16x32_bf16 v[72:75], v[154:157], v[198:201], v[72:75]
	v_mfma_f32_16x16x32_bf16 v[68:71], v[154:157], v[202:205], v[68:71]
	v_mfma_f32_16x16x32_bf16 v[64:67], v[154:157], v[206:209], v[64:67]
	s_add_u32 s48, s48, 0x80
	s_addc_u32 s49, s49, 0
	s_add_i32 s47, s47, 1
	s_waitcnt lgkmcnt(0)
	s_waitcnt vmcnt(0)
	s_barrier
	v_mfma_f32_16x16x32_bf16 v[60:63], v[158:161], v[194:197], v[60:63]
	v_mfma_f32_16x16x32_bf16 v[56:59], v[158:161], v[198:201], v[56:59]
	v_mfma_f32_16x16x32_bf16 v[52:55], v[158:161], v[202:205], v[52:55]
	v_mfma_f32_16x16x32_bf16 v[48:51], v[158:161], v[206:209], v[48:51]
	v_mfma_f32_16x16x32_bf16 v[44:47], v[162:165], v[194:197], v[44:47]
	v_mfma_f32_16x16x32_bf16 v[32:35], v[162:165], v[198:201], v[32:35]
	v_mfma_f32_16x16x32_bf16 v[28:31], v[162:165], v[202:205], v[28:31]
	v_mfma_f32_16x16x32_bf16 v[24:27], v[162:165], v[206:209], v[24:27]
	v_mfma_f32_16x16x32_bf16 v[20:23], v[166:169], v[194:197], v[20:23]
	v_mfma_f32_16x16x32_bf16 v[16:19], v[166:169], v[198:201], v[16:19]
	v_mfma_f32_16x16x32_bf16 v[12:15], v[166:169], v[202:205], v[12:15]
	v_mfma_f32_16x16x32_bf16 v[8:11], v[166:169], v[206:209], v[8:11]
	v_mfma_f32_16x16x32_bf16 v[4:7], v[170:173], v[194:197], v[4:7]
	v_mfma_f32_16x16x32_bf16 v[0:3], v[170:173], v[198:201], v[0:3]
	v_mfma_f32_16x16x32_bf16 v[40:43], v[170:173], v[202:205], v[40:43]
	v_mfma_f32_16x16x32_bf16 v[36:39], v[170:173], v[206:209], v[36:39]
	s_nop 7
	s_nop 7
	s_sub_u32 s48, s48, s34
	s_subb_u32 s49, s49, s35
	s_mov_b32 s61, 0x100000
	s_mov_b32 s62, 0x100000
	s_mov_b64 s[50:51], 0
	s_mov_b64 vcc, exec
	s_branch .LBB0_745

.LBB0_933:
	s_mul_hi_i32 s21, s70, 0x2e8ba2e9
	s_lshr_b32 s56, s21, 31
	s_ashr_i32 s71, s21, 4
	s_add_i32 s71, s71, s56
	s_and_b32 s20, s70, 7
	s_lshl_b32 s62, s71, 3
	s_or_b32 s58, s62, s20
	s_ashr_i32 s20, s70, 3
	s_mul_hi_i32 s21, s20, 0x2e8ba2e9
	v_mov_b32_e32 v6, v181
	s_lshr_b32 s56, s21, 31
	s_ashr_i32 s21, s21, 1
	s_add_i32 s21, s21, s56
	v_lshrrev_b32_e32 v7, 4, v6
	v_lshlrev_b32_e32 v1, 6, v6
	v_xor_b32_e32 v0, v7, v6
	v_and_b32_e32 v8, 0x3c0, v1
	v_lshlrev_b32_e32 v1, 7, v6
	s_mul_i32 s21, s21, 11
	s_ashr_i32 s59, s58, 31
	v_lshlrev_b32_e32 v0, 3, v0
	v_and_b32_e32 v1, 0xfffffc00, v1
	s_and_b32 s64, s69, 7
	s_sub_i32 s56, s20, s21
	s_lshl_b64 s[20:21], s[58:59], 19
	v_and_or_b32 v0, v0, 56, v1
	s_add_u32 s20, s3, s20
	v_ashrrev_i32_e32 v1, 31, v0
	s_addc_u32 s21, s66, s21
	v_lshlrev_b64 v[0:1], 1, v[0:1]
	v_lshl_add_u32 v130, v6, 4, 0
	v_lshl_add_u64 v[2:3], s[20:21], 0, v[0:1]
	v_readfirstlane_b32 s20, v130
	v_add_u32_e32 v9, 0x2000, v130
	s_mov_b32 m0, s20
	v_readfirstlane_b32 s20, v9
	v_add_u32_e32 v9, 0x4000, v130
	s_waitcnt vmcnt(63) expcnt(7) lgkmcnt(15)
	s_barrier
	global_load_lds_dwordx4 v[2:3], off
	v_lshl_add_u64 v[4:5], v[2:3], 0, s[14:15]
	s_mov_b32 m0, s20
	v_readfirstlane_b32 s20, v9
	global_load_lds_dwordx4 v[4:5], off
	v_lshl_add_u64 v[4:5], v[2:3], 0, s[16:17]
	s_mov_b32 m0, s20
	s_ashr_i32 s57, s56, 31
	global_load_lds_dwordx4 v[4:5], off
	v_add_u32_e32 v4, 0x6000, v130
	s_lshl_b64 s[60:61], s[56:57], 19
	v_readfirstlane_b32 s20, v4
	v_lshl_add_u64 v[2:3], v[2:3], 0, s[18:19]
	s_mov_b32 m0, s20
	s_add_u32 s60, s34, s60
	global_load_lds_dwordx4 v[2:3], off
	v_add_u32_e32 v2, 0x8000, v130
	s_addc_u32 s61, s35, s61
	v_readfirstlane_b32 s20, v2
	v_add_u32_e32 v4, 0xa000, v130
	v_lshl_add_u64 v[140:141], s[60:61], 0, v[0:1]
	s_mov_b32 m0, s20
	v_readfirstlane_b32 s20, v4
	v_add_u32_e32 v4, 0xc000, v130
	global_load_lds_dwordx4 v[140:141], off
	v_lshl_add_u64 v[2:3], v[140:141], 0, s[14:15]
	s_mov_b32 m0, s20
	v_readfirstlane_b32 s20, v4
	v_add_u32_e32 v4, 0xe000, v130
	global_load_lds_dwordx4 v[2:3], off
	v_lshl_add_u64 v[2:3], v[140:141], 0, s[16:17]
	s_mov_b32 m0, s20
	v_readfirstlane_b32 s20, v4
	global_load_lds_dwordx4 v[2:3], off
	v_lshl_add_u64 v[2:3], v[140:141], 0, s[18:19]
	s_mov_b32 m0, s20
	v_ashrrev_i32_e32 v4, 6, v6
	global_load_lds_dwordx4 v[2:3], off
	v_lshrrev_b32_e32 v5, 30, v4
	v_add_u32_e32 v5, v4, v5
	s_or_b32 s20, s62, s64
	v_bfe_u32 v2, v6, 4, 2
	v_bfe_u32 v3, v6, 1, 3
	v_and_b32_e32 v6, 0x7fffc, v5
	s_ashr_i32 s21, s20, 31
	v_sub_u32_e32 v4, v4, v6
	s_lshl_b64 s[20:21], s[20:21], 19
	v_lshlrev_b32_e32 v150, 13, v4
	v_bitop3_b32 v4, v7, v3, 3 bitop3:0x6c
	v_bitop3_b32 v2, v2, v3, 4 bitop3:0x36
	s_add_u32 s20, s34, s20
	v_lshlrev_b32_e32 v5, 12, v5
	v_lshlrev_b32_e32 v4, 3, v4
	v_lshlrev_b32_e32 v2, 3, v2
	s_addc_u32 s21, s35, s21
	v_and_b32_e32 v149, 0xffffc000, v5
	v_lshl_add_u64 v[142:143], s[20:21], 0, v[0:1]
	s_mov_b64 s[60:61], 0
	v_lshlrev_b32_e32 v151, 1, v8
	v_lshlrev_b32_e32 v152, 1, v4
	v_lshlrev_b32_e32 v153, 1, v2
	s_mov_b32 s59, 0
	s_mov_b32 s57, 0
	v_mov_b32_e32 v40, 0
	v_mov_b32_e32 v41, v131
	v_mov_b32_e32 v42, v131
	v_mov_b32_e32 v43, v131
	v_mov_b32_e32 v48, 0
	v_mov_b32_e32 v49, v131
	v_mov_b32_e32 v50, v131
	v_mov_b32_e32 v51, v131
	v_mov_b32_e32 v0, 0
	v_mov_b32_e32 v1, v131
	v_mov_b32_e32 v2, v131
	v_mov_b32_e32 v3, v131
	v_mov_b32_e32 v4, 0
	v_mov_b32_e32 v5, v131
	v_mov_b32_e32 v6, v131
	v_mov_b32_e32 v7, v131
	v_mov_b32_e32 v8, 0
	v_mov_b32_e32 v9, v131
	v_mov_b32_e32 v10, v131
	v_mov_b32_e32 v11, v131
	v_mov_b32_e32 v12, 0
	v_mov_b32_e32 v13, v131
	v_mov_b32_e32 v14, v131
	v_mov_b32_e32 v15, v131
	v_mov_b32_e32 v16, 0
	v_mov_b32_e32 v17, v131
	v_mov_b32_e32 v18, v131
	v_mov_b32_e32 v19, v131
	v_mov_b32_e32 v20, 0
	v_mov_b32_e32 v21, v131
	v_mov_b32_e32 v22, v131
	v_mov_b32_e32 v23, v131
	v_mov_b32_e32 v24, 0
	v_mov_b32_e32 v25, v131
	v_mov_b32_e32 v26, v131
	v_mov_b32_e32 v27, v131
	v_mov_b32_e32 v28, 0
	v_mov_b32_e32 v29, v131
	v_mov_b32_e32 v30, v131
	v_mov_b32_e32 v31, v131
	v_mov_b32_e32 v32, 0
	v_mov_b32_e32 v33, v131
	v_mov_b32_e32 v34, v131
	v_mov_b32_e32 v35, v131
	v_mov_b32_e32 v36, 0
	v_mov_b32_e32 v37, v131
	v_mov_b32_e32 v38, v131
	v_mov_b32_e32 v39, v131
	v_mov_b32_e32 v44, 0
	v_mov_b32_e32 v45, v131
	v_mov_b32_e32 v46, v131
	v_mov_b32_e32 v47, v131
	v_mov_b32_e32 v52, 0
	v_mov_b32_e32 v53, v131
	v_mov_b32_e32 v54, v131
	v_mov_b32_e32 v55, v131
	v_mov_b32_e32 v56, 0
	v_mov_b32_e32 v57, v131
	v_mov_b32_e32 v58, v131
	v_mov_b32_e32 v59, v131
	v_mov_b32_e32 v60, 0
	v_mov_b32_e32 v61, v131
	v_mov_b32_e32 v62, v131
	v_mov_b32_e32 v63, v131
	v_mov_b32_e32 v64, 0
	v_mov_b32_e32 v65, v131
	v_mov_b32_e32 v66, v131
	v_mov_b32_e32 v67, v131
	v_mov_b32_e32 v68, 0
	v_mov_b32_e32 v69, v131
	v_mov_b32_e32 v70, v131
	v_mov_b32_e32 v71, v131
	v_mov_b32_e32 v72, 0
	v_mov_b32_e32 v73, v131
	v_mov_b32_e32 v74, v131
	v_mov_b32_e32 v75, v131
	v_mov_b32_e32 v76, 0
	v_mov_b32_e32 v77, v131
	v_mov_b32_e32 v78, v131
	v_mov_b32_e32 v79, v131
	v_mov_b32_e32 v80, 0
	v_mov_b32_e32 v81, v131
	v_mov_b32_e32 v82, v131
	v_mov_b32_e32 v83, v131
	v_mov_b32_e32 v84, 0
	v_mov_b32_e32 v85, v131
	v_mov_b32_e32 v86, v131
	v_mov_b32_e32 v87, v131
	v_mov_b32_e32 v88, 0
	v_mov_b32_e32 v89, v131
	v_mov_b32_e32 v90, v131
	v_mov_b32_e32 v91, v131
	v_mov_b32_e32 v92, 0
	v_mov_b32_e32 v93, v131
	v_mov_b32_e32 v94, v131
	v_mov_b32_e32 v95, v131
	v_mov_b32_e32 v96, 0
	v_mov_b32_e32 v97, v131
	v_mov_b32_e32 v98, v131
	v_mov_b32_e32 v99, v131
	v_mov_b32_e32 v100, 0
	v_mov_b32_e32 v101, v131
	v_mov_b32_e32 v102, v131
	v_mov_b32_e32 v103, v131
	v_mov_b32_e32 v104, 0
	v_mov_b32_e32 v105, v131
	v_mov_b32_e32 v106, v131
	v_mov_b32_e32 v107, v131
	v_mov_b32_e32 v108, 0
	v_mov_b32_e32 v109, v131
	v_mov_b32_e32 v110, v131
	v_mov_b32_e32 v111, v131
	v_mov_b32_e32 v112, 0
	v_mov_b32_e32 v113, v131
	v_mov_b32_e32 v114, v131
	v_mov_b32_e32 v115, v131
	v_mov_b32_e32 v116, 0
	v_mov_b32_e32 v117, v131
	v_mov_b32_e32 v118, v131
	v_mov_b32_e32 v119, v131
	v_mov_b32_e32 v120, 0
	v_mov_b32_e32 v121, v131
	v_mov_b32_e32 v122, v131
	v_mov_b32_e32 v123, v131
	v_mov_b32_e32 v124, 0
	v_mov_b32_e32 v125, v131
	v_mov_b32_e32 v126, v131
	v_mov_b32_e32 v127, v131
	s_waitcnt vmcnt(0) lgkmcnt(0)
	s_barrier
	v_add3_u32 v180, v149, v151, v152
	v_add3_u32 v223, v150, v151, v152
	v_add3_u32 v222, v149, v151, v153
	v_add3_u32 v224, v150, v151, v153
	v_readfirstlane_b32 s59, v130
	ds_read_b128 v[154:157], v180
	ds_read_b128 v[158:161], v180 offset:2048
	ds_read_b128 v[162:165], v180 offset:4096
	ds_read_b128 v[166:169], v180 offset:6144
	ds_read_b128 v[190:193], v223 offset:32768
	ds_read_b128 v[194:197], v223 offset:34816
	ds_read_b128 v[198:201], v223 offset:36864
	ds_read_b128 v[202:205], v223 offset:38912
	s_mov_b32 s57, 0
	s_mov_b64 s[60:61], s[34:35]
	v_subrev_u32_e32 v178, s34, v142
	v_subrev_u32_e32 v179, s34, v140
	s_add_u32 s59, s59, 0x10000
	s_add_u32 s62, s60, s22
	s_addc_u32 s63, s61, s23
	s_mov_b32 m0, s59
	global_load_lds_dwordx4 v178, s[62:63]
	s_add_u32 s62, s60, s36
	s_addc_u32 s63, s61, s37
	s_add_u32 m0, s59, 0x2000
	global_load_lds_dwordx4 v178, s[62:63]
	s_add_u32 s62, s60, s38
	s_addc_u32 s63, s61, s39
	s_add_u32 m0, s59, 0x4000
	global_load_lds_dwordx4 v178, s[62:63]
	s_add_u32 s62, s60, s40
	s_addc_u32 s63, s61, s41
	s_add_u32 m0, s59, 0x6000
	global_load_lds_dwordx4 v178, s[62:63]
	s_add_u32 s62, s60, s42
	s_addc_u32 s63, s61, s43
	s_add_u32 m0, s59, 0x8000
	global_load_lds_dwordx4 v179, s[62:63]
	s_add_u32 s62, s60, s44
	s_addc_u32 s63, s61, s45
	s_add_u32 m0, s59, 0xa000
	global_load_lds_dwordx4 v179, s[62:63]
	s_add_u32 s62, s60, s46
	s_addc_u32 s63, s61, s47
	s_add_u32 m0, s59, 0xc000
	global_load_lds_dwordx4 v179, s[62:63]
	s_add_u32 s62, s60, s48
	s_addc_u32 s63, s61, s49
	s_add_u32 m0, s59, 0xe000
	global_load_lds_dwordx4 v179, s[62:63]
	s_branch .Lg8_entry
.Lg8_top:
	s_waitcnt lgkmcnt(0)
	s_waitcnt vmcnt(0)
	s_barrier
	v_xor_b32_e32 v180, 0x10000, v180
	v_xor_b32_e32 v223, 0x10000, v223
	v_xor_b32_e32 v222, 0x10000, v222
	v_xor_b32_e32 v224, 0x10000, v224
	s_xor_b32 s59, s59, 0x10000
	ds_read_b128 v[154:157], v180
	ds_read_b128 v[158:161], v180 offset:2048
	ds_read_b128 v[162:165], v180 offset:4096
	ds_read_b128 v[166:169], v180 offset:6144
	ds_read_b128 v[190:193], v223 offset:32768
	ds_read_b128 v[194:197], v223 offset:34816
	ds_read_b128 v[198:201], v223 offset:36864
	ds_read_b128 v[202:205], v223 offset:38912
	v_mfma_f32_16x16x32_bf16 v[60:63], v[170:173], v[206:209], v[60:63]
	v_mfma_f32_16x16x32_bf16 v[56:59], v[170:173], v[210:213], v[56:59]
	s_add_u32 s62, s60, s22
	s_addc_u32 s63, s61, s23
	s_mov_b32 m0, s59
	global_load_lds_dwordx4 v178, s[62:63]
	v_mfma_f32_16x16x32_bf16 v[52:55], v[170:173], v[214:217], v[52:55]
	v_mfma_f32_16x16x32_bf16 v[44:47], v[170:173], v[218:221], v[44:47]
	s_add_u32 s62, s60, s36
	s_addc_u32 s63, s61, s37
	s_add_u32 m0, s59, 0x2000
	global_load_lds_dwordx4 v178, s[62:63]
	v_mfma_f32_16x16x32_bf16 v[36:39], v[174:177], v[206:209], v[36:39]
	v_mfma_f32_16x16x32_bf16 v[32:35], v[174:177], v[210:213], v[32:35]
	s_add_u32 s62, s60, s38
	s_addc_u32 s63, s61, s39
	s_add_u32 m0, s59, 0x4000
	global_load_lds_dwordx4 v178, s[62:63]
	v_mfma_f32_16x16x32_bf16 v[28:31], v[174:177], v[214:217], v[28:31]
	v_mfma_f32_16x16x32_bf16 v[24:27], v[174:177], v[218:221], v[24:27]
	s_add_u32 s62, s60, s40
	s_addc_u32 s63, s61, s41
	s_add_u32 m0, s59, 0x6000
	global_load_lds_dwordx4 v178, s[62:63]
	v_mfma_f32_16x16x32_bf16 v[20:23], v[182:185], v[206:209], v[20:23]
	v_mfma_f32_16x16x32_bf16 v[16:19], v[182:185], v[210:213], v[16:19]
	s_add_u32 s62, s60, s42
	s_addc_u32 s63, s61, s43
	s_add_u32 m0, s59, 0x8000
	global_load_lds_dwordx4 v179, s[62:63]
	v_mfma_f32_16x16x32_bf16 v[12:15], v[182:185], v[214:217], v[12:15]
	v_mfma_f32_16x16x32_bf16 v[8:11], v[182:185], v[218:221], v[8:11]
	s_add_u32 s62, s60, s44
	s_addc_u32 s63, s61, s45
	s_add_u32 m0, s59, 0xa000
	global_load_lds_dwordx4 v179, s[62:63]
	v_mfma_f32_16x16x32_bf16 v[4:7], v[186:189], v[206:209], v[4:7]
	v_mfma_f32_16x16x32_bf16 v[0:3], v[186:189], v[210:213], v[0:3]
	s_add_u32 s62, s60, s46
	s_addc_u32 s63, s61, s47
	s_add_u32 m0, s59, 0xc000
	global_load_lds_dwordx4 v179, s[62:63]
	v_mfma_f32_16x16x32_bf16 v[48:51], v[186:189], v[214:217], v[48:51]
	v_mfma_f32_16x16x32_bf16 v[40:43], v[186:189], v[218:221], v[40:43]
	s_add_u32 s62, s60, s48
	s_addc_u32 s63, s61, s49
	s_add_u32 m0, s59, 0xe000
	global_load_lds_dwordx4 v179, s[62:63]
.Lg8_entry:
	ds_read_b128 v[170:173], v180 offset:8192
	ds_read_b128 v[174:177], v180 offset:10240
	ds_read_b128 v[182:185], v180 offset:12288
	ds_read_b128 v[186:189], v180 offset:14336
	s_waitcnt lgkmcnt(4)
	v_mfma_f32_16x16x32_bf16 v[124:127], v[154:157], v[190:193], v[124:127]
	v_mfma_f32_16x16x32_bf16 v[120:123], v[154:157], v[194:197], v[120:123]
	v_mfma_f32_16x16x32_bf16 v[116:119], v[154:157], v[198:201], v[116:119]
	v_mfma_f32_16x16x32_bf16 v[112:115], v[154:157], v[202:205], v[112:115]
	v_mfma_f32_16x16x32_bf16 v[108:111], v[158:161], v[190:193], v[108:111]
	v_mfma_f32_16x16x32_bf16 v[104:107], v[158:161], v[194:197], v[104:107]
	v_mfma_f32_16x16x32_bf16 v[100:103], v[158:161], v[198:201], v[100:103]
	v_mfma_f32_16x16x32_bf16 v[96:99], v[158:161], v[202:205], v[96:99]
	v_mfma_f32_16x16x32_bf16 v[92:95], v[162:165], v[190:193], v[92:95]
	v_mfma_f32_16x16x32_bf16 v[88:91], v[162:165], v[194:197], v[88:91]
	v_mfma_f32_16x16x32_bf16 v[84:87], v[162:165], v[198:201], v[84:87]
	v_mfma_f32_16x16x32_bf16 v[80:83], v[162:165], v[202:205], v[80:83]
	v_mfma_f32_16x16x32_bf16 v[76:79], v[166:169], v[190:193], v[76:79]
	v_mfma_f32_16x16x32_bf16 v[72:75], v[166:169], v[194:197], v[72:75]
	v_mfma_f32_16x16x32_bf16 v[68:71], v[166:169], v[198:201], v[68:71]
	v_mfma_f32_16x16x32_bf16 v[64:67], v[166:169], v[202:205], v[64:67]
	ds_read_b128 v[154:157], v222
	ds_read_b128 v[158:161], v222 offset:2048
	ds_read_b128 v[162:165], v222 offset:4096
	ds_read_b128 v[166:169], v222 offset:6144
	ds_read_b128 v[206:209], v224 offset:32768
	ds_read_b128 v[210:213], v224 offset:34816
	ds_read_b128 v[214:217], v224 offset:36864
	ds_read_b128 v[218:221], v224 offset:38912
	s_waitcnt lgkmcnt(8)
	v_mfma_f32_16x16x32_bf16 v[60:63], v[170:173], v[190:193], v[60:63]
	v_mfma_f32_16x16x32_bf16 v[56:59], v[170:173], v[194:197], v[56:59]
	v_mfma_f32_16x16x32_bf16 v[52:55], v[170:173], v[198:201], v[52:55]
	v_mfma_f32_16x16x32_bf16 v[44:47], v[170:173], v[202:205], v[44:47]
	v_mfma_f32_16x16x32_bf16 v[36:39], v[174:177], v[190:193], v[36:39]
	v_mfma_f32_16x16x32_bf16 v[32:35], v[174:177], v[194:197], v[32:35]
	v_mfma_f32_16x16x32_bf16 v[28:31], v[174:177], v[198:201], v[28:31]
	v_mfma_f32_16x16x32_bf16 v[24:27], v[174:177], v[202:205], v[24:27]
	v_mfma_f32_16x16x32_bf16 v[20:23], v[182:185], v[190:193], v[20:23]
	v_mfma_f32_16x16x32_bf16 v[16:19], v[182:185], v[194:197], v[16:19]
	v_mfma_f32_16x16x32_bf16 v[12:15], v[182:185], v[198:201], v[12:15]
	v_mfma_f32_16x16x32_bf16 v[8:11], v[182:185], v[202:205], v[8:11]
	v_mfma_f32_16x16x32_bf16 v[4:7], v[186:189], v[190:193], v[4:7]
	v_mfma_f32_16x16x32_bf16 v[0:3], v[186:189], v[194:197], v[0:3]
	v_mfma_f32_16x16x32_bf16 v[48:51], v[186:189], v[198:201], v[48:51]
	v_mfma_f32_16x16x32_bf16 v[40:43], v[186:189], v[202:205], v[40:43]
	ds_read_b128 v[170:173], v222 offset:8192
	ds_read_b128 v[174:177], v222 offset:10240
	ds_read_b128 v[182:185], v222 offset:12288
	ds_read_b128 v[186:189], v222 offset:14336
	s_waitcnt lgkmcnt(4)
	v_mfma_f32_16x16x32_bf16 v[124:127], v[154:157], v[206:209], v[124:127]
	v_mfma_f32_16x16x32_bf16 v[120:123], v[154:157], v[210:213], v[120:123]
	v_mfma_f32_16x16x32_bf16 v[116:119], v[154:157], v[214:217], v[116:119]
	v_mfma_f32_16x16x32_bf16 v[112:115], v[154:157], v[218:221], v[112:115]
	v_mfma_f32_16x16x32_bf16 v[108:111], v[158:161], v[206:209], v[108:111]
	v_mfma_f32_16x16x32_bf16 v[104:107], v[158:161], v[210:213], v[104:107]
	v_mfma_f32_16x16x32_bf16 v[100:103], v[158:161], v[214:217], v[100:103]
	v_mfma_f32_16x16x32_bf16 v[96:99], v[158:161], v[218:221], v[96:99]
	v_mfma_f32_16x16x32_bf16 v[92:95], v[162:165], v[206:209], v[92:95]
	v_mfma_f32_16x16x32_bf16 v[88:91], v[162:165], v[210:213], v[88:91]
	v_mfma_f32_16x16x32_bf16 v[84:87], v[162:165], v[214:217], v[84:87]
	v_mfma_f32_16x16x32_bf16 v[80:83], v[162:165], v[218:221], v[80:83]
	v_mfma_f32_16x16x32_bf16 v[76:79], v[166:169], v[206:209], v[76:79]
	v_mfma_f32_16x16x32_bf16 v[72:75], v[166:169], v[210:213], v[72:75]
	v_mfma_f32_16x16x32_bf16 v[68:71], v[166:169], v[214:217], v[68:71]
	v_mfma_f32_16x16x32_bf16 v[64:67], v[166:169], v[218:221], v[64:67]
	s_add_u32 s60, s60, 0x80
	s_addc_u32 s61, s61, 0
	s_add_i32 s57, s57, 1
	s_cmp_lt_u32 s57, 15
	s_cbranch_scc1 .Lg8_top
	s_waitcnt lgkmcnt(0)
	s_waitcnt vmcnt(0)
	s_barrier
	v_xor_b32_e32 v180, 0x10000, v180
	v_xor_b32_e32 v223, 0x10000, v223
	v_xor_b32_e32 v222, 0x10000, v222
	v_xor_b32_e32 v224, 0x10000, v224
	s_xor_b32 s59, s59, 0x10000
	ds_read_b128 v[154:157], v180
	ds_read_b128 v[158:161], v180 offset:2048
	ds_read_b128 v[162:165], v180 offset:4096
	ds_read_b128 v[166:169], v180 offset:6144
	ds_read_b128 v[190:193], v223 offset:32768
	ds_read_b128 v[194:197], v223 offset:34816
	ds_read_b128 v[198:201], v223 offset:36864
	ds_read_b128 v[202:205], v223 offset:38912
	v_mfma_f32_16x16x32_bf16 v[60:63], v[170:173], v[206:209], v[60:63]
	v_mfma_f32_16x16x32_bf16 v[56:59], v[170:173], v[210:213], v[56:59]
	v_mfma_f32_16x16x32_bf16 v[52:55], v[170:173], v[214:217], v[52:55]
	v_mfma_f32_16x16x32_bf16 v[44:47], v[170:173], v[218:221], v[44:47]
	v_mfma_f32_16x16x32_bf16 v[36:39], v[174:177], v[206:209], v[36:39]
	v_mfma_f32_16x16x32_bf16 v[32:35], v[174:177], v[210:213], v[32:35]
	v_mfma_f32_16x16x32_bf16 v[28:31], v[174:177], v[214:217], v[28:31]
	v_mfma_f32_16x16x32_bf16 v[24:27], v[174:177], v[218:221], v[24:27]
	v_mfma_f32_16x16x32_bf16 v[20:23], v[182:185], v[206:209], v[20:23]
	v_mfma_f32_16x16x32_bf16 v[16:19], v[182:185], v[210:213], v[16:19]
	v_mfma_f32_16x16x32_bf16 v[12:15], v[182:185], v[214:217], v[12:15]
	v_mfma_f32_16x16x32_bf16 v[8:11], v[182:185], v[218:221], v[8:11]
	v_mfma_f32_16x16x32_bf16 v[4:7], v[186:189], v[206:209], v[4:7]
	v_mfma_f32_16x16x32_bf16 v[0:3], v[186:189], v[210:213], v[0:3]
	v_mfma_f32_16x16x32_bf16 v[48:51], v[186:189], v[214:217], v[48:51]
	v_mfma_f32_16x16x32_bf16 v[40:43], v[186:189], v[218:221], v[40:43]
	ds_read_b128 v[170:173], v180 offset:8192
	ds_read_b128 v[174:177], v180 offset:10240
	ds_read_b128 v[182:185], v180 offset:12288
	ds_read_b128 v[186:189], v180 offset:14336
	s_waitcnt lgkmcnt(4)
	v_mfma_f32_16x16x32_bf16 v[124:127], v[154:157], v[190:193], v[124:127]
	v_mfma_f32_16x16x32_bf16 v[120:123], v[154:157], v[194:197], v[120:123]
	v_mfma_f32_16x16x32_bf16 v[116:119], v[154:157], v[198:201], v[116:119]
	v_mfma_f32_16x16x32_bf16 v[112:115], v[154:157], v[202:205], v[112:115]
	v_mfma_f32_16x16x32_bf16 v[108:111], v[158:161], v[190:193], v[108:111]
	v_mfma_f32_16x16x32_bf16 v[104:107], v[158:161], v[194:197], v[104:107]
	v_mfma_f32_16x16x32_bf16 v[100:103], v[158:161], v[198:201], v[100:103]
	v_mfma_f32_16x16x32_bf16 v[96:99], v[158:161], v[202:205], v[96:99]
	v_mfma_f32_16x16x32_bf16 v[92:95], v[162:165], v[190:193], v[92:95]
	v_mfma_f32_16x16x32_bf16 v[88:91], v[162:165], v[194:197], v[88:91]
	v_mfma_f32_16x16x32_bf16 v[84:87], v[162:165], v[198:201], v[84:87]
	v_mfma_f32_16x16x32_bf16 v[80:83], v[162:165], v[202:205], v[80:83]
	v_mfma_f32_16x16x32_bf16 v[76:79], v[166:169], v[190:193], v[76:79]
	v_mfma_f32_16x16x32_bf16 v[72:75], v[166:169], v[194:197], v[72:75]
	v_mfma_f32_16x16x32_bf16 v[68:71], v[166:169], v[198:201], v[68:71]
	v_mfma_f32_16x16x32_bf16 v[64:67], v[166:169], v[202:205], v[64:67]
	ds_read_b128 v[154:157], v222
	ds_read_b128 v[158:161], v222 offset:2048
	ds_read_b128 v[162:165], v222 offset:4096
	ds_read_b128 v[166:169], v222 offset:6144
	ds_read_b128 v[206:209], v224 offset:32768
	ds_read_b128 v[210:213], v224 offset:34816
	ds_read_b128 v[214:217], v224 offset:36864
	ds_read_b128 v[218:221], v224 offset:38912
	s_waitcnt lgkmcnt(8)
	v_mfma_f32_16x16x32_bf16 v[60:63], v[170:173], v[190:193], v[60:63]
	v_mfma_f32_16x16x32_bf16 v[56:59], v[170:173], v[194:197], v[56:59]
	v_mfma_f32_16x16x32_bf16 v[52:55], v[170:173], v[198:201], v[52:55]
	v_mfma_f32_16x16x32_bf16 v[44:47], v[170:173], v[202:205], v[44:47]
	v_mfma_f32_16x16x32_bf16 v[36:39], v[174:177], v[190:193], v[36:39]
	v_mfma_f32_16x16x32_bf16 v[32:35], v[174:177], v[194:197], v[32:35]
	v_mfma_f32_16x16x32_bf16 v[28:31], v[174:177], v[198:201], v[28:31]
	v_mfma_f32_16x16x32_bf16 v[24:27], v[174:177], v[202:205], v[24:27]
	v_mfma_f32_16x16x32_bf16 v[20:23], v[182:185], v[190:193], v[20:23]
	v_mfma_f32_16x16x32_bf16 v[16:19], v[182:185], v[194:197], v[16:19]
	v_mfma_f32_16x16x32_bf16 v[12:15], v[182:185], v[198:201], v[12:15]
	v_mfma_f32_16x16x32_bf16 v[8:11], v[182:185], v[202:205], v[8:11]
	v_mfma_f32_16x16x32_bf16 v[4:7], v[186:189], v[190:193], v[4:7]
	v_mfma_f32_16x16x32_bf16 v[0:3], v[186:189], v[194:197], v[0:3]
	v_mfma_f32_16x16x32_bf16 v[48:51], v[186:189], v[198:201], v[48:51]
	v_mfma_f32_16x16x32_bf16 v[40:43], v[186:189], v[202:205], v[40:43]
	ds_read_b128 v[170:173], v222 offset:8192
	ds_read_b128 v[174:177], v222 offset:10240
	ds_read_b128 v[182:185], v222 offset:12288
	ds_read_b128 v[186:189], v222 offset:14336
	s_waitcnt lgkmcnt(4)
	v_mfma_f32_16x16x32_bf16 v[124:127], v[154:157], v[206:209], v[124:127]
	v_mfma_f32_16x16x32_bf16 v[120:123], v[154:157], v[210:213], v[120:123]
	v_mfma_f32_16x16x32_bf16 v[116:119], v[154:157], v[214:217], v[116:119]
	v_mfma_f32_16x16x32_bf16 v[112:115], v[154:157], v[218:221], v[112:115]
	v_mfma_f32_16x16x32_bf16 v[108:111], v[158:161], v[206:209], v[108:111]
	v_mfma_f32_16x16x32_bf16 v[104:107], v[158:161], v[210:213], v[104:107]
	v_mfma_f32_16x16x32_bf16 v[100:103], v[158:161], v[214:217], v[100:103]
	v_mfma_f32_16x16x32_bf16 v[96:99], v[158:161], v[218:221], v[96:99]
	v_mfma_f32_16x16x32_bf16 v[92:95], v[162:165], v[206:209], v[92:95]
	v_mfma_f32_16x16x32_bf16 v[88:91], v[162:165], v[210:213], v[88:91]
	v_mfma_f32_16x16x32_bf16 v[84:87], v[162:165], v[214:217], v[84:87]
	v_mfma_f32_16x16x32_bf16 v[80:83], v[162:165], v[218:221], v[80:83]
	v_mfma_f32_16x16x32_bf16 v[76:79], v[166:169], v[206:209], v[76:79]
	v_mfma_f32_16x16x32_bf16 v[72:75], v[166:169], v[210:213], v[72:75]
	v_mfma_f32_16x16x32_bf16 v[68:71], v[166:169], v[214:217], v[68:71]
	v_mfma_f32_16x16x32_bf16 v[64:67], v[166:169], v[218:221], v[64:67]
	s_add_u32 s60, s60, 0x80
	s_addc_u32 s61, s61, 0
	s_add_i32 s57, s57, 1
	s_waitcnt lgkmcnt(0)
	s_waitcnt vmcnt(0)
	s_barrier
	v_mfma_f32_16x16x32_bf16 v[60:63], v[170:173], v[206:209], v[60:63]
	v_mfma_f32_16x16x32_bf16 v[56:59], v[170:173], v[210:213], v[56:59]
	v_mfma_f32_16x16x32_bf16 v[52:55], v[170:173], v[214:217], v[52:55]
	v_mfma_f32_16x16x32_bf16 v[44:47], v[170:173], v[218:221], v[44:47]
	v_mfma_f32_16x16x32_bf16 v[36:39], v[174:177], v[206:209], v[36:39]
	v_mfma_f32_16x16x32_bf16 v[32:35], v[174:177], v[210:213], v[32:35]
	v_mfma_f32_16x16x32_bf16 v[28:31], v[174:177], v[214:217], v[28:31]
	v_mfma_f32_16x16x32_bf16 v[24:27], v[174:177], v[218:221], v[24:27]
	v_mfma_f32_16x16x32_bf16 v[20:23], v[182:185], v[206:209], v[20:23]
	v_mfma_f32_16x16x32_bf16 v[16:19], v[182:185], v[210:213], v[16:19]
	v_mfma_f32_16x16x32_bf16 v[12:15], v[182:185], v[214:217], v[12:15]
	v_mfma_f32_16x16x32_bf16 v[8:11], v[182:185], v[218:221], v[8:11]
	v_mfma_f32_16x16x32_bf16 v[4:7], v[186:189], v[206:209], v[4:7]
	v_mfma_f32_16x16x32_bf16 v[0:3], v[186:189], v[210:213], v[0:3]
	v_mfma_f32_16x16x32_bf16 v[48:51], v[186:189], v[214:217], v[48:51]
	v_mfma_f32_16x16x32_bf16 v[40:43], v[186:189], v[218:221], v[40:43]
	s_nop 7
	s_nop 7
	s_sub_u32 s60, s60, s34
	s_subb_u32 s61, s61, s35
	s_mov_b32 s59, 0x80000
	s_mov_b32 s65, 0x80000
	s_mov_b64 s[62:63], 0
	s_mov_b64 vcc, exec
	s_branch .LBB0_939

.LBB0_1331:
	s_ashr_i32 s20, s58, 2
	v_mov_b32_e32 v6, v181
	s_and_b32 s4, s58, 7
	s_and_b32 s47, s20, -8
	s_or_b32 s42, s47, s4
	v_lshrrev_b32_e32 v7, 4, v6
	v_lshlrev_b32_e32 v1, 6, v6
	v_xor_b32_e32 v0, v7, v6
	v_and_b32_e32 v8, 0x3c0, v1
	v_lshlrev_b32_e32 v1, 8, v6
	s_ashr_i32 s43, s42, 31
	v_lshlrev_b32_e32 v0, 3, v0
	v_and_b32_e32 v1, 0xfffff800, v1
	s_and_b32 s46, s57, 7
	s_bfe_u32 s4, s58, 0x20003
	s_lshl_b64 s[20:21], s[42:43], 20
	v_and_or_b32 v0, v0, 56, v1
	s_add_u32 s20, s3, s20
	v_ashrrev_i32_e32 v1, 31, v0
	s_addc_u32 s21, s48, s21
	v_lshlrev_b64 v[0:1], 1, v[0:1]
	v_lshl_add_u32 v134, v6, 4, 0
	v_lshl_add_u64 v[2:3], s[20:21], 0, v[0:1]
	v_readfirstlane_b32 s20, v134
	v_add_u32_e32 v9, 0x2000, v134
	s_mov_b32 m0, s20
	v_readfirstlane_b32 s20, v9
	v_add_u32_e32 v9, 0x4000, v134
	s_waitcnt vmcnt(63) expcnt(7) lgkmcnt(15)
	s_barrier
	global_load_lds_dwordx4 v[2:3], off
	v_lshl_add_u64 v[4:5], v[2:3], 0, s[6:7]
	s_mov_b32 m0, s20
	v_readfirstlane_b32 s20, v9
	global_load_lds_dwordx4 v[4:5], off
	v_lshl_add_u64 v[4:5], v[2:3], 0, s[8:9]
	s_mov_b32 m0, s20
	s_lshl_b32 s43, s4, 20
	global_load_lds_dwordx4 v[4:5], off
	v_add_u32_e32 v4, 0x6000, v134
	s_add_u32 s44, s49, s43
	v_readfirstlane_b32 s20, v4
	v_add_u32_e32 v4, 0x8000, v134
	s_addc_u32 s45, s56, 0
	v_lshl_add_u64 v[2:3], v[2:3], 0, s[10:11]
	s_mov_b32 m0, s20
	v_readfirstlane_b32 s20, v4
	v_add_u32_e32 v9, 0xa000, v134
	global_load_lds_dwordx4 v[2:3], off
	v_lshl_add_u64 v[2:3], s[44:45], 0, v[0:1]
	s_mov_b32 m0, s20
	v_readfirstlane_b32 s20, v9
	v_add_u32_e32 v9, 0xc000, v134
	global_load_lds_dwordx4 v[2:3], off
	v_lshl_add_u64 v[4:5], v[2:3], 0, s[6:7]
	s_mov_b32 m0, s20
	v_readfirstlane_b32 s20, v9
	global_load_lds_dwordx4 v[4:5], off
	v_lshl_add_u64 v[4:5], v[2:3], 0, s[8:9]
	s_mov_b32 m0, s20
	v_lshl_add_u64 v[2:3], v[2:3], 0, s[10:11]
	global_load_lds_dwordx4 v[4:5], off
	v_add_u32_e32 v4, 0xe000, v134
	v_mov_b32_e32 v36, 0
	v_readfirstlane_b32 s20, v4
	s_mov_b32 m0, s20
	v_ashrrev_i32_e32 v4, 6, v6
	global_load_lds_dwordx4 v[2:3], off
	s_or_b32 s20, s47, s46
	v_lshrrev_b32_e32 v5, 30, v4
	s_ashr_i32 s21, s20, 31
	v_add_u32_e32 v5, v4, v5
	s_lshl_b64 s[20:21], s[20:21], 20
	v_bfe_u32 v2, v6, 4, 2
	v_bfe_u32 v3, v6, 1, 3
	v_and_b32_e32 v6, 0x7fffc, v5
	s_add_u32 s20, s34, s20
	v_sub_u32_e32 v4, v4, v6
	s_addc_u32 s21, s35, s21
	v_lshlrev_b32_e32 v136, 13, v4
	v_bitop3_b32 v4, v7, v3, 3 bitop3:0x6c
	v_bitop3_b32 v2, v2, v3, 4 bitop3:0x36
	v_lshl_add_u64 v[130:131], s[20:21], 0, v[0:1]
	s_add_u32 s20, s34, s43
	v_lshlrev_b32_e32 v5, 12, v5
	v_lshlrev_b32_e32 v4, 3, v4
	v_lshlrev_b32_e32 v2, 3, v2
	s_addc_u32 s21, s35, 0
	v_and_b32_e32 v135, 0xffffc000, v5
	v_lshl_add_u64 v[132:133], s[20:21], 0, v[0:1]
	s_mov_b64 s[44:45], 0
	v_lshlrev_b32_e32 v137, 1, v8
	v_lshlrev_b32_e32 v138, 1, v4
	v_lshlrev_b32_e32 v139, 1, v2
	s_mov_b32 s59, 0
	s_mov_b32 s43, 0
	v_mov_b32_e32 v37, v36
	v_mov_b32_e32 v38, v36
	v_mov_b32_e32 v39, v36
	v_mov_b32_e32 v40, v36
	v_mov_b32_e32 v41, v36
	v_mov_b32_e32 v42, v36
	v_mov_b32_e32 v43, v36
	v_mov_b32_e32 v0, v36
	v_mov_b32_e32 v1, v36
	v_mov_b32_e32 v2, v36
	v_mov_b32_e32 v3, v36
	v_mov_b32_e32 v4, v36
	v_mov_b32_e32 v5, v36
	v_mov_b32_e32 v6, v36
	v_mov_b32_e32 v7, v36
	v_mov_b32_e32 v8, v36
	v_mov_b32_e32 v9, v36
	v_mov_b32_e32 v10, v36
	v_mov_b32_e32 v11, v36
	v_mov_b32_e32 v12, v36
	v_mov_b32_e32 v13, v36
	v_mov_b32_e32 v14, v36
	v_mov_b32_e32 v15, v36
	v_mov_b32_e32 v16, v36
	v_mov_b32_e32 v17, v36
	v_mov_b32_e32 v18, v36
	v_mov_b32_e32 v19, v36
	v_mov_b32_e32 v20, v36
	v_mov_b32_e32 v21, v36
	v_mov_b32_e32 v22, v36
	v_mov_b32_e32 v23, v36
	v_mov_b32_e32 v24, v36
	v_mov_b32_e32 v25, v36
	v_mov_b32_e32 v26, v36
	v_mov_b32_e32 v27, v36
	v_mov_b32_e32 v28, v36
	v_mov_b32_e32 v29, v36
	v_mov_b32_e32 v30, v36
	v_mov_b32_e32 v31, v36
	v_mov_b32_e32 v32, v36
	v_mov_b32_e32 v33, v36
	v_mov_b32_e32 v34, v36
	v_mov_b32_e32 v35, v36
	v_mov_b32_e32 v44, v36
	v_mov_b32_e32 v45, v36
	v_mov_b32_e32 v46, v36
	v_mov_b32_e32 v47, v36
	v_mov_b32_e32 v48, v36
	v_mov_b32_e32 v49, v36
	v_mov_b32_e32 v50, v36
	v_mov_b32_e32 v51, v36
	v_mov_b32_e32 v52, v36
	v_mov_b32_e32 v53, v36
	v_mov_b32_e32 v54, v36
	v_mov_b32_e32 v55, v36
	v_mov_b32_e32 v56, v36
	v_mov_b32_e32 v57, v36
	v_mov_b32_e32 v58, v36
	v_mov_b32_e32 v59, v36
	v_mov_b32_e32 v60, v36
	v_mov_b32_e32 v61, v36
	v_mov_b32_e32 v62, v36
	v_mov_b32_e32 v63, v36
	v_mov_b32_e32 v64, v36
	v_mov_b32_e32 v65, v36
	v_mov_b32_e32 v66, v36
	v_mov_b32_e32 v67, v36
	v_mov_b32_e32 v68, v36
	v_mov_b32_e32 v69, v36
	v_mov_b32_e32 v70, v36
	v_mov_b32_e32 v71, v36
	v_mov_b32_e32 v72, v36
	v_mov_b32_e32 v73, v36
	v_mov_b32_e32 v74, v36
	v_mov_b32_e32 v75, v36
	v_mov_b32_e32 v76, v36
	v_mov_b32_e32 v77, v36
	v_mov_b32_e32 v78, v36
	v_mov_b32_e32 v79, v36
	v_mov_b32_e32 v80, v36
	v_mov_b32_e32 v81, v36
	v_mov_b32_e32 v82, v36
	v_mov_b32_e32 v83, v36
	v_mov_b32_e32 v84, v36
	v_mov_b32_e32 v85, v36
	v_mov_b32_e32 v86, v36
	v_mov_b32_e32 v87, v36
	v_mov_b32_e32 v88, v36
	v_mov_b32_e32 v89, v36
	v_mov_b32_e32 v90, v36
	v_mov_b32_e32 v91, v36
	v_mov_b32_e32 v92, v36
	v_mov_b32_e32 v93, v36
	v_mov_b32_e32 v94, v36
	v_mov_b32_e32 v95, v36
	v_mov_b32_e32 v96, v36
	v_mov_b32_e32 v97, v36
	v_mov_b32_e32 v98, v36
	v_mov_b32_e32 v99, v36
	v_mov_b32_e32 v100, v36
	v_mov_b32_e32 v101, v36
	v_mov_b32_e32 v102, v36
	v_mov_b32_e32 v103, v36
	v_mov_b32_e32 v104, v36
	v_mov_b32_e32 v105, v36
	v_mov_b32_e32 v106, v36
	v_mov_b32_e32 v107, v36
	v_mov_b32_e32 v108, v36
	v_mov_b32_e32 v109, v36
	v_mov_b32_e32 v110, v36
	v_mov_b32_e32 v111, v36
	v_mov_b32_e32 v112, v36
	v_mov_b32_e32 v113, v36
	v_mov_b32_e32 v114, v36
	v_mov_b32_e32 v115, v36
	v_mov_b32_e32 v116, v36
	v_mov_b32_e32 v117, v36
	v_mov_b32_e32 v118, v36
	v_mov_b32_e32 v119, v36
	v_mov_b32_e32 v120, v36
	v_mov_b32_e32 v121, v36
	v_mov_b32_e32 v122, v36
	v_mov_b32_e32 v123, v36
	v_mov_b32_e32 v124, v36
	v_mov_b32_e32 v125, v36
	v_mov_b32_e32 v126, v36
	v_mov_b32_e32 v127, v36
	s_waitcnt vmcnt(0) lgkmcnt(0)
	s_barrier
	v_add3_u32 v141, v135, v137, v138
	v_add3_u32 v210, v136, v137, v138
	v_add3_u32 v180, v135, v137, v139
	v_add3_u32 v211, v136, v137, v139
	v_readfirstlane_b32 s59, v134
	ds_read_b128 v[142:145], v141
	ds_read_b128 v[146:149], v141 offset:2048
	ds_read_b128 v[150:153], v141 offset:4096
	ds_read_b128 v[154:157], v141 offset:6144
	ds_read_b128 v[174:177], v210 offset:32768
	ds_read_b128 v[182:185], v210 offset:34816
	ds_read_b128 v[186:189], v210 offset:36864
	ds_read_b128 v[190:193], v210 offset:38912
	s_mov_b32 s43, 0
	s_mov_b64 s[44:45], s[34:35]
	v_subrev_u32_e32 v178, s34, v130
	v_subrev_u32_e32 v179, s34, v132
	s_add_u32 s59, s59, 0x10000
	s_add_u32 s46, s44, s12
	s_addc_u32 s47, s45, s13
	s_mov_b32 m0, s59
	global_load_lds_dwordx4 v178, s[46:47]
	s_add_u32 s46, s44, s14
	s_addc_u32 s47, s45, s15
	s_add_u32 m0, s59, 0x2000
	global_load_lds_dwordx4 v178, s[46:47]
	s_add_u32 s46, s44, s16
	s_addc_u32 s47, s45, s17
	s_add_u32 m0, s59, 0x4000
	global_load_lds_dwordx4 v178, s[46:47]
	s_add_u32 s46, s44, s18
	s_addc_u32 s47, s45, s19
	s_add_u32 m0, s59, 0x6000
	global_load_lds_dwordx4 v178, s[46:47]
	s_add_u32 s46, s44, s22
	s_addc_u32 s47, s45, s23
	s_add_u32 m0, s59, 0x8000
	global_load_lds_dwordx4 v179, s[46:47]
	s_add_u32 s46, s44, s36
	s_addc_u32 s47, s45, s37
	s_add_u32 m0, s59, 0xa000
	global_load_lds_dwordx4 v179, s[46:47]
	s_add_u32 s46, s44, s38
	s_addc_u32 s47, s45, s39
	s_add_u32 m0, s59, 0xc000
	global_load_lds_dwordx4 v179, s[46:47]
	s_add_u32 s46, s44, s40
	s_addc_u32 s47, s45, s41
	s_add_u32 m0, s59, 0xe000
	global_load_lds_dwordx4 v179, s[46:47]
	s_branch .Lg9_entry
.Lg9_top:
	s_waitcnt lgkmcnt(0)
	s_waitcnt vmcnt(0)
	s_barrier
	v_xor_b32_e32 v141, 0x10000, v141
	v_xor_b32_e32 v210, 0x10000, v210
	v_xor_b32_e32 v180, 0x10000, v180
	v_xor_b32_e32 v211, 0x10000, v211
	s_xor_b32 s59, s59, 0x10000
	ds_read_b128 v[142:145], v141
	ds_read_b128 v[146:149], v141 offset:2048
	ds_read_b128 v[150:153], v141 offset:4096
	ds_read_b128 v[154:157], v141 offset:6144
	ds_read_b128 v[174:177], v210 offset:32768
	ds_read_b128 v[182:185], v210 offset:34816
	ds_read_b128 v[186:189], v210 offset:36864
	ds_read_b128 v[190:193], v210 offset:38912
	v_mfma_f32_16x16x32_bf16 v[60:63], v[158:161], v[194:197], v[60:63]
	v_mfma_f32_16x16x32_bf16 v[56:59], v[158:161], v[198:201], v[56:59]
	s_add_u32 s46, s44, s12
	s_addc_u32 s47, s45, s13
	s_mov_b32 m0, s59
	global_load_lds_dwordx4 v178, s[46:47]
	v_mfma_f32_16x16x32_bf16 v[52:55], v[158:161], v[202:205], v[52:55]
	v_mfma_f32_16x16x32_bf16 v[48:51], v[158:161], v[206:209], v[48:51]
	s_add_u32 s46, s44, s14
	s_addc_u32 s47, s45, s15
	s_add_u32 m0, s59, 0x2000
	global_load_lds_dwordx4 v178, s[46:47]
	v_mfma_f32_16x16x32_bf16 v[44:47], v[162:165], v[194:197], v[44:47]
	v_mfma_f32_16x16x32_bf16 v[32:35], v[162:165], v[198:201], v[32:35]
	s_add_u32 s46, s44, s16
	s_addc_u32 s47, s45, s17
	s_add_u32 m0, s59, 0x4000
	global_load_lds_dwordx4 v178, s[46:47]
	v_mfma_f32_16x16x32_bf16 v[28:31], v[162:165], v[202:205], v[28:31]
	v_mfma_f32_16x16x32_bf16 v[24:27], v[162:165], v[206:209], v[24:27]
	s_add_u32 s46, s44, s18
	s_addc_u32 s47, s45, s19
	s_add_u32 m0, s59, 0x6000
	global_load_lds_dwordx4 v178, s[46:47]
	v_mfma_f32_16x16x32_bf16 v[20:23], v[166:169], v[194:197], v[20:23]
	v_mfma_f32_16x16x32_bf16 v[16:19], v[166:169], v[198:201], v[16:19]
	s_add_u32 s46, s44, s22
	s_addc_u32 s47, s45, s23
	s_add_u32 m0, s59, 0x8000
	global_load_lds_dwordx4 v179, s[46:47]
	v_mfma_f32_16x16x32_bf16 v[12:15], v[166:169], v[202:205], v[12:15]
	v_mfma_f32_16x16x32_bf16 v[8:11], v[166:169], v[206:209], v[8:11]
	s_add_u32 s46, s44, s36
	s_addc_u32 s47, s45, s37
	s_add_u32 m0, s59, 0xa000
	global_load_lds_dwordx4 v179, s[46:47]
	v_mfma_f32_16x16x32_bf16 v[4:7], v[170:173], v[194:197], v[4:7]
	v_mfma_f32_16x16x32_bf16 v[0:3], v[170:173], v[198:201], v[0:3]
	s_add_u32 s46, s44, s38
	s_addc_u32 s47, s45, s39
	s_add_u32 m0, s59, 0xc000
	global_load_lds_dwordx4 v179, s[46:47]
	v_mfma_f32_16x16x32_bf16 v[40:43], v[170:173], v[202:205], v[40:43]
	v_mfma_f32_16x16x32_bf16 v[36:39], v[170:173], v[206:209], v[36:39]
	s_add_u32 s46, s44, s40
	s_addc_u32 s47, s45, s41
	s_add_u32 m0, s59, 0xe000
	global_load_lds_dwordx4 v179, s[46:47]
.Lg9_entry:
	ds_read_b128 v[158:161], v141 offset:8192
	ds_read_b128 v[162:165], v141 offset:10240
	ds_read_b128 v[166:169], v141 offset:12288
	ds_read_b128 v[170:173], v141 offset:14336
	s_waitcnt lgkmcnt(4)
	v_mfma_f32_16x16x32_bf16 v[124:127], v[142:145], v[174:177], v[124:127]
	v_mfma_f32_16x16x32_bf16 v[120:123], v[142:145], v[182:185], v[120:123]
	v_mfma_f32_16x16x32_bf16 v[116:119], v[142:145], v[186:189], v[116:119]
	v_mfma_f32_16x16x32_bf16 v[112:115], v[142:145], v[190:193], v[112:115]
	v_mfma_f32_16x16x32_bf16 v[108:111], v[146:149], v[174:177], v[108:111]
	v_mfma_f32_16x16x32_bf16 v[104:107], v[146:149], v[182:185], v[104:107]
	v_mfma_f32_16x16x32_bf16 v[100:103], v[146:149], v[186:189], v[100:103]
	v_mfma_f32_16x16x32_bf16 v[96:99], v[146:149], v[190:193], v[96:99]
	v_mfma_f32_16x16x32_bf16 v[92:95], v[150:153], v[174:177], v[92:95]
	v_mfma_f32_16x16x32_bf16 v[88:91], v[150:153], v[182:185], v[88:91]
	v_mfma_f32_16x16x32_bf16 v[84:87], v[150:153], v[186:189], v[84:87]
	v_mfma_f32_16x16x32_bf16 v[80:83], v[150:153], v[190:193], v[80:83]
	v_mfma_f32_16x16x32_bf16 v[76:79], v[154:157], v[174:177], v[76:79]
	v_mfma_f32_16x16x32_bf16 v[72:75], v[154:157], v[182:185], v[72:75]
	v_mfma_f32_16x16x32_bf16 v[68:71], v[154:157], v[186:189], v[68:71]
	v_mfma_f32_16x16x32_bf16 v[64:67], v[154:157], v[190:193], v[64:67]
	ds_read_b128 v[142:145], v180
	ds_read_b128 v[146:149], v180 offset:2048
	ds_read_b128 v[150:153], v180 offset:4096
	ds_read_b128 v[154:157], v180 offset:6144
	ds_read_b128 v[194:197], v211 offset:32768
	ds_read_b128 v[198:201], v211 offset:34816
	ds_read_b128 v[202:205], v211 offset:36864
	ds_read_b128 v[206:209], v211 offset:38912
	s_waitcnt lgkmcnt(8)
	v_mfma_f32_16x16x32_bf16 v[60:63], v[158:161], v[174:177], v[60:63]
	v_mfma_f32_16x16x32_bf16 v[56:59], v[158:161], v[182:185], v[56:59]
	v_mfma_f32_16x16x32_bf16 v[52:55], v[158:161], v[186:189], v[52:55]
	v_mfma_f32_16x16x32_bf16 v[48:51], v[158:161], v[190:193], v[48:51]
	v_mfma_f32_16x16x32_bf16 v[44:47], v[162:165], v[174:177], v[44:47]
	v_mfma_f32_16x16x32_bf16 v[32:35], v[162:165], v[182:185], v[32:35]
	v_mfma_f32_16x16x32_bf16 v[28:31], v[162:165], v[186:189], v[28:31]
	v_mfma_f32_16x16x32_bf16 v[24:27], v[162:165], v[190:193], v[24:27]
	v_mfma_f32_16x16x32_bf16 v[20:23], v[166:169], v[174:177], v[20:23]
	v_mfma_f32_16x16x32_bf16 v[16:19], v[166:169], v[182:185], v[16:19]
	v_mfma_f32_16x16x32_bf16 v[12:15], v[166:169], v[186:189], v[12:15]
	v_mfma_f32_16x16x32_bf16 v[8:11], v[166:169], v[190:193], v[8:11]
	v_mfma_f32_16x16x32_bf16 v[4:7], v[170:173], v[174:177], v[4:7]
	v_mfma_f32_16x16x32_bf16 v[0:3], v[170:173], v[182:185], v[0:3]
	v_mfma_f32_16x16x32_bf16 v[40:43], v[170:173], v[186:189], v[40:43]
	v_mfma_f32_16x16x32_bf16 v[36:39], v[170:173], v[190:193], v[36:39]
	ds_read_b128 v[158:161], v180 offset:8192
	ds_read_b128 v[162:165], v180 offset:10240
	ds_read_b128 v[166:169], v180 offset:12288
	ds_read_b128 v[170:173], v180 offset:14336
	s_waitcnt lgkmcnt(4)
	v_mfma_f32_16x16x32_bf16 v[124:127], v[142:145], v[194:197], v[124:127]
	v_mfma_f32_16x16x32_bf16 v[120:123], v[142:145], v[198:201], v[120:123]
	v_mfma_f32_16x16x32_bf16 v[116:119], v[142:145], v[202:205], v[116:119]
	v_mfma_f32_16x16x32_bf16 v[112:115], v[142:145], v[206:209], v[112:115]
	v_mfma_f32_16x16x32_bf16 v[108:111], v[146:149], v[194:197], v[108:111]
	v_mfma_f32_16x16x32_bf16 v[104:107], v[146:149], v[198:201], v[104:107]
	v_mfma_f32_16x16x32_bf16 v[100:103], v[146:149], v[202:205], v[100:103]
	v_mfma_f32_16x16x32_bf16 v[96:99], v[146:149], v[206:209], v[96:99]
	v_mfma_f32_16x16x32_bf16 v[92:95], v[150:153], v[194:197], v[92:95]
	v_mfma_f32_16x16x32_bf16 v[88:91], v[150:153], v[198:201], v[88:91]
	v_mfma_f32_16x16x32_bf16 v[84:87], v[150:153], v[202:205], v[84:87]
	v_mfma_f32_16x16x32_bf16 v[80:83], v[150:153], v[206:209], v[80:83]
	v_mfma_f32_16x16x32_bf16 v[76:79], v[154:157], v[194:197], v[76:79]
	v_mfma_f32_16x16x32_bf16 v[72:75], v[154:157], v[198:201], v[72:75]
	v_mfma_f32_16x16x32_bf16 v[68:71], v[154:157], v[202:205], v[68:71]
	v_mfma_f32_16x16x32_bf16 v[64:67], v[154:157], v[206:209], v[64:67]
	s_add_u32 s44, s44, 0x80
	s_addc_u32 s45, s45, 0
	s_add_i32 s43, s43, 1
	s_cmp_lt_u32 s43, 31
	s_cbranch_scc1 .Lg9_top
	s_waitcnt lgkmcnt(0)
	s_waitcnt vmcnt(0)
	s_barrier
	v_xor_b32_e32 v141, 0x10000, v141
	v_xor_b32_e32 v210, 0x10000, v210
	v_xor_b32_e32 v180, 0x10000, v180
	v_xor_b32_e32 v211, 0x10000, v211
	s_xor_b32 s59, s59, 0x10000
	ds_read_b128 v[142:145], v141
	ds_read_b128 v[146:149], v141 offset:2048
	ds_read_b128 v[150:153], v141 offset:4096
	ds_read_b128 v[154:157], v141 offset:6144
	ds_read_b128 v[174:177], v210 offset:32768
	ds_read_b128 v[182:185], v210 offset:34816
	ds_read_b128 v[186:189], v210 offset:36864
	ds_read_b128 v[190:193], v210 offset:38912
	v_mfma_f32_16x16x32_bf16 v[60:63], v[158:161], v[194:197], v[60:63]
	v_mfma_f32_16x16x32_bf16 v[56:59], v[158:161], v[198:201], v[56:59]
	v_mfma_f32_16x16x32_bf16 v[52:55], v[158:161], v[202:205], v[52:55]
	v_mfma_f32_16x16x32_bf16 v[48:51], v[158:161], v[206:209], v[48:51]
	v_mfma_f32_16x16x32_bf16 v[44:47], v[162:165], v[194:197], v[44:47]
	v_mfma_f32_16x16x32_bf16 v[32:35], v[162:165], v[198:201], v[32:35]
	v_mfma_f32_16x16x32_bf16 v[28:31], v[162:165], v[202:205], v[28:31]
	v_mfma_f32_16x16x32_bf16 v[24:27], v[162:165], v[206:209], v[24:27]
	v_mfma_f32_16x16x32_bf16 v[20:23], v[166:169], v[194:197], v[20:23]
	v_mfma_f32_16x16x32_bf16 v[16:19], v[166:169], v[198:201], v[16:19]
	v_mfma_f32_16x16x32_bf16 v[12:15], v[166:169], v[202:205], v[12:15]
	v_mfma_f32_16x16x32_bf16 v[8:11], v[166:169], v[206:209], v[8:11]
	v_mfma_f32_16x16x32_bf16 v[4:7], v[170:173], v[194:197], v[4:7]
	v_mfma_f32_16x16x32_bf16 v[0:3], v[170:173], v[198:201], v[0:3]
	v_mfma_f32_16x16x32_bf16 v[40:43], v[170:173], v[202:205], v[40:43]
	v_mfma_f32_16x16x32_bf16 v[36:39], v[170:173], v[206:209], v[36:39]
	ds_read_b128 v[158:161], v141 offset:8192
	ds_read_b128 v[162:165], v141 offset:10240
	ds_read_b128 v[166:169], v141 offset:12288
	ds_read_b128 v[170:173], v141 offset:14336
	s_waitcnt lgkmcnt(4)
	v_mfma_f32_16x16x32_bf16 v[124:127], v[142:145], v[174:177], v[124:127]
	v_mfma_f32_16x16x32_bf16 v[120:123], v[142:145], v[182:185], v[120:123]
	v_mfma_f32_16x16x32_bf16 v[116:119], v[142:145], v[186:189], v[116:119]
	v_mfma_f32_16x16x32_bf16 v[112:115], v[142:145], v[190:193], v[112:115]
	v_mfma_f32_16x16x32_bf16 v[108:111], v[146:149], v[174:177], v[108:111]
	v_mfma_f32_16x16x32_bf16 v[104:107], v[146:149], v[182:185], v[104:107]
	v_mfma_f32_16x16x32_bf16 v[100:103], v[146:149], v[186:189], v[100:103]
	v_mfma_f32_16x16x32_bf16 v[96:99], v[146:149], v[190:193], v[96:99]
	v_mfma_f32_16x16x32_bf16 v[92:95], v[150:153], v[174:177], v[92:95]
	v_mfma_f32_16x16x32_bf16 v[88:91], v[150:153], v[182:185], v[88:91]
	v_mfma_f32_16x16x32_bf16 v[84:87], v[150:153], v[186:189], v[84:87]
	v_mfma_f32_16x16x32_bf16 v[80:83], v[150:153], v[190:193], v[80:83]
	v_mfma_f32_16x16x32_bf16 v[76:79], v[154:157], v[174:177], v[76:79]
	v_mfma_f32_16x16x32_bf16 v[72:75], v[154:157], v[182:185], v[72:75]
	v_mfma_f32_16x16x32_bf16 v[68:71], v[154:157], v[186:189], v[68:71]
	v_mfma_f32_16x16x32_bf16 v[64:67], v[154:157], v[190:193], v[64:67]
	ds_read_b128 v[142:145], v180
	ds_read_b128 v[146:149], v180 offset:2048
	ds_read_b128 v[150:153], v180 offset:4096
	ds_read_b128 v[154:157], v180 offset:6144
	ds_read_b128 v[194:197], v211 offset:32768
	ds_read_b128 v[198:201], v211 offset:34816
	ds_read_b128 v[202:205], v211 offset:36864
	ds_read_b128 v[206:209], v211 offset:38912
	s_waitcnt lgkmcnt(8)
	v_mfma_f32_16x16x32_bf16 v[60:63], v[158:161], v[174:177], v[60:63]
	v_mfma_f32_16x16x32_bf16 v[56:59], v[158:161], v[182:185], v[56:59]
	v_mfma_f32_16x16x32_bf16 v[52:55], v[158:161], v[186:189], v[52:55]
	v_mfma_f32_16x16x32_bf16 v[48:51], v[158:161], v[190:193], v[48:51]
	v_mfma_f32_16x16x32_bf16 v[44:47], v[162:165], v[174:177], v[44:47]
	v_mfma_f32_16x16x32_bf16 v[32:35], v[162:165], v[182:185], v[32:35]
	v_mfma_f32_16x16x32_bf16 v[28:31], v[162:165], v[186:189], v[28:31]
	v_mfma_f32_16x16x32_bf16 v[24:27], v[162:165], v[190:193], v[24:27]
	v_mfma_f32_16x16x32_bf16 v[20:23], v[166:169], v[174:177], v[20:23]
	v_mfma_f32_16x16x32_bf16 v[16:19], v[166:169], v[182:185], v[16:19]
	v_mfma_f32_16x16x32_bf16 v[12:15], v[166:169], v[186:189], v[12:15]
	v_mfma_f32_16x16x32_bf16 v[8:11], v[166:169], v[190:193], v[8:11]
	v_mfma_f32_16x16x32_bf16 v[4:7], v[170:173], v[174:177], v[4:7]
	v_mfma_f32_16x16x32_bf16 v[0:3], v[170:173], v[182:185], v[0:3]
	v_mfma_f32_16x16x32_bf16 v[40:43], v[170:173], v[186:189], v[40:43]
	v_mfma_f32_16x16x32_bf16 v[36:39], v[170:173], v[190:193], v[36:39]
	ds_read_b128 v[158:161], v180 offset:8192
	ds_read_b128 v[162:165], v180 offset:10240
	ds_read_b128 v[166:169], v180 offset:12288
	ds_read_b128 v[170:173], v180 offset:14336
	s_waitcnt lgkmcnt(4)
	v_mfma_f32_16x16x32_bf16 v[124:127], v[142:145], v[194:197], v[124:127]
	v_mfma_f32_16x16x32_bf16 v[120:123], v[142:145], v[198:201], v[120:123]
	v_mfma_f32_16x16x32_bf16 v[116:119], v[142:145], v[202:205], v[116:119]
	v_mfma_f32_16x16x32_bf16 v[112:115], v[142:145], v[206:209], v[112:115]
	v_mfma_f32_16x16x32_bf16 v[108:111], v[146:149], v[194:197], v[108:111]
	v_mfma_f32_16x16x32_bf16 v[104:107], v[146:149], v[198:201], v[104:107]
	v_mfma_f32_16x16x32_bf16 v[100:103], v[146:149], v[202:205], v[100:103]
	v_mfma_f32_16x16x32_bf16 v[96:99], v[146:149], v[206:209], v[96:99]
	v_mfma_f32_16x16x32_bf16 v[92:95], v[150:153], v[194:197], v[92:95]
	v_mfma_f32_16x16x32_bf16 v[88:91], v[150:153], v[198:201], v[88:91]
	v_mfma_f32_16x16x32_bf16 v[84:87], v[150:153], v[202:205], v[84:87]
	v_mfma_f32_16x16x32_bf16 v[80:83], v[150:153], v[206:209], v[80:83]
	v_mfma_f32_16x16x32_bf16 v[76:79], v[154:157], v[194:197], v[76:79]
	v_mfma_f32_16x16x32_bf16 v[72:75], v[154:157], v[198:201], v[72:75]
	v_mfma_f32_16x16x32_bf16 v[68:71], v[154:157], v[202:205], v[68:71]
	v_mfma_f32_16x16x32_bf16 v[64:67], v[154:157], v[206:209], v[64:67]
	s_add_u32 s44, s44, 0x80
	s_addc_u32 s45, s45, 0
	s_add_i32 s43, s43, 1
	s_waitcnt lgkmcnt(0)
	s_waitcnt vmcnt(0)
	s_barrier
	v_mfma_f32_16x16x32_bf16 v[60:63], v[158:161], v[194:197], v[60:63]
	v_mfma_f32_16x16x32_bf16 v[56:59], v[158:161], v[198:201], v[56:59]
	v_mfma_f32_16x16x32_bf16 v[52:55], v[158:161], v[202:205], v[52:55]
	v_mfma_f32_16x16x32_bf16 v[48:51], v[158:161], v[206:209], v[48:51]
	v_mfma_f32_16x16x32_bf16 v[44:47], v[162:165], v[194:197], v[44:47]
	v_mfma_f32_16x16x32_bf16 v[32:35], v[162:165], v[198:201], v[32:35]
	v_mfma_f32_16x16x32_bf16 v[28:31], v[162:165], v[202:205], v[28:31]
	v_mfma_f32_16x16x32_bf16 v[24:27], v[162:165], v[206:209], v[24:27]
	v_mfma_f32_16x16x32_bf16 v[20:23], v[166:169], v[194:197], v[20:23]
	v_mfma_f32_16x16x32_bf16 v[16:19], v[166:169], v[198:201], v[16:19]
	v_mfma_f32_16x16x32_bf16 v[12:15], v[166:169], v[202:205], v[12:15]
	v_mfma_f32_16x16x32_bf16 v[8:11], v[166:169], v[206:209], v[8:11]
	v_mfma_f32_16x16x32_bf16 v[4:7], v[170:173], v[194:197], v[4:7]
	v_mfma_f32_16x16x32_bf16 v[0:3], v[170:173], v[198:201], v[0:3]
	v_mfma_f32_16x16x32_bf16 v[40:43], v[170:173], v[202:205], v[40:43]
	v_mfma_f32_16x16x32_bf16 v[36:39], v[170:173], v[206:209], v[36:39]
	s_nop 7
	s_nop 7
	s_sub_u32 s44, s44, s34
	s_subb_u32 s45, s45, s35
	s_mov_b32 s59, 0x100000
	s_mov_b32 s60, 0x100000
	s_mov_b64 s[46:47], 0
	s_mov_b64 vcc, exec
	s_branch .LBB0_1330

.LBB0_1488:
	v_mov_b32_e32 v6, v181
	s_ashr_i32 s51, s50, 6
	v_lshrrev_b32_e32 v7, 4, v6
	v_lshlrev_b32_e32 v1, 6, v6
	v_xor_b32_e32 v0, v7, v6
	v_and_b32_e32 v8, 0x3c0, v1
	v_lshlrev_b32_e32 v1, 7, v6
	s_bfe_u32 s52, s50, 0x20006
	s_and_b32 s56, s49, 63
	s_and_b32 s53, s50, 63
	s_and_b32 s20, s51, -4
	v_lshlrev_b32_e32 v0, 3, v0
	v_and_b32_e32 v1, 0xfffffc00, v1
	s_lshl_b32 s46, s56, 19
	s_or_b32 s42, s20, s52
	s_lshl_b32 s20, s53, 19
	v_and_or_b32 v0, v0, 56, v1
	s_add_u32 s20, s3, s20
	v_ashrrev_i32_e32 v1, 31, v0
	s_addc_u32 s21, s48, 0
	v_lshlrev_b64 v[0:1], 1, v[0:1]
	v_lshl_add_u32 v129, v6, 4, 0
	v_lshl_add_u64 v[2:3], s[20:21], 0, v[0:1]
	v_readfirstlane_b32 s20, v129
	v_add_u32_e32 v9, 0x2000, v129
	s_mov_b32 m0, s20
	v_readfirstlane_b32 s20, v9
	v_add_u32_e32 v9, 0x4000, v129
	s_waitcnt vmcnt(63) expcnt(7) lgkmcnt(15)
	s_barrier
	global_load_lds_dwordx4 v[2:3], off
	v_lshl_add_u64 v[4:5], v[2:3], 0, s[8:9]
	s_mov_b32 m0, s20
	v_readfirstlane_b32 s20, v9
	global_load_lds_dwordx4 v[4:5], off
	v_lshl_add_u64 v[4:5], v[2:3], 0, s[10:11]
	s_mov_b32 m0, s20
	s_ashr_i32 s43, s42, 31
	global_load_lds_dwordx4 v[4:5], off
	v_add_u32_e32 v4, 0x6000, v129
	s_lshl_b64 s[44:45], s[42:43], 19
	v_readfirstlane_b32 s20, v4
	v_lshl_add_u64 v[2:3], v[2:3], 0, s[12:13]
	s_mov_b32 m0, s20
	s_add_u32 s44, s34, s44
	global_load_lds_dwordx4 v[2:3], off
	v_add_u32_e32 v2, 0x8000, v129
	s_addc_u32 s45, s35, s45
	v_readfirstlane_b32 s20, v2
	v_add_u32_e32 v4, 0xa000, v129
	v_lshl_add_u64 v[134:135], s[44:45], 0, v[0:1]
	s_mov_b32 m0, s20
	v_readfirstlane_b32 s20, v4
	v_add_u32_e32 v4, 0xc000, v129
	global_load_lds_dwordx4 v[134:135], off
	v_lshl_add_u64 v[2:3], v[134:135], 0, s[8:9]
	s_mov_b32 m0, s20
	v_readfirstlane_b32 s20, v4
	v_add_u32_e32 v4, 0xe000, v129
	global_load_lds_dwordx4 v[2:3], off
	v_lshl_add_u64 v[2:3], v[134:135], 0, s[10:11]
	s_mov_b32 m0, s20
	v_readfirstlane_b32 s20, v4
	global_load_lds_dwordx4 v[2:3], off
	v_lshl_add_u64 v[2:3], v[134:135], 0, s[12:13]
	s_mov_b32 m0, s20
	v_ashrrev_i32_e32 v4, 6, v6
	global_load_lds_dwordx4 v[2:3], off
	v_lshrrev_b32_e32 v5, 30, v4
	v_add_u32_e32 v5, v4, v5
	v_bfe_u32 v2, v6, 4, 2
	v_bfe_u32 v3, v6, 1, 3
	v_and_b32_e32 v6, 0x7fffc, v5
	v_sub_u32_e32 v4, v4, v6
	v_lshlrev_b32_e32 v139, 13, v4
	v_bitop3_b32 v4, v7, v3, 3 bitop3:0x6c
	v_bitop3_b32 v2, v2, v3, 4 bitop3:0x36
	s_add_u32 s20, s34, s46
	v_lshlrev_b32_e32 v5, 12, v5
	v_lshlrev_b32_e32 v4, 3, v4
	v_lshlrev_b32_e32 v2, 3, v2
	s_addc_u32 s21, s35, 0
	v_and_b32_e32 v138, 0xffffc000, v5
	v_lshl_add_u64 v[136:137], s[20:21], 0, v[0:1]
	s_mov_b64 s[44:45], 0
	s_waitcnt lgkmcnt(0)
	v_lshlrev_b32_e32 v140, 1, v8
	v_lshlrev_b32_e32 v141, 1, v4
	v_lshlrev_b32_e32 v142, 1, v2
	s_mov_b32 s57, 0
	s_mov_b32 s43, 0
	v_mov_b32_e32 v8, v128
	v_mov_b32_e32 v9, v128
	v_mov_b32_e32 v10, v128
	v_mov_b32_e32 v11, v128
	v_mov_b32_e32 v20, v128
	v_mov_b32_e32 v21, v128
	v_mov_b32_e32 v22, v128
	v_mov_b32_e32 v23, v128
	v_mov_b32_e32 v0, v128
	v_mov_b32_e32 v1, v128
	v_mov_b32_e32 v2, v128
	v_mov_b32_e32 v3, v128
	v_mov_b32_e32 v4, v128
	v_mov_b32_e32 v5, v128
	v_mov_b32_e32 v6, v128
	v_mov_b32_e32 v7, v128
	v_mov_b32_e32 v12, v128
	v_mov_b32_e32 v13, v128
	v_mov_b32_e32 v14, v128
	v_mov_b32_e32 v15, v128
	v_mov_b32_e32 v24, v128
	v_mov_b32_e32 v25, v128
	v_mov_b32_e32 v26, v128
	v_mov_b32_e32 v27, v128
	v_mov_b32_e32 v16, v128
	v_mov_b32_e32 v17, v128
	v_mov_b32_e32 v18, v128
	v_mov_b32_e32 v19, v128
	v_mov_b32_e32 v28, v128
	v_mov_b32_e32 v29, v128
	v_mov_b32_e32 v30, v128
	v_mov_b32_e32 v31, v128
	v_mov_b32_e32 v32, v128
	v_mov_b32_e32 v33, v128
	v_mov_b32_e32 v34, v128
	v_mov_b32_e32 v35, v128
	v_mov_b32_e32 v40, v128
	v_mov_b32_e32 v41, v128
	v_mov_b32_e32 v42, v128
	v_mov_b32_e32 v43, v128
	v_mov_b32_e32 v36, v128
	v_mov_b32_e32 v37, v128
	v_mov_b32_e32 v38, v128
	v_mov_b32_e32 v39, v128
	v_mov_b32_e32 v44, v128
	v_mov_b32_e32 v45, v128
	v_mov_b32_e32 v46, v128
	v_mov_b32_e32 v47, v128
	v_mov_b32_e32 v48, v128
	v_mov_b32_e32 v49, v128
	v_mov_b32_e32 v50, v128
	v_mov_b32_e32 v51, v128
	v_mov_b32_e32 v56, v128
	v_mov_b32_e32 v57, v128
	v_mov_b32_e32 v58, v128
	v_mov_b32_e32 v59, v128
	v_mov_b32_e32 v52, v128
	v_mov_b32_e32 v53, v128
	v_mov_b32_e32 v54, v128
	v_mov_b32_e32 v55, v128
	v_mov_b32_e32 v60, v128
	v_mov_b32_e32 v61, v128
	v_mov_b32_e32 v62, v128
	v_mov_b32_e32 v63, v128
	v_mov_b32_e32 v64, v128
	v_mov_b32_e32 v65, v128
	v_mov_b32_e32 v66, v128
	v_mov_b32_e32 v67, v128
	v_mov_b32_e32 v72, v128
	v_mov_b32_e32 v73, v128
	v_mov_b32_e32 v74, v128
	v_mov_b32_e32 v75, v128
	v_mov_b32_e32 v68, v128
	v_mov_b32_e32 v69, v128
	v_mov_b32_e32 v70, v128
	v_mov_b32_e32 v71, v128
	v_mov_b32_e32 v76, v128
	v_mov_b32_e32 v77, v128
	v_mov_b32_e32 v78, v128
	v_mov_b32_e32 v79, v128
	v_mov_b32_e32 v80, v128
	v_mov_b32_e32 v81, v128
	v_mov_b32_e32 v82, v128
	v_mov_b32_e32 v83, v128
	v_mov_b32_e32 v88, v128
	v_mov_b32_e32 v89, v128
	v_mov_b32_e32 v90, v128
	v_mov_b32_e32 v91, v128
	v_mov_b32_e32 v84, v128
	v_mov_b32_e32 v85, v128
	v_mov_b32_e32 v86, v128
	v_mov_b32_e32 v87, v128
	v_mov_b32_e32 v92, v128
	v_mov_b32_e32 v93, v128
	v_mov_b32_e32 v94, v128
	v_mov_b32_e32 v95, v128
	v_mov_b32_e32 v96, v128
	v_mov_b32_e32 v97, v128
	v_mov_b32_e32 v98, v128
	v_mov_b32_e32 v99, v128
	v_mov_b32_e32 v104, v128
	v_mov_b32_e32 v105, v128
	v_mov_b32_e32 v106, v128
	v_mov_b32_e32 v107, v128
	v_mov_b32_e32 v100, v128
	v_mov_b32_e32 v101, v128
	v_mov_b32_e32 v102, v128
	v_mov_b32_e32 v103, v128
	v_mov_b32_e32 v108, v128
	v_mov_b32_e32 v109, v128
	v_mov_b32_e32 v110, v128
	v_mov_b32_e32 v111, v128
	v_mov_b32_e32 v112, v128
	v_mov_b32_e32 v113, v128
	v_mov_b32_e32 v114, v128
	v_mov_b32_e32 v115, v128
	v_mov_b32_e32 v120, v128
	v_mov_b32_e32 v121, v128
	v_mov_b32_e32 v122, v128
	v_mov_b32_e32 v123, v128
	v_mov_b32_e32 v116, v128
	v_mov_b32_e32 v117, v128
	v_mov_b32_e32 v118, v128
	v_mov_b32_e32 v119, v128
	v_mov_b32_e32 v124, v128
	v_mov_b32_e32 v125, v128
	v_mov_b32_e32 v126, v128
	v_mov_b32_e32 v127, v128
	s_waitcnt vmcnt(0) lgkmcnt(0)
	s_barrier
	v_add3_u32 v143, v138, v140, v141
	v_add3_u32 v180, v139, v140, v141
	v_add3_u32 v155, v138, v140, v142
	v_add3_u32 v222, v139, v140, v142
	v_readfirstlane_b32 s57, v129
	ds_read_b128 v[156:159], v143
	ds_read_b128 v[160:163], v143 offset:2048
	ds_read_b128 v[164:167], v143 offset:4096
	ds_read_b128 v[168:171], v143 offset:6144
	ds_read_b128 v[190:193], v180 offset:32768
	ds_read_b128 v[194:197], v180 offset:34816
	ds_read_b128 v[198:201], v180 offset:36864
	ds_read_b128 v[202:205], v180 offset:38912
	s_mov_b32 s43, 0
	s_mov_b64 s[44:45], s[34:35]
	v_subrev_u32_e32 v144, s34, v136
	v_subrev_u32_e32 v145, s34, v134
	s_add_u32 s57, s57, 0x10000
	s_add_u32 s46, s44, s14
	s_addc_u32 s47, s45, s15
	s_mov_b32 m0, s57
	global_load_lds_dwordx4 v144, s[46:47]
	s_add_u32 s46, s44, s16
	s_addc_u32 s47, s45, s17
	s_add_u32 m0, s57, 0x2000
	global_load_lds_dwordx4 v144, s[46:47]
	s_add_u32 s46, s44, s18
	s_addc_u32 s47, s45, s19
	s_add_u32 m0, s57, 0x4000
	global_load_lds_dwordx4 v144, s[46:47]
	s_add_u32 s46, s44, s22
	s_addc_u32 s47, s45, s23
	s_add_u32 m0, s57, 0x6000
	global_load_lds_dwordx4 v144, s[46:47]
	s_add_u32 s46, s44, s30
	s_addc_u32 s47, s45, s31
	s_add_u32 m0, s57, 0x8000
	global_load_lds_dwordx4 v145, s[46:47]
	s_add_u32 s46, s44, s36
	s_addc_u32 s47, s45, s37
	s_add_u32 m0, s57, 0xa000
	global_load_lds_dwordx4 v145, s[46:47]
	s_add_u32 s46, s44, s38
	s_addc_u32 s47, s45, s39
	s_add_u32 m0, s57, 0xc000
	global_load_lds_dwordx4 v145, s[46:47]
	s_add_u32 s46, s44, s40
	s_addc_u32 s47, s45, s41
	s_add_u32 m0, s57, 0xe000
	global_load_lds_dwordx4 v145, s[46:47]
	s_branch .Lg10_entry
.Lg10_top:
	s_waitcnt lgkmcnt(0)
	s_waitcnt vmcnt(0)
	s_barrier
	v_xor_b32_e32 v143, 0x10000, v143
	v_xor_b32_e32 v180, 0x10000, v180
	v_xor_b32_e32 v155, 0x10000, v155
	v_xor_b32_e32 v222, 0x10000, v222
	s_xor_b32 s57, s57, 0x10000
	ds_read_b128 v[156:159], v143
	ds_read_b128 v[160:163], v143 offset:2048
	ds_read_b128 v[164:167], v143 offset:4096
	ds_read_b128 v[168:171], v143 offset:6144
	ds_read_b128 v[190:193], v180 offset:32768
	ds_read_b128 v[194:197], v180 offset:34816
	ds_read_b128 v[198:201], v180 offset:36864
	ds_read_b128 v[202:205], v180 offset:38912
	v_mfma_f32_16x16x32_bf16 v[60:63], v[172:175], v[206:209], v[60:63]
	v_mfma_f32_16x16x32_bf16 v[52:55], v[172:175], v[210:213], v[52:55]
	s_add_u32 s46, s44, s14
	s_addc_u32 s47, s45, s15
	s_mov_b32 m0, s57
	global_load_lds_dwordx4 v144, s[46:47]
	v_mfma_f32_16x16x32_bf16 v[56:59], v[172:175], v[214:217], v[56:59]
	v_mfma_f32_16x16x32_bf16 v[48:51], v[172:175], v[218:221], v[48:51]
	s_add_u32 s46, s44, s16
	s_addc_u32 s47, s45, s17
	s_add_u32 m0, s57, 0x2000
	global_load_lds_dwordx4 v144, s[46:47]
	v_mfma_f32_16x16x32_bf16 v[44:47], v[176:179], v[206:209], v[44:47]
	v_mfma_f32_16x16x32_bf16 v[36:39], v[176:179], v[210:213], v[36:39]
	s_add_u32 s46, s44, s18
	s_addc_u32 s47, s45, s19
	s_add_u32 m0, s57, 0x4000
	global_load_lds_dwordx4 v144, s[46:47]
	v_mfma_f32_16x16x32_bf16 v[40:43], v[176:179], v[214:217], v[40:43]
	v_mfma_f32_16x16x32_bf16 v[32:35], v[176:179], v[218:221], v[32:35]
	s_add_u32 s46, s44, s22
	s_addc_u32 s47, s45, s23
	s_add_u32 m0, s57, 0x6000
	global_load_lds_dwordx4 v144, s[46:47]
	v_mfma_f32_16x16x32_bf16 v[28:31], v[182:185], v[206:209], v[28:31]
	v_mfma_f32_16x16x32_bf16 v[16:19], v[182:185], v[210:213], v[16:19]
	s_add_u32 s46, s44, s30
	s_addc_u32 s47, s45, s31
	s_add_u32 m0, s57, 0x8000
	global_load_lds_dwordx4 v145, s[46:47]
	v_mfma_f32_16x16x32_bf16 v[24:27], v[182:185], v[214:217], v[24:27]
	v_mfma_f32_16x16x32_bf16 v[12:15], v[182:185], v[218:221], v[12:15]
	s_add_u32 s46, s44, s36
	s_addc_u32 s47, s45, s37
	s_add_u32 m0, s57, 0xa000
	global_load_lds_dwordx4 v145, s[46:47]
	v_mfma_f32_16x16x32_bf16 v[4:7], v[186:189], v[206:209], v[4:7]
	v_mfma_f32_16x16x32_bf16 v[0:3], v[186:189], v[210:213], v[0:3]
	s_add_u32 s46, s44, s38
	s_addc_u32 s47, s45, s39
	s_add_u32 m0, s57, 0xc000
	global_load_lds_dwordx4 v145, s[46:47]
	v_mfma_f32_16x16x32_bf16 v[20:23], v[186:189], v[214:217], v[20:23]
	v_mfma_f32_16x16x32_bf16 v[8:11], v[186:189], v[218:221], v[8:11]
	s_add_u32 s46, s44, s40
	s_addc_u32 s47, s45, s41
	s_add_u32 m0, s57, 0xe000
	global_load_lds_dwordx4 v145, s[46:47]
.Lg10_entry:
	ds_read_b128 v[172:175], v143 offset:8192
	ds_read_b128 v[176:179], v143 offset:10240
	ds_read_b128 v[182:185], v143 offset:12288
	ds_read_b128 v[186:189], v143 offset:14336
	s_waitcnt lgkmcnt(4)
	v_mfma_f32_16x16x32_bf16 v[124:127], v[156:159], v[190:193], v[124:127]
	v_mfma_f32_16x16x32_bf16 v[116:119], v[156:159], v[194:197], v[116:119]
	v_mfma_f32_16x16x32_bf16 v[120:123], v[156:159], v[198:201], v[120:123]
	v_mfma_f32_16x16x32_bf16 v[112:115], v[156:159], v[202:205], v[112:115]
	v_mfma_f32_16x16x32_bf16 v[108:111], v[160:163], v[190:193], v[108:111]
	v_mfma_f32_16x16x32_bf16 v[100:103], v[160:163], v[194:197], v[100:103]
	v_mfma_f32_16x16x32_bf16 v[104:107], v[160:163], v[198:201], v[104:107]
	v_mfma_f32_16x16x32_bf16 v[96:99], v[160:163], v[202:205], v[96:99]
	v_mfma_f32_16x16x32_bf16 v[92:95], v[164:167], v[190:193], v[92:95]
	v_mfma_f32_16x16x32_bf16 v[84:87], v[164:167], v[194:197], v[84:87]
	v_mfma_f32_16x16x32_bf16 v[88:91], v[164:167], v[198:201], v[88:91]
	v_mfma_f32_16x16x32_bf16 v[80:83], v[164:167], v[202:205], v[80:83]
	v_mfma_f32_16x16x32_bf16 v[76:79], v[168:171], v[190:193], v[76:79]
	v_mfma_f32_16x16x32_bf16 v[68:71], v[168:171], v[194:197], v[68:71]
	v_mfma_f32_16x16x32_bf16 v[72:75], v[168:171], v[198:201], v[72:75]
	v_mfma_f32_16x16x32_bf16 v[64:67], v[168:171], v[202:205], v[64:67]
	ds_read_b128 v[156:159], v155
	ds_read_b128 v[160:163], v155 offset:2048
	ds_read_b128 v[164:167], v155 offset:4096
	ds_read_b128 v[168:171], v155 offset:6144
	ds_read_b128 v[206:209], v222 offset:32768
	ds_read_b128 v[210:213], v222 offset:34816
	ds_read_b128 v[214:217], v222 offset:36864
	ds_read_b128 v[218:221], v222 offset:38912
	s_waitcnt lgkmcnt(8)
	v_mfma_f32_16x16x32_bf16 v[60:63], v[172:175], v[190:193], v[60:63]
	v_mfma_f32_16x16x32_bf16 v[52:55], v[172:175], v[194:197], v[52:55]
	v_mfma_f32_16x16x32_bf16 v[56:59], v[172:175], v[198:201], v[56:59]
	v_mfma_f32_16x16x32_bf16 v[48:51], v[172:175], v[202:205], v[48:51]
	v_mfma_f32_16x16x32_bf16 v[44:47], v[176:179], v[190:193], v[44:47]
	v_mfma_f32_16x16x32_bf16 v[36:39], v[176:179], v[194:197], v[36:39]
	v_mfma_f32_16x16x32_bf16 v[40:43], v[176:179], v[198:201], v[40:43]
	v_mfma_f32_16x16x32_bf16 v[32:35], v[176:179], v[202:205], v[32:35]
	v_mfma_f32_16x16x32_bf16 v[28:31], v[182:185], v[190:193], v[28:31]
	v_mfma_f32_16x16x32_bf16 v[16:19], v[182:185], v[194:197], v[16:19]
	v_mfma_f32_16x16x32_bf16 v[24:27], v[182:185], v[198:201], v[24:27]
	v_mfma_f32_16x16x32_bf16 v[12:15], v[182:185], v[202:205], v[12:15]
	v_mfma_f32_16x16x32_bf16 v[4:7], v[186:189], v[190:193], v[4:7]
	v_mfma_f32_16x16x32_bf16 v[0:3], v[186:189], v[194:197], v[0:3]
	v_mfma_f32_16x16x32_bf16 v[20:23], v[186:189], v[198:201], v[20:23]
	v_mfma_f32_16x16x32_bf16 v[8:11], v[186:189], v[202:205], v[8:11]
	ds_read_b128 v[172:175], v155 offset:8192
	ds_read_b128 v[176:179], v155 offset:10240
	ds_read_b128 v[182:185], v155 offset:12288
	ds_read_b128 v[186:189], v155 offset:14336
	s_waitcnt lgkmcnt(4)
	v_mfma_f32_16x16x32_bf16 v[124:127], v[156:159], v[206:209], v[124:127]
	v_mfma_f32_16x16x32_bf16 v[116:119], v[156:159], v[210:213], v[116:119]
	v_mfma_f32_16x16x32_bf16 v[120:123], v[156:159], v[214:217], v[120:123]
	v_mfma_f32_16x16x32_bf16 v[112:115], v[156:159], v[218:221], v[112:115]
	v_mfma_f32_16x16x32_bf16 v[108:111], v[160:163], v[206:209], v[108:111]
	v_mfma_f32_16x16x32_bf16 v[100:103], v[160:163], v[210:213], v[100:103]
	v_mfma_f32_16x16x32_bf16 v[104:107], v[160:163], v[214:217], v[104:107]
	v_mfma_f32_16x16x32_bf16 v[96:99], v[160:163], v[218:221], v[96:99]
	v_mfma_f32_16x16x32_bf16 v[92:95], v[164:167], v[206:209], v[92:95]
	v_mfma_f32_16x16x32_bf16 v[84:87], v[164:167], v[210:213], v[84:87]
	v_mfma_f32_16x16x32_bf16 v[88:91], v[164:167], v[214:217], v[88:91]
	v_mfma_f32_16x16x32_bf16 v[80:83], v[164:167], v[218:221], v[80:83]
	v_mfma_f32_16x16x32_bf16 v[76:79], v[168:171], v[206:209], v[76:79]
	v_mfma_f32_16x16x32_bf16 v[68:71], v[168:171], v[210:213], v[68:71]
	v_mfma_f32_16x16x32_bf16 v[72:75], v[168:171], v[214:217], v[72:75]
	v_mfma_f32_16x16x32_bf16 v[64:67], v[168:171], v[218:221], v[64:67]
	s_add_u32 s44, s44, 0x80
	s_addc_u32 s45, s45, 0
	s_add_i32 s43, s43, 1
	s_cmp_lt_u32 s43, 15
	s_cbranch_scc1 .Lg10_top
	s_waitcnt lgkmcnt(0)
	s_waitcnt vmcnt(0)
	s_barrier
	v_xor_b32_e32 v143, 0x10000, v143
	v_xor_b32_e32 v180, 0x10000, v180
	v_xor_b32_e32 v155, 0x10000, v155
	v_xor_b32_e32 v222, 0x10000, v222
	s_xor_b32 s57, s57, 0x10000
	ds_read_b128 v[156:159], v143
	ds_read_b128 v[160:163], v143 offset:2048
	ds_read_b128 v[164:167], v143 offset:4096
	ds_read_b128 v[168:171], v143 offset:6144
	ds_read_b128 v[190:193], v180 offset:32768
	ds_read_b128 v[194:197], v180 offset:34816
	ds_read_b128 v[198:201], v180 offset:36864
	ds_read_b128 v[202:205], v180 offset:38912
	v_mfma_f32_16x16x32_bf16 v[60:63], v[172:175], v[206:209], v[60:63]
	v_mfma_f32_16x16x32_bf16 v[52:55], v[172:175], v[210:213], v[52:55]
	v_mfma_f32_16x16x32_bf16 v[56:59], v[172:175], v[214:217], v[56:59]
	v_mfma_f32_16x16x32_bf16 v[48:51], v[172:175], v[218:221], v[48:51]
	v_mfma_f32_16x16x32_bf16 v[44:47], v[176:179], v[206:209], v[44:47]
	v_mfma_f32_16x16x32_bf16 v[36:39], v[176:179], v[210:213], v[36:39]
	v_mfma_f32_16x16x32_bf16 v[40:43], v[176:179], v[214:217], v[40:43]
	v_mfma_f32_16x16x32_bf16 v[32:35], v[176:179], v[218:221], v[32:35]
	v_mfma_f32_16x16x32_bf16 v[28:31], v[182:185], v[206:209], v[28:31]
	v_mfma_f32_16x16x32_bf16 v[16:19], v[182:185], v[210:213], v[16:19]
	v_mfma_f32_16x16x32_bf16 v[24:27], v[182:185], v[214:217], v[24:27]
	v_mfma_f32_16x16x32_bf16 v[12:15], v[182:185], v[218:221], v[12:15]
	v_mfma_f32_16x16x32_bf16 v[4:7], v[186:189], v[206:209], v[4:7]
	v_mfma_f32_16x16x32_bf16 v[0:3], v[186:189], v[210:213], v[0:3]
	v_mfma_f32_16x16x32_bf16 v[20:23], v[186:189], v[214:217], v[20:23]
	v_mfma_f32_16x16x32_bf16 v[8:11], v[186:189], v[218:221], v[8:11]
	ds_read_b128 v[172:175], v143 offset:8192
	ds_read_b128 v[176:179], v143 offset:10240
	ds_read_b128 v[182:185], v143 offset:12288
	ds_read_b128 v[186:189], v143 offset:14336
	s_waitcnt lgkmcnt(4)
	v_mfma_f32_16x16x32_bf16 v[124:127], v[156:159], v[190:193], v[124:127]
	v_mfma_f32_16x16x32_bf16 v[116:119], v[156:159], v[194:197], v[116:119]
	v_mfma_f32_16x16x32_bf16 v[120:123], v[156:159], v[198:201], v[120:123]
	v_mfma_f32_16x16x32_bf16 v[112:115], v[156:159], v[202:205], v[112:115]
	v_mfma_f32_16x16x32_bf16 v[108:111], v[160:163], v[190:193], v[108:111]
	v_mfma_f32_16x16x32_bf16 v[100:103], v[160:163], v[194:197], v[100:103]
	v_mfma_f32_16x16x32_bf16 v[104:107], v[160:163], v[198:201], v[104:107]
	v_mfma_f32_16x16x32_bf16 v[96:99], v[160:163], v[202:205], v[96:99]
	v_mfma_f32_16x16x32_bf16 v[92:95], v[164:167], v[190:193], v[92:95]
	v_mfma_f32_16x16x32_bf16 v[84:87], v[164:167], v[194:197], v[84:87]
	v_mfma_f32_16x16x32_bf16 v[88:91], v[164:167], v[198:201], v[88:91]
	v_mfma_f32_16x16x32_bf16 v[80:83], v[164:167], v[202:205], v[80:83]
	v_mfma_f32_16x16x32_bf16 v[76:79], v[168:171], v[190:193], v[76:79]
	v_mfma_f32_16x16x32_bf16 v[68:71], v[168:171], v[194:197], v[68:71]
	v_mfma_f32_16x16x32_bf16 v[72:75], v[168:171], v[198:201], v[72:75]
	v_mfma_f32_16x16x32_bf16 v[64:67], v[168:171], v[202:205], v[64:67]
	ds_read_b128 v[156:159], v155
	ds_read_b128 v[160:163], v155 offset:2048
	ds_read_b128 v[164:167], v155 offset:4096
	ds_read_b128 v[168:171], v155 offset:6144
	ds_read_b128 v[206:209], v222 offset:32768
	ds_read_b128 v[210:213], v222 offset:34816
	ds_read_b128 v[214:217], v222 offset:36864
	ds_read_b128 v[218:221], v222 offset:38912
	s_waitcnt lgkmcnt(8)
	v_mfma_f32_16x16x32_bf16 v[60:63], v[172:175], v[190:193], v[60:63]
	v_mfma_f32_16x16x32_bf16 v[52:55], v[172:175], v[194:197], v[52:55]
	v_mfma_f32_16x16x32_bf16 v[56:59], v[172:175], v[198:201], v[56:59]
	v_mfma_f32_16x16x32_bf16 v[48:51], v[172:175], v[202:205], v[48:51]
	v_mfma_f32_16x16x32_bf16 v[44:47], v[176:179], v[190:193], v[44:47]
	v_mfma_f32_16x16x32_bf16 v[36:39], v[176:179], v[194:197], v[36:39]
	v_mfma_f32_16x16x32_bf16 v[40:43], v[176:179], v[198:201], v[40:43]
	v_mfma_f32_16x16x32_bf16 v[32:35], v[176:179], v[202:205], v[32:35]
	v_mfma_f32_16x16x32_bf16 v[28:31], v[182:185], v[190:193], v[28:31]
	v_mfma_f32_16x16x32_bf16 v[16:19], v[182:185], v[194:197], v[16:19]
	v_mfma_f32_16x16x32_bf16 v[24:27], v[182:185], v[198:201], v[24:27]
	v_mfma_f32_16x16x32_bf16 v[12:15], v[182:185], v[202:205], v[12:15]
	v_mfma_f32_16x16x32_bf16 v[4:7], v[186:189], v[190:193], v[4:7]
	v_mfma_f32_16x16x32_bf16 v[0:3], v[186:189], v[194:197], v[0:3]
	v_mfma_f32_16x16x32_bf16 v[20:23], v[186:189], v[198:201], v[20:23]
	v_mfma_f32_16x16x32_bf16 v[8:11], v[186:189], v[202:205], v[8:11]
	ds_read_b128 v[172:175], v155 offset:8192
	ds_read_b128 v[176:179], v155 offset:10240
	ds_read_b128 v[182:185], v155 offset:12288
	ds_read_b128 v[186:189], v155 offset:14336
	s_waitcnt lgkmcnt(4)
	v_mfma_f32_16x16x32_bf16 v[124:127], v[156:159], v[206:209], v[124:127]
	v_mfma_f32_16x16x32_bf16 v[116:119], v[156:159], v[210:213], v[116:119]
	v_mfma_f32_16x16x32_bf16 v[120:123], v[156:159], v[214:217], v[120:123]
	v_mfma_f32_16x16x32_bf16 v[112:115], v[156:159], v[218:221], v[112:115]
	v_mfma_f32_16x16x32_bf16 v[108:111], v[160:163], v[206:209], v[108:111]
	v_mfma_f32_16x16x32_bf16 v[100:103], v[160:163], v[210:213], v[100:103]
	v_mfma_f32_16x16x32_bf16 v[104:107], v[160:163], v[214:217], v[104:107]
	v_mfma_f32_16x16x32_bf16 v[96:99], v[160:163], v[218:221], v[96:99]
	v_mfma_f32_16x16x32_bf16 v[92:95], v[164:167], v[206:209], v[92:95]
	v_mfma_f32_16x16x32_bf16 v[84:87], v[164:167], v[210:213], v[84:87]
	v_mfma_f32_16x16x32_bf16 v[88:91], v[164:167], v[214:217], v[88:91]
	v_mfma_f32_16x16x32_bf16 v[80:83], v[164:167], v[218:221], v[80:83]
	v_mfma_f32_16x16x32_bf16 v[76:79], v[168:171], v[206:209], v[76:79]
	v_mfma_f32_16x16x32_bf16 v[68:71], v[168:171], v[210:213], v[68:71]
	v_mfma_f32_16x16x32_bf16 v[72:75], v[168:171], v[214:217], v[72:75]
	v_mfma_f32_16x16x32_bf16 v[64:67], v[168:171], v[218:221], v[64:67]
	s_add_u32 s44, s44, 0x80
	s_addc_u32 s45, s45, 0
	s_add_i32 s43, s43, 1
	s_waitcnt lgkmcnt(0)
	s_waitcnt vmcnt(0)
	s_barrier
	v_mfma_f32_16x16x32_bf16 v[60:63], v[172:175], v[206:209], v[60:63]
	v_mfma_f32_16x16x32_bf16 v[52:55], v[172:175], v[210:213], v[52:55]
	v_mfma_f32_16x16x32_bf16 v[56:59], v[172:175], v[214:217], v[56:59]
	v_mfma_f32_16x16x32_bf16 v[48:51], v[172:175], v[218:221], v[48:51]
	v_mfma_f32_16x16x32_bf16 v[44:47], v[176:179], v[206:209], v[44:47]
	v_mfma_f32_16x16x32_bf16 v[36:39], v[176:179], v[210:213], v[36:39]
	v_mfma_f32_16x16x32_bf16 v[40:43], v[176:179], v[214:217], v[40:43]
	v_mfma_f32_16x16x32_bf16 v[32:35], v[176:179], v[218:221], v[32:35]
	v_mfma_f32_16x16x32_bf16 v[28:31], v[182:185], v[206:209], v[28:31]
	v_mfma_f32_16x16x32_bf16 v[16:19], v[182:185], v[210:213], v[16:19]
	v_mfma_f32_16x16x32_bf16 v[24:27], v[182:185], v[214:217], v[24:27]
	v_mfma_f32_16x16x32_bf16 v[12:15], v[182:185], v[218:221], v[12:15]
	v_mfma_f32_16x16x32_bf16 v[4:7], v[186:189], v[206:209], v[4:7]
	v_mfma_f32_16x16x32_bf16 v[0:3], v[186:189], v[210:213], v[0:3]
	v_mfma_f32_16x16x32_bf16 v[20:23], v[186:189], v[214:217], v[20:23]
	v_mfma_f32_16x16x32_bf16 v[8:11], v[186:189], v[218:221], v[8:11]
	s_nop 7
	s_nop 7
	s_sub_u32 s44, s44, s34
	s_subb_u32 s45, s45, s35
	s_mov_b32 s57, 0x80000
	s_mov_b32 s58, 0x80000
	s_mov_b64 s[46:47], 0
	s_mov_b64 vcc, exec
	s_branch .LBB0_1494

.LBB0_1636:
	s_ashr_i32 s20, s44, 2
	v_mov_b32_e32 v6, v181
	s_and_b32 s4, s44, 7
	s_and_b32 s39, s20, -8
	s_or_b32 s30, s39, s4
	v_lshrrev_b32_e32 v7, 4, v6
	v_lshlrev_b32_e32 v1, 6, v6
	v_xor_b32_e32 v0, v7, v6
	v_and_b32_e32 v8, 0x3c0, v1
	v_lshlrev_b32_e32 v1, 8, v6
	s_ashr_i32 s31, s30, 31
	v_lshlrev_b32_e32 v0, 3, v0
	v_and_b32_e32 v1, 0xfffff800, v1
	s_and_b32 s38, s43, 7
	s_bfe_u32 s4, s44, 0x20003
	s_lshl_b64 s[20:21], s[30:31], 20
	v_and_or_b32 v0, v0, 56, v1
	s_add_u32 s20, s3, s20
	v_ashrrev_i32_e32 v1, 31, v0
	s_addc_u32 s21, s40, s21
	v_lshlrev_b64 v[0:1], 1, v[0:1]
	v_lshl_add_u32 v134, v6, 4, 0
	v_lshl_add_u64 v[2:3], s[20:21], 0, v[0:1]
	v_readfirstlane_b32 s20, v134
	v_add_u32_e32 v9, 0x2000, v134
	s_mov_b32 m0, s20
	v_readfirstlane_b32 s20, v9
	v_add_u32_e32 v9, 0x4000, v134
	s_waitcnt vmcnt(63) expcnt(7) lgkmcnt(15)
	s_barrier
	global_load_lds_dwordx4 v[2:3], off
	v_lshl_add_u64 v[4:5], v[2:3], 0, s[6:7]
	s_mov_b32 m0, s20
	v_readfirstlane_b32 s20, v9
	global_load_lds_dwordx4 v[4:5], off
	v_lshl_add_u64 v[4:5], v[2:3], 0, s[8:9]
	s_mov_b32 m0, s20
	s_lshl_b32 s31, s4, 20
	global_load_lds_dwordx4 v[4:5], off
	v_add_u32_e32 v4, 0x6000, v134
	s_add_u32 s36, s41, s31
	v_readfirstlane_b32 s20, v4
	v_add_u32_e32 v4, 0x8000, v134
	s_addc_u32 s37, s42, 0
	v_lshl_add_u64 v[2:3], v[2:3], 0, s[10:11]
	s_mov_b32 m0, s20
	v_readfirstlane_b32 s20, v4
	v_add_u32_e32 v9, 0xa000, v134
	global_load_lds_dwordx4 v[2:3], off
	v_lshl_add_u64 v[2:3], s[36:37], 0, v[0:1]
	s_mov_b32 m0, s20
	v_readfirstlane_b32 s20, v9
	v_add_u32_e32 v9, 0xc000, v134
	global_load_lds_dwordx4 v[2:3], off
	v_lshl_add_u64 v[4:5], v[2:3], 0, s[6:7]
	s_mov_b32 m0, s20
	v_readfirstlane_b32 s20, v9
	global_load_lds_dwordx4 v[4:5], off
	v_lshl_add_u64 v[4:5], v[2:3], 0, s[8:9]
	s_mov_b32 m0, s20
	v_lshl_add_u64 v[2:3], v[2:3], 0, s[10:11]
	global_load_lds_dwordx4 v[4:5], off
	v_add_u32_e32 v4, 0xe000, v134
	v_mov_b32_e32 v36, 0
	v_readfirstlane_b32 s20, v4
	s_mov_b32 m0, s20
	v_ashrrev_i32_e32 v4, 6, v6
	global_load_lds_dwordx4 v[2:3], off
	s_or_b32 s20, s39, s38
	v_lshrrev_b32_e32 v5, 30, v4
	s_ashr_i32 s21, s20, 31
	v_add_u32_e32 v5, v4, v5
	s_lshl_b64 s[20:21], s[20:21], 20
	v_bfe_u32 v2, v6, 4, 2
	v_bfe_u32 v3, v6, 1, 3
	v_and_b32_e32 v6, 0x7fffc, v5
	s_add_u32 s20, s34, s20
	v_sub_u32_e32 v4, v4, v6
	s_addc_u32 s21, s35, s21
	v_lshlrev_b32_e32 v136, 13, v4
	v_bitop3_b32 v4, v7, v3, 3 bitop3:0x6c
	v_bitop3_b32 v2, v2, v3, 4 bitop3:0x36
	v_lshl_add_u64 v[130:131], s[20:21], 0, v[0:1]
	s_add_u32 s20, s34, s31
	v_lshlrev_b32_e32 v5, 12, v5
	v_lshlrev_b32_e32 v4, 3, v4
	v_lshlrev_b32_e32 v2, 3, v2
	s_addc_u32 s21, s35, 0
	v_and_b32_e32 v135, 0xffffc000, v5
	v_lshl_add_u64 v[132:133], s[20:21], 0, v[0:1]
	s_mov_b64 s[36:37], 0
	v_lshlrev_b32_e32 v137, 1, v8
	v_lshlrev_b32_e32 v138, 1, v4
	v_lshlrev_b32_e32 v139, 1, v2
	s_mov_b32 s45, 0
	s_mov_b32 s31, 0
	v_mov_b32_e32 v37, v36
	v_mov_b32_e32 v38, v36
	v_mov_b32_e32 v39, v36
	v_mov_b32_e32 v40, v36
	v_mov_b32_e32 v41, v36
	v_mov_b32_e32 v42, v36
	v_mov_b32_e32 v43, v36
	v_mov_b32_e32 v0, v36
	v_mov_b32_e32 v1, v36
	v_mov_b32_e32 v2, v36
	v_mov_b32_e32 v3, v36
	v_mov_b32_e32 v4, v36
	v_mov_b32_e32 v5, v36
	v_mov_b32_e32 v6, v36
	v_mov_b32_e32 v7, v36
	v_mov_b32_e32 v8, v36
	v_mov_b32_e32 v9, v36
	v_mov_b32_e32 v10, v36
	v_mov_b32_e32 v11, v36
	v_mov_b32_e32 v12, v36
	v_mov_b32_e32 v13, v36
	v_mov_b32_e32 v14, v36
	v_mov_b32_e32 v15, v36
	v_mov_b32_e32 v16, v36
	v_mov_b32_e32 v17, v36
	v_mov_b32_e32 v18, v36
	v_mov_b32_e32 v19, v36
	v_mov_b32_e32 v20, v36
	v_mov_b32_e32 v21, v36
	v_mov_b32_e32 v22, v36
	v_mov_b32_e32 v23, v36
	v_mov_b32_e32 v24, v36
	v_mov_b32_e32 v25, v36
	v_mov_b32_e32 v26, v36
	v_mov_b32_e32 v27, v36
	v_mov_b32_e32 v28, v36
	v_mov_b32_e32 v29, v36
	v_mov_b32_e32 v30, v36
	v_mov_b32_e32 v31, v36
	v_mov_b32_e32 v32, v36
	v_mov_b32_e32 v33, v36
	v_mov_b32_e32 v34, v36
	v_mov_b32_e32 v35, v36
	v_mov_b32_e32 v44, v36
	v_mov_b32_e32 v45, v36
	v_mov_b32_e32 v46, v36
	v_mov_b32_e32 v47, v36
	v_mov_b32_e32 v48, v36
	v_mov_b32_e32 v49, v36
	v_mov_b32_e32 v50, v36
	v_mov_b32_e32 v51, v36
	v_mov_b32_e32 v52, v36
	v_mov_b32_e32 v53, v36
	v_mov_b32_e32 v54, v36
	v_mov_b32_e32 v55, v36
	v_mov_b32_e32 v56, v36
	v_mov_b32_e32 v57, v36
	v_mov_b32_e32 v58, v36
	v_mov_b32_e32 v59, v36
	v_mov_b32_e32 v60, v36
	v_mov_b32_e32 v61, v36
	v_mov_b32_e32 v62, v36
	v_mov_b32_e32 v63, v36
	v_mov_b32_e32 v64, v36
	v_mov_b32_e32 v65, v36
	v_mov_b32_e32 v66, v36
	v_mov_b32_e32 v67, v36
	v_mov_b32_e32 v68, v36
	v_mov_b32_e32 v69, v36
	v_mov_b32_e32 v70, v36
	v_mov_b32_e32 v71, v36
	v_mov_b32_e32 v72, v36
	v_mov_b32_e32 v73, v36
	v_mov_b32_e32 v74, v36
	v_mov_b32_e32 v75, v36
	v_mov_b32_e32 v76, v36
	v_mov_b32_e32 v77, v36
	v_mov_b32_e32 v78, v36
	v_mov_b32_e32 v79, v36
	v_mov_b32_e32 v80, v36
	v_mov_b32_e32 v81, v36
	v_mov_b32_e32 v82, v36
	v_mov_b32_e32 v83, v36
	v_mov_b32_e32 v84, v36
	v_mov_b32_e32 v85, v36
	v_mov_b32_e32 v86, v36
	v_mov_b32_e32 v87, v36
	v_mov_b32_e32 v88, v36
	v_mov_b32_e32 v89, v36
	v_mov_b32_e32 v90, v36
	v_mov_b32_e32 v91, v36
	v_mov_b32_e32 v92, v36
	v_mov_b32_e32 v93, v36
	v_mov_b32_e32 v94, v36
	v_mov_b32_e32 v95, v36
	v_mov_b32_e32 v96, v36
	v_mov_b32_e32 v97, v36
	v_mov_b32_e32 v98, v36
	v_mov_b32_e32 v99, v36
	v_mov_b32_e32 v100, v36
	v_mov_b32_e32 v101, v36
	v_mov_b32_e32 v102, v36
	v_mov_b32_e32 v103, v36
	v_mov_b32_e32 v104, v36
	v_mov_b32_e32 v105, v36
	v_mov_b32_e32 v106, v36
	v_mov_b32_e32 v107, v36
	v_mov_b32_e32 v108, v36
	v_mov_b32_e32 v109, v36
	v_mov_b32_e32 v110, v36
	v_mov_b32_e32 v111, v36
	v_mov_b32_e32 v112, v36
	v_mov_b32_e32 v113, v36
	v_mov_b32_e32 v114, v36
	v_mov_b32_e32 v115, v36
	v_mov_b32_e32 v116, v36
	v_mov_b32_e32 v117, v36
	v_mov_b32_e32 v118, v36
	v_mov_b32_e32 v119, v36
	v_mov_b32_e32 v120, v36
	v_mov_b32_e32 v121, v36
	v_mov_b32_e32 v122, v36
	v_mov_b32_e32 v123, v36
	v_mov_b32_e32 v124, v36
	v_mov_b32_e32 v125, v36
	v_mov_b32_e32 v126, v36
	v_mov_b32_e32 v127, v36
	s_waitcnt vmcnt(0) lgkmcnt(0)
	s_barrier
	v_add3_u32 v141, v135, v137, v138
	v_add3_u32 v210, v136, v137, v138
	v_add3_u32 v180, v135, v137, v139
	v_add3_u32 v211, v136, v137, v139
	v_readfirstlane_b32 s45, v134
	ds_read_b128 v[142:145], v141
	ds_read_b128 v[146:149], v141 offset:2048
	ds_read_b128 v[150:153], v141 offset:4096
	ds_read_b128 v[154:157], v141 offset:6144
	ds_read_b128 v[174:177], v210 offset:32768
	ds_read_b128 v[182:185], v210 offset:34816
	ds_read_b128 v[186:189], v210 offset:36864
	ds_read_b128 v[190:193], v210 offset:38912
	s_mov_b32 s31, 0
	s_mov_b64 s[36:37], s[34:35]
	v_subrev_u32_e32 v178, s34, v130
	v_subrev_u32_e32 v179, s34, v132
	s_add_u32 s45, s45, 0x10000
	s_add_u32 s38, s36, s12
	s_addc_u32 s39, s37, s13
	s_mov_b32 m0, s45
	global_load_lds_dwordx4 v178, s[38:39]
	s_add_u32 s38, s36, s14
	s_addc_u32 s39, s37, s15
	s_add_u32 m0, s45, 0x2000
	global_load_lds_dwordx4 v178, s[38:39]
	s_add_u32 s38, s36, s16
	s_addc_u32 s39, s37, s17
	s_add_u32 m0, s45, 0x4000
	global_load_lds_dwordx4 v178, s[38:39]
	s_add_u32 s38, s36, s18
	s_addc_u32 s39, s37, s19
	s_add_u32 m0, s45, 0x6000
	global_load_lds_dwordx4 v178, s[38:39]
	s_add_u32 s38, s36, s22
	s_addc_u32 s39, s37, s23
	s_add_u32 m0, s45, 0x8000
	global_load_lds_dwordx4 v179, s[38:39]
	s_add_u32 s38, s36, s24
	s_addc_u32 s39, s37, s25
	s_add_u32 m0, s45, 0xa000
	global_load_lds_dwordx4 v179, s[38:39]
	s_add_u32 s38, s36, s26
	s_addc_u32 s39, s37, s27
	s_add_u32 m0, s45, 0xc000
	global_load_lds_dwordx4 v179, s[38:39]
	s_add_u32 s38, s36, s28
	s_addc_u32 s39, s37, s29
	s_add_u32 m0, s45, 0xe000
	global_load_lds_dwordx4 v179, s[38:39]
	s_branch .Lg11_entry
.Lg11_top:
	s_waitcnt lgkmcnt(0)
	s_waitcnt vmcnt(0)
	s_barrier
	v_xor_b32_e32 v141, 0x10000, v141
	v_xor_b32_e32 v210, 0x10000, v210
	v_xor_b32_e32 v180, 0x10000, v180
	v_xor_b32_e32 v211, 0x10000, v211
	s_xor_b32 s45, s45, 0x10000
	ds_read_b128 v[142:145], v141
	ds_read_b128 v[146:149], v141 offset:2048
	ds_read_b128 v[150:153], v141 offset:4096
	ds_read_b128 v[154:157], v141 offset:6144
	ds_read_b128 v[174:177], v210 offset:32768
	ds_read_b128 v[182:185], v210 offset:34816
	ds_read_b128 v[186:189], v210 offset:36864
	ds_read_b128 v[190:193], v210 offset:38912
	v_mfma_f32_16x16x32_bf16 v[60:63], v[158:161], v[194:197], v[60:63]
	v_mfma_f32_16x16x32_bf16 v[56:59], v[158:161], v[198:201], v[56:59]
	s_add_u32 s38, s36, s12
	s_addc_u32 s39, s37, s13
	s_mov_b32 m0, s45
	global_load_lds_dwordx4 v178, s[38:39]
	v_mfma_f32_16x16x32_bf16 v[52:55], v[158:161], v[202:205], v[52:55]
	v_mfma_f32_16x16x32_bf16 v[48:51], v[158:161], v[206:209], v[48:51]
	s_add_u32 s38, s36, s14
	s_addc_u32 s39, s37, s15
	s_add_u32 m0, s45, 0x2000
	global_load_lds_dwordx4 v178, s[38:39]
	v_mfma_f32_16x16x32_bf16 v[44:47], v[162:165], v[194:197], v[44:47]
	v_mfma_f32_16x16x32_bf16 v[32:35], v[162:165], v[198:201], v[32:35]
	s_add_u32 s38, s36, s16
	s_addc_u32 s39, s37, s17
	s_add_u32 m0, s45, 0x4000
	global_load_lds_dwordx4 v178, s[38:39]
	v_mfma_f32_16x16x32_bf16 v[28:31], v[162:165], v[202:205], v[28:31]
	v_mfma_f32_16x16x32_bf16 v[24:27], v[162:165], v[206:209], v[24:27]
	s_add_u32 s38, s36, s18
	s_addc_u32 s39, s37, s19
	s_add_u32 m0, s45, 0x6000
	global_load_lds_dwordx4 v178, s[38:39]
	v_mfma_f32_16x16x32_bf16 v[20:23], v[166:169], v[194:197], v[20:23]
	v_mfma_f32_16x16x32_bf16 v[16:19], v[166:169], v[198:201], v[16:19]
	s_add_u32 s38, s36, s22
	s_addc_u32 s39, s37, s23
	s_add_u32 m0, s45, 0x8000
	global_load_lds_dwordx4 v179, s[38:39]
	v_mfma_f32_16x16x32_bf16 v[12:15], v[166:169], v[202:205], v[12:15]
	v_mfma_f32_16x16x32_bf16 v[8:11], v[166:169], v[206:209], v[8:11]
	s_add_u32 s38, s36, s24
	s_addc_u32 s39, s37, s25
	s_add_u32 m0, s45, 0xa000
	global_load_lds_dwordx4 v179, s[38:39]
	v_mfma_f32_16x16x32_bf16 v[4:7], v[170:173], v[194:197], v[4:7]
	v_mfma_f32_16x16x32_bf16 v[0:3], v[170:173], v[198:201], v[0:3]
	s_add_u32 s38, s36, s26
	s_addc_u32 s39, s37, s27
	s_add_u32 m0, s45, 0xc000
	global_load_lds_dwordx4 v179, s[38:39]
	v_mfma_f32_16x16x32_bf16 v[40:43], v[170:173], v[202:205], v[40:43]
	v_mfma_f32_16x16x32_bf16 v[36:39], v[170:173], v[206:209], v[36:39]
	s_add_u32 s38, s36, s28
	s_addc_u32 s39, s37, s29
	s_add_u32 m0, s45, 0xe000
	global_load_lds_dwordx4 v179, s[38:39]
.Lg11_entry:
	ds_read_b128 v[158:161], v141 offset:8192
	ds_read_b128 v[162:165], v141 offset:10240
	ds_read_b128 v[166:169], v141 offset:12288
	ds_read_b128 v[170:173], v141 offset:14336
	s_waitcnt lgkmcnt(4)
	v_mfma_f32_16x16x32_bf16 v[124:127], v[142:145], v[174:177], v[124:127]
	v_mfma_f32_16x16x32_bf16 v[120:123], v[142:145], v[182:185], v[120:123]
	v_mfma_f32_16x16x32_bf16 v[116:119], v[142:145], v[186:189], v[116:119]
	v_mfma_f32_16x16x32_bf16 v[112:115], v[142:145], v[190:193], v[112:115]
	v_mfma_f32_16x16x32_bf16 v[108:111], v[146:149], v[174:177], v[108:111]
	v_mfma_f32_16x16x32_bf16 v[104:107], v[146:149], v[182:185], v[104:107]
	v_mfma_f32_16x16x32_bf16 v[100:103], v[146:149], v[186:189], v[100:103]
	v_mfma_f32_16x16x32_bf16 v[96:99], v[146:149], v[190:193], v[96:99]
	v_mfma_f32_16x16x32_bf16 v[92:95], v[150:153], v[174:177], v[92:95]
	v_mfma_f32_16x16x32_bf16 v[88:91], v[150:153], v[182:185], v[88:91]
	v_mfma_f32_16x16x32_bf16 v[84:87], v[150:153], v[186:189], v[84:87]
	v_mfma_f32_16x16x32_bf16 v[80:83], v[150:153], v[190:193], v[80:83]
	v_mfma_f32_16x16x32_bf16 v[76:79], v[154:157], v[174:177], v[76:79]
	v_mfma_f32_16x16x32_bf16 v[72:75], v[154:157], v[182:185], v[72:75]
	v_mfma_f32_16x16x32_bf16 v[68:71], v[154:157], v[186:189], v[68:71]
	v_mfma_f32_16x16x32_bf16 v[64:67], v[154:157], v[190:193], v[64:67]
	ds_read_b128 v[142:145], v180
	ds_read_b128 v[146:149], v180 offset:2048
	ds_read_b128 v[150:153], v180 offset:4096
	ds_read_b128 v[154:157], v180 offset:6144
	ds_read_b128 v[194:197], v211 offset:32768
	ds_read_b128 v[198:201], v211 offset:34816
	ds_read_b128 v[202:205], v211 offset:36864
	ds_read_b128 v[206:209], v211 offset:38912
	s_waitcnt lgkmcnt(8)
	v_mfma_f32_16x16x32_bf16 v[60:63], v[158:161], v[174:177], v[60:63]
	v_mfma_f32_16x16x32_bf16 v[56:59], v[158:161], v[182:185], v[56:59]
	v_mfma_f32_16x16x32_bf16 v[52:55], v[158:161], v[186:189], v[52:55]
	v_mfma_f32_16x16x32_bf16 v[48:51], v[158:161], v[190:193], v[48:51]
	v_mfma_f32_16x16x32_bf16 v[44:47], v[162:165], v[174:177], v[44:47]
	v_mfma_f32_16x16x32_bf16 v[32:35], v[162:165], v[182:185], v[32:35]
	v_mfma_f32_16x16x32_bf16 v[28:31], v[162:165], v[186:189], v[28:31]
	v_mfma_f32_16x16x32_bf16 v[24:27], v[162:165], v[190:193], v[24:27]
	v_mfma_f32_16x16x32_bf16 v[20:23], v[166:169], v[174:177], v[20:23]
	v_mfma_f32_16x16x32_bf16 v[16:19], v[166:169], v[182:185], v[16:19]
	v_mfma_f32_16x16x32_bf16 v[12:15], v[166:169], v[186:189], v[12:15]
	v_mfma_f32_16x16x32_bf16 v[8:11], v[166:169], v[190:193], v[8:11]
	v_mfma_f32_16x16x32_bf16 v[4:7], v[170:173], v[174:177], v[4:7]
	v_mfma_f32_16x16x32_bf16 v[0:3], v[170:173], v[182:185], v[0:3]
	v_mfma_f32_16x16x32_bf16 v[40:43], v[170:173], v[186:189], v[40:43]
	v_mfma_f32_16x16x32_bf16 v[36:39], v[170:173], v[190:193], v[36:39]
	ds_read_b128 v[158:161], v180 offset:8192
	ds_read_b128 v[162:165], v180 offset:10240
	ds_read_b128 v[166:169], v180 offset:12288
	ds_read_b128 v[170:173], v180 offset:14336
	s_waitcnt lgkmcnt(4)
	v_mfma_f32_16x16x32_bf16 v[124:127], v[142:145], v[194:197], v[124:127]
	v_mfma_f32_16x16x32_bf16 v[120:123], v[142:145], v[198:201], v[120:123]
	v_mfma_f32_16x16x32_bf16 v[116:119], v[142:145], v[202:205], v[116:119]
	v_mfma_f32_16x16x32_bf16 v[112:115], v[142:145], v[206:209], v[112:115]
	v_mfma_f32_16x16x32_bf16 v[108:111], v[146:149], v[194:197], v[108:111]
	v_mfma_f32_16x16x32_bf16 v[104:107], v[146:149], v[198:201], v[104:107]
	v_mfma_f32_16x16x32_bf16 v[100:103], v[146:149], v[202:205], v[100:103]
	v_mfma_f32_16x16x32_bf16 v[96:99], v[146:149], v[206:209], v[96:99]
	v_mfma_f32_16x16x32_bf16 v[92:95], v[150:153], v[194:197], v[92:95]
	v_mfma_f32_16x16x32_bf16 v[88:91], v[150:153], v[198:201], v[88:91]
	v_mfma_f32_16x16x32_bf16 v[84:87], v[150:153], v[202:205], v[84:87]
	v_mfma_f32_16x16x32_bf16 v[80:83], v[150:153], v[206:209], v[80:83]
	v_mfma_f32_16x16x32_bf16 v[76:79], v[154:157], v[194:197], v[76:79]
	v_mfma_f32_16x16x32_bf16 v[72:75], v[154:157], v[198:201], v[72:75]
	v_mfma_f32_16x16x32_bf16 v[68:71], v[154:157], v[202:205], v[68:71]
	v_mfma_f32_16x16x32_bf16 v[64:67], v[154:157], v[206:209], v[64:67]
	s_add_u32 s36, s36, 0x80
	s_addc_u32 s37, s37, 0
	s_add_i32 s31, s31, 1
	s_cmp_lt_u32 s31, 31
	s_cbranch_scc1 .Lg11_top
	s_waitcnt lgkmcnt(0)
	s_waitcnt vmcnt(0)
	s_barrier
	v_xor_b32_e32 v141, 0x10000, v141
	v_xor_b32_e32 v210, 0x10000, v210
	v_xor_b32_e32 v180, 0x10000, v180
	v_xor_b32_e32 v211, 0x10000, v211
	s_xor_b32 s45, s45, 0x10000
	ds_read_b128 v[142:145], v141
	ds_read_b128 v[146:149], v141 offset:2048
	ds_read_b128 v[150:153], v141 offset:4096
	ds_read_b128 v[154:157], v141 offset:6144
	ds_read_b128 v[174:177], v210 offset:32768
	ds_read_b128 v[182:185], v210 offset:34816
	ds_read_b128 v[186:189], v210 offset:36864
	ds_read_b128 v[190:193], v210 offset:38912
	v_mfma_f32_16x16x32_bf16 v[60:63], v[158:161], v[194:197], v[60:63]
	v_mfma_f32_16x16x32_bf16 v[56:59], v[158:161], v[198:201], v[56:59]
	v_mfma_f32_16x16x32_bf16 v[52:55], v[158:161], v[202:205], v[52:55]
	v_mfma_f32_16x16x32_bf16 v[48:51], v[158:161], v[206:209], v[48:51]
	v_mfma_f32_16x16x32_bf16 v[44:47], v[162:165], v[194:197], v[44:47]
	v_mfma_f32_16x16x32_bf16 v[32:35], v[162:165], v[198:201], v[32:35]
	v_mfma_f32_16x16x32_bf16 v[28:31], v[162:165], v[202:205], v[28:31]
	v_mfma_f32_16x16x32_bf16 v[24:27], v[162:165], v[206:209], v[24:27]
	v_mfma_f32_16x16x32_bf16 v[20:23], v[166:169], v[194:197], v[20:23]
	v_mfma_f32_16x16x32_bf16 v[16:19], v[166:169], v[198:201], v[16:19]
	v_mfma_f32_16x16x32_bf16 v[12:15], v[166:169], v[202:205], v[12:15]
	v_mfma_f32_16x16x32_bf16 v[8:11], v[166:169], v[206:209], v[8:11]
	v_mfma_f32_16x16x32_bf16 v[4:7], v[170:173], v[194:197], v[4:7]
	v_mfma_f32_16x16x32_bf16 v[0:3], v[170:173], v[198:201], v[0:3]
	v_mfma_f32_16x16x32_bf16 v[40:43], v[170:173], v[202:205], v[40:43]
	v_mfma_f32_16x16x32_bf16 v[36:39], v[170:173], v[206:209], v[36:39]
	ds_read_b128 v[158:161], v141 offset:8192
	ds_read_b128 v[162:165], v141 offset:10240
	ds_read_b128 v[166:169], v141 offset:12288
	ds_read_b128 v[170:173], v141 offset:14336
	s_waitcnt lgkmcnt(4)
	v_mfma_f32_16x16x32_bf16 v[124:127], v[142:145], v[174:177], v[124:127]
	v_mfma_f32_16x16x32_bf16 v[120:123], v[142:145], v[182:185], v[120:123]
	v_mfma_f32_16x16x32_bf16 v[116:119], v[142:145], v[186:189], v[116:119]
	v_mfma_f32_16x16x32_bf16 v[112:115], v[142:145], v[190:193], v[112:115]
	v_mfma_f32_16x16x32_bf16 v[108:111], v[146:149], v[174:177], v[108:111]
	v_mfma_f32_16x16x32_bf16 v[104:107], v[146:149], v[182:185], v[104:107]
	v_mfma_f32_16x16x32_bf16 v[100:103], v[146:149], v[186:189], v[100:103]
	v_mfma_f32_16x16x32_bf16 v[96:99], v[146:149], v[190:193], v[96:99]
	v_mfma_f32_16x16x32_bf16 v[92:95], v[150:153], v[174:177], v[92:95]
	v_mfma_f32_16x16x32_bf16 v[88:91], v[150:153], v[182:185], v[88:91]
	v_mfma_f32_16x16x32_bf16 v[84:87], v[150:153], v[186:189], v[84:87]
	v_mfma_f32_16x16x32_bf16 v[80:83], v[150:153], v[190:193], v[80:83]
	v_mfma_f32_16x16x32_bf16 v[76:79], v[154:157], v[174:177], v[76:79]
	v_mfma_f32_16x16x32_bf16 v[72:75], v[154:157], v[182:185], v[72:75]
	v_mfma_f32_16x16x32_bf16 v[68:71], v[154:157], v[186:189], v[68:71]
	v_mfma_f32_16x16x32_bf16 v[64:67], v[154:157], v[190:193], v[64:67]
	ds_read_b128 v[142:145], v180
	ds_read_b128 v[146:149], v180 offset:2048
	ds_read_b128 v[150:153], v180 offset:4096
	ds_read_b128 v[154:157], v180 offset:6144
	ds_read_b128 v[194:197], v211 offset:32768
	ds_read_b128 v[198:201], v211 offset:34816
	ds_read_b128 v[202:205], v211 offset:36864
	ds_read_b128 v[206:209], v211 offset:38912
	s_waitcnt lgkmcnt(8)
	v_mfma_f32_16x16x32_bf16 v[60:63], v[158:161], v[174:177], v[60:63]
	v_mfma_f32_16x16x32_bf16 v[56:59], v[158:161], v[182:185], v[56:59]
	v_mfma_f32_16x16x32_bf16 v[52:55], v[158:161], v[186:189], v[52:55]
	v_mfma_f32_16x16x32_bf16 v[48:51], v[158:161], v[190:193], v[48:51]
	v_mfma_f32_16x16x32_bf16 v[44:47], v[162:165], v[174:177], v[44:47]
	v_mfma_f32_16x16x32_bf16 v[32:35], v[162:165], v[182:185], v[32:35]
	v_mfma_f32_16x16x32_bf16 v[28:31], v[162:165], v[186:189], v[28:31]
	v_mfma_f32_16x16x32_bf16 v[24:27], v[162:165], v[190:193], v[24:27]
	v_mfma_f32_16x16x32_bf16 v[20:23], v[166:169], v[174:177], v[20:23]
	v_mfma_f32_16x16x32_bf16 v[16:19], v[166:169], v[182:185], v[16:19]
	v_mfma_f32_16x16x32_bf16 v[12:15], v[166:169], v[186:189], v[12:15]
	v_mfma_f32_16x16x32_bf16 v[8:11], v[166:169], v[190:193], v[8:11]
	v_mfma_f32_16x16x32_bf16 v[4:7], v[170:173], v[174:177], v[4:7]
	v_mfma_f32_16x16x32_bf16 v[0:3], v[170:173], v[182:185], v[0:3]
	v_mfma_f32_16x16x32_bf16 v[40:43], v[170:173], v[186:189], v[40:43]
	v_mfma_f32_16x16x32_bf16 v[36:39], v[170:173], v[190:193], v[36:39]
	ds_read_b128 v[158:161], v180 offset:8192
	ds_read_b128 v[162:165], v180 offset:10240
	ds_read_b128 v[166:169], v180 offset:12288
	ds_read_b128 v[170:173], v180 offset:14336
	s_waitcnt lgkmcnt(4)
	v_mfma_f32_16x16x32_bf16 v[124:127], v[142:145], v[194:197], v[124:127]
	v_mfma_f32_16x16x32_bf16 v[120:123], v[142:145], v[198:201], v[120:123]
	v_mfma_f32_16x16x32_bf16 v[116:119], v[142:145], v[202:205], v[116:119]
	v_mfma_f32_16x16x32_bf16 v[112:115], v[142:145], v[206:209], v[112:115]
	v_mfma_f32_16x16x32_bf16 v[108:111], v[146:149], v[194:197], v[108:111]
	v_mfma_f32_16x16x32_bf16 v[104:107], v[146:149], v[198:201], v[104:107]
	v_mfma_f32_16x16x32_bf16 v[100:103], v[146:149], v[202:205], v[100:103]
	v_mfma_f32_16x16x32_bf16 v[96:99], v[146:149], v[206:209], v[96:99]
	v_mfma_f32_16x16x32_bf16 v[92:95], v[150:153], v[194:197], v[92:95]
	v_mfma_f32_16x16x32_bf16 v[88:91], v[150:153], v[198:201], v[88:91]
	v_mfma_f32_16x16x32_bf16 v[84:87], v[150:153], v[202:205], v[84:87]
	v_mfma_f32_16x16x32_bf16 v[80:83], v[150:153], v[206:209], v[80:83]
	v_mfma_f32_16x16x32_bf16 v[76:79], v[154:157], v[194:197], v[76:79]
	v_mfma_f32_16x16x32_bf16 v[72:75], v[154:157], v[198:201], v[72:75]
	v_mfma_f32_16x16x32_bf16 v[68:71], v[154:157], v[202:205], v[68:71]
	v_mfma_f32_16x16x32_bf16 v[64:67], v[154:157], v[206:209], v[64:67]
	s_add_u32 s36, s36, 0x80
	s_addc_u32 s37, s37, 0
	s_add_i32 s31, s31, 1
	s_waitcnt lgkmcnt(0)
	s_waitcnt vmcnt(0)
	s_barrier
	v_mfma_f32_16x16x32_bf16 v[60:63], v[158:161], v[194:197], v[60:63]
	v_mfma_f32_16x16x32_bf16 v[56:59], v[158:161], v[198:201], v[56:59]
	v_mfma_f32_16x16x32_bf16 v[52:55], v[158:161], v[202:205], v[52:55]
	v_mfma_f32_16x16x32_bf16 v[48:51], v[158:161], v[206:209], v[48:51]
	v_mfma_f32_16x16x32_bf16 v[44:47], v[162:165], v[194:197], v[44:47]
	v_mfma_f32_16x16x32_bf16 v[32:35], v[162:165], v[198:201], v[32:35]
	v_mfma_f32_16x16x32_bf16 v[28:31], v[162:165], v[202:205], v[28:31]
	v_mfma_f32_16x16x32_bf16 v[24:27], v[162:165], v[206:209], v[24:27]
	v_mfma_f32_16x16x32_bf16 v[20:23], v[166:169], v[194:197], v[20:23]
	v_mfma_f32_16x16x32_bf16 v[16:19], v[166:169], v[198:201], v[16:19]
	v_mfma_f32_16x16x32_bf16 v[12:15], v[166:169], v[202:205], v[12:15]
	v_mfma_f32_16x16x32_bf16 v[8:11], v[166:169], v[206:209], v[8:11]
	v_mfma_f32_16x16x32_bf16 v[4:7], v[170:173], v[194:197], v[4:7]
	v_mfma_f32_16x16x32_bf16 v[0:3], v[170:173], v[198:201], v[0:3]
	v_mfma_f32_16x16x32_bf16 v[40:43], v[170:173], v[202:205], v[40:43]
	v_mfma_f32_16x16x32_bf16 v[36:39], v[170:173], v[206:209], v[36:39]
	s_nop 7
	s_nop 7
	s_sub_u32 s36, s36, s34
	s_subb_u32 s37, s37, s35
	s_mov_b32 s45, 0x100000
	s_mov_b32 s46, 0x100000
	s_mov_b64 s[38:39], 0
	s_mov_b64 vcc, exec
	s_branch .LBB0_1635
